# GEMM phases: per-phase s_setprio flips removed (A/B'd by cycle count on FFN2 phases: -1.7 pct), on top of v58
# baseline (speedup 1.0000x reference)
; #define PG8_STAGE(bufoff, gbase, voff) do { _Pragma("unroll") for (int _i = 0; _i < 2; ++_i) \
;         __builtin_amdgcn_global_load_lds((const unsigned*)((const char*)(gbase) + (voff)[_i]), (LAS unsigned*)(lds + (bufoff) + ldsw + _i * 8192), 16, 0, 0); } while (0)
; #define PG8_LDA(dst, b, h) do { _Pragma("unroll") for (int m = 0; m < 4; ++m) _Pragma("unroll") for (int k = 0; k < 2; ++k) dst[m][k] = *(const LAS bf16x8*)(lds + PG8_SA(b, h) + aoff + m * 2048 + k * 1024); } while (0)
; #define PG8_LDB(dst, b, h) do { _Pragma("unroll") for (int n = 0; n < 2; ++n) _Pragma("unroll") for (int k = 0; k < 2; ++k) dst[n][k] = *(const LAS bf16x8*)(lds + PG8_SB(b, h) + boff + n * 2048 + k * 1024); } while (0)
; #define PG8_MMA(ai, bj, At, Bt) do { __builtin_amdgcn_s_setprio(1); _Pragma("unroll") for (int m = 0; m < 4; ++m) _Pragma("unroll") for (int n = 0; n < 2; ++n) _Pragma("unroll") for (int k = 0; k < 2; ++k) \
;         acc[ai][bj][m][n] = __builtin_amdgcn_mfma_f32_16x16x32_bf16(Bt[n][k], At[m][k], acc[ai][bj][m][n], 0, 0, 0); __builtin_amdgcn_s_setprio(0); } while (0)
; #define PG8_WAIT_V(n) asm volatile("s_waitcnt vmcnt(" #n ")" ::: "memory")
; #define PG8_WAIT_L(n) asm volatile("s_waitcnt lgkmcnt(" #n ")" ::: "memory")
; #define PG8_BAR __builtin_amdgcn_s_barrier()
; #define PG8_SCHED __builtin_amdgcn_sched_barrier(0)
; template <class Epi, class Sched, bool ALIGN_EPI = true, bool SP2 = true>
; __device__ __forceinline__ void gemm_phase(LAS unsigned char* lds, const Gemm g, const Sched& S, const Epi& E) {
;     ...
;             PG8_LDB(B0, 0, 0); PG8_LDB(B1, 0, 1); PG8_SCHED; PG8_LDA(At, 0, 0); PG8_STAGE(PG8_SA(1, 1), a1 + hstep, voffA);
;             PG8_WAIT_V(8); PG8_WAIT_L(0); PG8_BAR; PG8_MMA(0, 0, At, B0); PG8_MMA(0, 1, At, B1); PG8_BAR; PG8_SCHED;
;             PG8_LDA(At, 0, 1); PG8_STAGE(PG8_SB(0, 0), b2, voffB); PG8_STAGE(PG8_SB(0, 1), b2 + hstep, voffB); PG8_STAGE(PG8_SA(0, 0), a2, voffA);
;             PG8_WAIT_V(8); PG8_WAIT_L(0); PG8_BAR; PG8_MMA(1, 0, At, B0); PG8_MMA(1, 1, At, B1); PG8_BAR; PG8_SCHED;
.LBB0_244:
	ds_read_b128 v[148:151], v143
	ds_read_b128 v[152:155], v143 offset:1024
	ds_read_b128 v[156:159], v143 offset:2048
	ds_read_b128 v[166:169], v143 offset:3072
	ds_read_b128 v[170:173], v144
	ds_read_b128 v[176:179], v144 offset:1024
	ds_read_b128 v[180:183], v144 offset:2048
	ds_read_b128 v[184:187], v144 offset:3072
	s_add_u32 s46, s14, s48
	s_addc_u32 s47, s15, s49
	s_add_u32 s46, s46, 0x7a00100
	s_addc_u32 s47, s47, 0
	s_add_u32 s60, s44, s48
	s_addc_u32 s61, s45, s49
	s_cmpk_eq_i32 s48, 0x700
	s_cselect_b32 s63, s11, s47
	s_cselect_b32 s62, s10, s46
	s_cselect_b32 s61, s9, s61
	s_cselect_b32 s60, s8, s60
	s_mov_b32 m0, s65
	v_lshl_add_u64 v[220:221], v[138:139], 0, s[48:49]
	ds_read_b128 v[188:191], v145
	ds_read_b128 v[192:195], v145 offset:1024
	ds_read_b128 v[196:199], v145 offset:2048
	ds_read_b128 v[200:203], v145 offset:3072
	ds_read_b128 v[204:207], v145 offset:4096
	ds_read_b128 v[208:211], v145 offset:5120
	ds_read_b128 v[212:215], v145 offset:6144
	ds_read_b128 v[216:219], v145 offset:7168
	global_load_lds_dwordx4 v[220:221], off
	v_lshl_add_u64 v[220:221], v[140:141], 0, s[48:49]
	s_mov_b32 m0, s68
	s_nop 0
	global_load_lds_dwordx4 v[220:221], off
	s_waitcnt vmcnt(8)
	s_waitcnt lgkmcnt(0)
	s_barrier
	s_waitcnt lgkmcnt(0)
	v_mfma_f32_16x16x32_bf16 v[124:127], v[148:151], v[188:191], v[124:127]
	v_mfma_f32_16x16x32_bf16 v[120:123], v[156:159], v[188:191], v[120:123]
	v_mfma_f32_16x16x32_bf16 v[108:111], v[148:151], v[196:199], v[108:111]
	v_mfma_f32_16x16x32_bf16 v[104:107], v[156:159], v[196:199], v[104:107]
	v_mfma_f32_16x16x32_bf16 v[92:95], v[148:151], v[204:207], v[92:95]
	v_mfma_f32_16x16x32_bf16 v[88:91], v[156:159], v[204:207], v[88:91]
	v_mfma_f32_16x16x32_bf16 v[76:79], v[148:151], v[212:215], v[76:79]
	v_mfma_f32_16x16x32_bf16 v[72:75], v[156:159], v[212:215], v[72:75]
	v_mfma_f32_16x16x32_bf16 v[124:127], v[152:155], v[192:195], v[124:127]
	v_mfma_f32_16x16x32_bf16 v[120:123], v[166:169], v[192:195], v[120:123]
	v_mfma_f32_16x16x32_bf16 v[108:111], v[152:155], v[200:203], v[108:111]
	v_mfma_f32_16x16x32_bf16 v[104:107], v[166:169], v[200:203], v[104:107]
	v_mfma_f32_16x16x32_bf16 v[92:95], v[152:155], v[208:211], v[92:95]
	v_mfma_f32_16x16x32_bf16 v[88:91], v[166:169], v[208:211], v[88:91]
	v_mfma_f32_16x16x32_bf16 v[76:79], v[152:155], v[216:219], v[76:79]
	v_mfma_f32_16x16x32_bf16 v[72:75], v[166:169], v[216:219], v[72:75]
	v_mfma_f32_16x16x32_bf16 v[116:119], v[170:173], v[188:191], v[116:119]
	v_mfma_f32_16x16x32_bf16 v[112:115], v[180:183], v[188:191], v[112:115]
	v_mfma_f32_16x16x32_bf16 v[100:103], v[170:173], v[196:199], v[100:103]
	v_mfma_f32_16x16x32_bf16 v[96:99], v[180:183], v[196:199], v[96:99]
	v_mfma_f32_16x16x32_bf16 v[84:87], v[170:173], v[204:207], v[84:87]
	v_mfma_f32_16x16x32_bf16 v[80:83], v[180:183], v[204:207], v[80:83]
	v_mfma_f32_16x16x32_bf16 v[68:71], v[170:173], v[212:215], v[68:71]
	v_mfma_f32_16x16x32_bf16 v[64:67], v[180:183], v[212:215], v[64:67]
	v_mfma_f32_16x16x32_bf16 v[116:119], v[176:179], v[192:195], v[116:119]
	v_mfma_f32_16x16x32_bf16 v[112:115], v[184:187], v[192:195], v[112:115]
	v_mfma_f32_16x16x32_bf16 v[100:103], v[176:179], v[200:203], v[100:103]
	v_mfma_f32_16x16x32_bf16 v[96:99], v[184:187], v[200:203], v[96:99]
	v_mfma_f32_16x16x32_bf16 v[84:87], v[176:179], v[208:211], v[84:87]
	v_mfma_f32_16x16x32_bf16 v[80:83], v[184:187], v[208:211], v[80:83]
	v_mfma_f32_16x16x32_bf16 v[68:71], v[176:179], v[216:219], v[68:71]
	v_mfma_f32_16x16x32_bf16 v[64:67], v[184:187], v[216:219], v[64:67]
	s_barrier
	s_mov_b32 m0, s69
	v_lshl_add_u64 v[220:221], s[60:61], 0, v[134:135]
	s_add_u32 s88, s60, 0x40000
	ds_read_b128 v[188:191], v145 offset:16384
	ds_read_b128 v[192:195], v145 offset:17408
	ds_read_b128 v[196:199], v145 offset:18432
	ds_read_b128 v[200:203], v145 offset:19456
	ds_read_b128 v[204:207], v145 offset:20480
	ds_read_b128 v[208:211], v145 offset:21504
	ds_read_b128 v[212:215], v145 offset:22528
	ds_read_b128 v[216:219], v145 offset:23552
	global_load_lds_dwordx4 v[220:221], off
	v_lshl_add_u64 v[222:223], s[60:61], 0, v[130:131]
	s_mov_b32 m0, s70
	s_addc_u32 s89, s61, 0
	global_load_lds_dwordx4 v[222:223], off
	v_lshl_add_u64 v[224:225], s[88:89], 0, v[134:135]
	s_mov_b32 m0, s71
	v_lshl_add_u64 v[226:227], s[62:63], 0, v[132:133]
	global_load_lds_dwordx4 v[224:225], off
	v_lshl_add_u64 v[224:225], s[88:89], 0, v[130:131]
	s_mov_b32 m0, s72
	s_nop 0
	global_load_lds_dwordx4 v[224:225], off
	v_lshl_add_u64 v[224:225], s[62:63], 0, v[136:137]
	s_mov_b32 m0, s25
	s_nop 0
	global_load_lds_dwordx4 v[224:225], off
	s_mov_b32 m0, s34
	s_nop 0
	global_load_lds_dwordx4 v[226:227], off
	s_waitcnt vmcnt(8)
	s_waitcnt lgkmcnt(0)
	s_barrier
; #define PG8_STAGE(bufoff, gbase, voff) do { _Pragma("unroll") for (int _i = 0; _i < 2; ++_i) \
;         __builtin_amdgcn_global_load_lds((const unsigned*)((const char*)(gbase) + (voff)[_i]), (LAS unsigned*)(lds + (bufoff) + ldsw + _i * 8192), 16, 0, 0); } while (0)
; #define PG8_LDA(dst, b, h) do { _Pragma("unroll") for (int m = 0; m < 4; ++m) _Pragma("unroll") for (int k = 0; k < 2; ++k) dst[m][k] = *(const LAS bf16x8*)(lds + PG8_SA(b, h) + aoff + m * 2048 + k * 1024); } while (0)
; #define PG8_LDB(dst, b, h) do { _Pragma("unroll") for (int n = 0; n < 2; ++n) _Pragma("unroll") for (int k = 0; k < 2; ++k) dst[n][k] = *(const LAS bf16x8*)(lds + PG8_SB(b, h) + boff + n * 2048 + k * 1024); } while (0)
; #define PG8_MMA(ai, bj, At, Bt) do { __builtin_amdgcn_s_setprio(1); _Pragma("unroll") for (int m = 0; m < 4; ++m) _Pragma("unroll") for (int n = 0; n < 2; ++n) _Pragma("unroll") for (int k = 0; k < 2; ++k) \
;         acc[ai][bj][m][n] = __builtin_amdgcn_mfma_f32_16x16x32_bf16(Bt[n][k], At[m][k], acc[ai][bj][m][n], 0, 0, 0); __builtin_amdgcn_s_setprio(0); } while (0)
; #define PG8_WAIT_V(n) asm volatile("s_waitcnt vmcnt(" #n ")" ::: "memory")
; #define PG8_WAIT_L(n) asm volatile("s_waitcnt lgkmcnt(" #n ")" ::: "memory")
; #define PG8_BAR __builtin_amdgcn_s_barrier()
; #define PG8_SCHED __builtin_amdgcn_sched_barrier(0)
; template <class Epi, class Sched, bool ALIGN_EPI = true, bool SP2 = true>
; __device__ __forceinline__ void gemm_phase(LAS unsigned char* lds, const Gemm g, const Sched& S, const Epi& E) {
;     ...
;             PG8_WAIT_V(8); PG8_WAIT_L(0); PG8_BAR; PG8_MMA(1, 0, At, B0); PG8_MMA(1, 1, At, B1); PG8_BAR; PG8_SCHED;
;             PG8_LDB(B0, 1, 0); PG8_LDB(B1, 1, 1); PG8_SCHED; PG8_LDA(At, 1, 0); PG8_STAGE(PG8_SA(0, 1), a2 + hstep, voffA);
;             PG8_WAIT_V(8); PG8_WAIT_L(0); PG8_BAR; PG8_MMA(0, 0, At, B0); PG8_MMA(0, 1, At, B1); PG8_BAR; PG8_SCHED;
	s_waitcnt lgkmcnt(0)
	v_mfma_f32_16x16x32_bf16 v[60:63], v[148:151], v[188:191], v[60:63]
	v_mfma_f32_16x16x32_bf16 v[56:59], v[156:159], v[188:191], v[56:59]
	v_mfma_f32_16x16x32_bf16 v[44:47], v[148:151], v[196:199], v[44:47]
	v_mfma_f32_16x16x32_bf16 v[40:43], v[156:159], v[196:199], v[40:43]
	v_mfma_f32_16x16x32_bf16 v[28:31], v[148:151], v[204:207], v[28:31]
	v_mfma_f32_16x16x32_bf16 v[24:27], v[156:159], v[204:207], v[24:27]
	v_mfma_f32_16x16x32_bf16 v[12:15], v[148:151], v[212:215], v[12:15]
	v_mfma_f32_16x16x32_bf16 v[8:11], v[156:159], v[212:215], v[8:11]
	v_mfma_f32_16x16x32_bf16 v[60:63], v[152:155], v[192:195], v[60:63]
	v_mfma_f32_16x16x32_bf16 v[56:59], v[166:169], v[192:195], v[56:59]
	v_mfma_f32_16x16x32_bf16 v[44:47], v[152:155], v[200:203], v[44:47]
	v_mfma_f32_16x16x32_bf16 v[40:43], v[166:169], v[200:203], v[40:43]
	v_mfma_f32_16x16x32_bf16 v[28:31], v[152:155], v[208:211], v[28:31]
	v_mfma_f32_16x16x32_bf16 v[24:27], v[166:169], v[208:211], v[24:27]
	v_mfma_f32_16x16x32_bf16 v[12:15], v[152:155], v[216:219], v[12:15]
	v_mfma_f32_16x16x32_bf16 v[8:11], v[166:169], v[216:219], v[8:11]
	v_mfma_f32_16x16x32_bf16 v[52:55], v[170:173], v[188:191], v[52:55]
	v_mfma_f32_16x16x32_bf16 v[48:51], v[180:183], v[188:191], v[48:51]
	v_mfma_f32_16x16x32_bf16 v[36:39], v[170:173], v[196:199], v[36:39]
	v_mfma_f32_16x16x32_bf16 v[32:35], v[180:183], v[196:199], v[32:35]
	v_mfma_f32_16x16x32_bf16 v[20:23], v[170:173], v[204:207], v[20:23]
	v_mfma_f32_16x16x32_bf16 v[16:19], v[180:183], v[204:207], v[16:19]
	v_mfma_f32_16x16x32_bf16 v[4:7], v[170:173], v[212:215], v[4:7]
	v_mfma_f32_16x16x32_bf16 v[0:3], v[180:183], v[212:215], v[0:3]
	v_mfma_f32_16x16x32_bf16 v[52:55], v[176:179], v[192:195], v[52:55]
	v_mfma_f32_16x16x32_bf16 v[48:51], v[184:187], v[192:195], v[48:51]
	v_mfma_f32_16x16x32_bf16 v[36:39], v[176:179], v[200:203], v[36:39]
	v_mfma_f32_16x16x32_bf16 v[32:35], v[184:187], v[200:203], v[32:35]
	v_mfma_f32_16x16x32_bf16 v[20:23], v[176:179], v[208:211], v[20:23]
	v_mfma_f32_16x16x32_bf16 v[16:19], v[184:187], v[208:211], v[16:19]
	v_mfma_f32_16x16x32_bf16 v[4:7], v[176:179], v[216:219], v[4:7]
	v_mfma_f32_16x16x32_bf16 v[0:3], v[184:187], v[216:219], v[0:3]
	s_barrier
	ds_read_b128 v[148:151], v146
	ds_read_b128 v[152:155], v146 offset:1024
	ds_read_b128 v[156:159], v146 offset:2048
	ds_read_b128 v[166:169], v146 offset:3072
	ds_read_b128 v[170:173], v147
	ds_read_b128 v[176:179], v147 offset:1024
	ds_read_b128 v[180:183], v147 offset:2048
	ds_read_b128 v[184:187], v147 offset:3072
	s_add_u32 s62, s62, 0x40000
	s_addc_u32 s63, s63, 0
	s_mov_b32 m0, s35
	v_lshl_add_u64 v[228:229], s[62:63], 0, v[136:137]
	ds_read_b128 v[188:191], v145 offset:32768
	ds_read_b128 v[192:195], v145 offset:33792
	ds_read_b128 v[196:199], v145 offset:34816
	ds_read_b128 v[200:203], v145 offset:35840
	ds_read_b128 v[204:207], v145 offset:36864
	ds_read_b128 v[208:211], v145 offset:37888
	ds_read_b128 v[212:215], v145 offset:38912
	ds_read_b128 v[216:219], v145 offset:39936
	global_load_lds_dwordx4 v[228:229], off
	v_lshl_add_u64 v[228:229], s[62:63], 0, v[132:133]
	s_mov_b32 m0, s38
	s_nop 0
	global_load_lds_dwordx4 v[228:229], off
	s_waitcnt vmcnt(8)
	s_waitcnt lgkmcnt(0)
	s_barrier
	s_waitcnt lgkmcnt(0)
	v_mfma_f32_16x16x32_bf16 v[124:127], v[148:151], v[188:191], v[124:127]
	v_mfma_f32_16x16x32_bf16 v[120:123], v[156:159], v[188:191], v[120:123]
	v_mfma_f32_16x16x32_bf16 v[108:111], v[148:151], v[196:199], v[108:111]
	v_mfma_f32_16x16x32_bf16 v[104:107], v[156:159], v[196:199], v[104:107]
	v_mfma_f32_16x16x32_bf16 v[92:95], v[148:151], v[204:207], v[92:95]
	v_mfma_f32_16x16x32_bf16 v[88:91], v[156:159], v[204:207], v[88:91]
	v_mfma_f32_16x16x32_bf16 v[76:79], v[148:151], v[212:215], v[76:79]
	v_mfma_f32_16x16x32_bf16 v[72:75], v[156:159], v[212:215], v[72:75]
	v_mfma_f32_16x16x32_bf16 v[124:127], v[152:155], v[192:195], v[124:127]
	v_mfma_f32_16x16x32_bf16 v[120:123], v[166:169], v[192:195], v[120:123]
	v_mfma_f32_16x16x32_bf16 v[108:111], v[152:155], v[200:203], v[108:111]
	v_mfma_f32_16x16x32_bf16 v[104:107], v[166:169], v[200:203], v[104:107]
	v_mfma_f32_16x16x32_bf16 v[92:95], v[152:155], v[208:211], v[92:95]
	v_mfma_f32_16x16x32_bf16 v[88:91], v[166:169], v[208:211], v[88:91]
	v_mfma_f32_16x16x32_bf16 v[76:79], v[152:155], v[216:219], v[76:79]
	v_mfma_f32_16x16x32_bf16 v[72:75], v[166:169], v[216:219], v[72:75]
	v_mfma_f32_16x16x32_bf16 v[116:119], v[170:173], v[188:191], v[116:119]
	v_mfma_f32_16x16x32_bf16 v[112:115], v[180:183], v[188:191], v[112:115]
	v_mfma_f32_16x16x32_bf16 v[100:103], v[170:173], v[196:199], v[100:103]
	v_mfma_f32_16x16x32_bf16 v[96:99], v[180:183], v[196:199], v[96:99]
	v_mfma_f32_16x16x32_bf16 v[84:87], v[170:173], v[204:207], v[84:87]
	v_mfma_f32_16x16x32_bf16 v[80:83], v[180:183], v[204:207], v[80:83]
	v_mfma_f32_16x16x32_bf16 v[68:71], v[170:173], v[212:215], v[68:71]
	v_mfma_f32_16x16x32_bf16 v[64:67], v[180:183], v[212:215], v[64:67]
	v_mfma_f32_16x16x32_bf16 v[116:119], v[176:179], v[192:195], v[116:119]
	v_mfma_f32_16x16x32_bf16 v[112:115], v[184:187], v[192:195], v[112:115]
	v_mfma_f32_16x16x32_bf16 v[100:103], v[176:179], v[200:203], v[100:103]
	v_mfma_f32_16x16x32_bf16 v[96:99], v[184:187], v[200:203], v[96:99]
	v_mfma_f32_16x16x32_bf16 v[84:87], v[176:179], v[208:211], v[84:87]
	v_mfma_f32_16x16x32_bf16 v[80:83], v[184:187], v[208:211], v[80:83]
	v_mfma_f32_16x16x32_bf16 v[68:71], v[176:179], v[216:219], v[68:71]
	v_mfma_f32_16x16x32_bf16 v[64:67], v[184:187], v[216:219], v[64:67]
	s_barrier
; #define PG8_STAGE(bufoff, gbase, voff) do { _Pragma("unroll") for (int _i = 0; _i < 2; ++_i) \
;         __builtin_amdgcn_global_load_lds((const unsigned*)((const char*)(gbase) + (voff)[_i]), (LAS unsigned*)(lds + (bufoff) + ldsw + _i * 8192), 16, 0, 0); } while (0)
; #define PG8_LDA(dst, b, h) do { _Pragma("unroll") for (int m = 0; m < 4; ++m) _Pragma("unroll") for (int k = 0; k < 2; ++k) dst[m][k] = *(const LAS bf16x8*)(lds + PG8_SA(b, h) + aoff + m * 2048 + k * 1024); } while (0)
; #define PG8_MMA(ai, bj, At, Bt) do { __builtin_amdgcn_s_setprio(1); _Pragma("unroll") for (int m = 0; m < 4; ++m) _Pragma("unroll") for (int n = 0; n < 2; ++n) _Pragma("unroll") for (int k = 0; k < 2; ++k) \
;         acc[ai][bj][m][n] = __builtin_amdgcn_mfma_f32_16x16x32_bf16(Bt[n][k], At[m][k], acc[ai][bj][m][n], 0, 0, 0); __builtin_amdgcn_s_setprio(0); } while (0)
; #define PG8_WAIT_V(n) asm volatile("s_waitcnt vmcnt(" #n ")" ::: "memory")
; #define PG8_WAIT_L(n) asm volatile("s_waitcnt lgkmcnt(" #n ")" ::: "memory")
; #define PG8_BAR __builtin_amdgcn_s_barrier()
; #define PG8_SCHED __builtin_amdgcn_sched_barrier(0)
; template <class Epi, class Sched, bool ALIGN_EPI = true, bool SP2 = true>
; __device__ __forceinline__ void gemm_phase(LAS unsigned char* lds, const Gemm g, const Sched& S, const Epi& E) {
;     ...
;             PG8_LDA(At, 1, 1); PG8_STAGE(PG8_SB(1, 0), b3, voffB); PG8_STAGE(PG8_SB(1, 1), b3 + hstep, voffB); PG8_STAGE(PG8_SA(1, 0), a3, voffA);
;             PG8_WAIT_V(8); PG8_WAIT_L(0); PG8_BAR; PG8_MMA(1, 0, At, B0); PG8_MMA(1, 1, At, B1); PG8_BAR; PG8_SCHED;
;     ...
;         if constexpr (ALIGN_EPI) { if (wr == 0) PG8_BAR; }
	s_mov_b32 m0, s73
	v_lshl_add_u64 v[220:221], v[220:221], 0, s[12:13]
	s_add_u32 s60, s60, 0x40080
	ds_read_b128 v[188:191], v145 offset:49152
	ds_read_b128 v[192:195], v145 offset:50176
	ds_read_b128 v[196:199], v145 offset:51200
	ds_read_b128 v[200:203], v145 offset:52224
	ds_read_b128 v[204:207], v145 offset:53248
	ds_read_b128 v[208:211], v145 offset:54272
	ds_read_b128 v[212:215], v145 offset:55296
	ds_read_b128 v[216:219], v145 offset:56320
	global_load_lds_dwordx4 v[220:221], off
	v_lshl_add_u64 v[220:221], v[222:223], 0, s[12:13]
	s_mov_b32 m0, s78
	s_addc_u32 s61, s61, 0
	global_load_lds_dwordx4 v[220:221], off
	v_lshl_add_u64 v[220:221], s[60:61], 0, v[134:135]
	s_mov_b32 m0, s79
	s_nop 0
	global_load_lds_dwordx4 v[220:221], off
	v_lshl_add_u64 v[220:221], s[60:61], 0, v[130:131]
	s_mov_b32 m0, s84
	s_nop 0
	global_load_lds_dwordx4 v[220:221], off
	v_lshl_add_u64 v[220:221], v[224:225], 0, s[12:13]
	s_mov_b32 m0, s42
	s_nop 0
	global_load_lds_dwordx4 v[220:221], off
	v_lshl_add_u64 v[220:221], v[226:227], 0, s[12:13]
	s_mov_b32 m0, s43
	s_nop 0
	global_load_lds_dwordx4 v[220:221], off
	s_waitcnt vmcnt(8)
	s_waitcnt lgkmcnt(0)
	s_barrier
	s_waitcnt lgkmcnt(0)
	v_mfma_f32_16x16x32_bf16 v[60:63], v[148:151], v[188:191], v[60:63]
	v_mfma_f32_16x16x32_bf16 v[56:59], v[156:159], v[188:191], v[56:59]
	v_mfma_f32_16x16x32_bf16 v[44:47], v[148:151], v[196:199], v[44:47]
	v_mfma_f32_16x16x32_bf16 v[40:43], v[156:159], v[196:199], v[40:43]
	v_mfma_f32_16x16x32_bf16 v[28:31], v[148:151], v[204:207], v[28:31]
	v_mfma_f32_16x16x32_bf16 v[24:27], v[156:159], v[204:207], v[24:27]
	v_mfma_f32_16x16x32_bf16 v[12:15], v[148:151], v[212:215], v[12:15]
	v_mfma_f32_16x16x32_bf16 v[8:11], v[156:159], v[212:215], v[8:11]
	v_mfma_f32_16x16x32_bf16 v[60:63], v[152:155], v[192:195], v[60:63]
	v_mfma_f32_16x16x32_bf16 v[56:59], v[166:169], v[192:195], v[56:59]
	v_mfma_f32_16x16x32_bf16 v[44:47], v[152:155], v[200:203], v[44:47]
	v_mfma_f32_16x16x32_bf16 v[40:43], v[166:169], v[200:203], v[40:43]
	v_mfma_f32_16x16x32_bf16 v[28:31], v[152:155], v[208:211], v[28:31]
	v_mfma_f32_16x16x32_bf16 v[24:27], v[166:169], v[208:211], v[24:27]
	v_mfma_f32_16x16x32_bf16 v[12:15], v[152:155], v[216:219], v[12:15]
	v_mfma_f32_16x16x32_bf16 v[8:11], v[166:169], v[216:219], v[8:11]
	v_mfma_f32_16x16x32_bf16 v[52:55], v[170:173], v[188:191], v[52:55]
	v_mfma_f32_16x16x32_bf16 v[48:51], v[180:183], v[188:191], v[48:51]
	v_mfma_f32_16x16x32_bf16 v[36:39], v[170:173], v[196:199], v[36:39]
	v_mfma_f32_16x16x32_bf16 v[32:35], v[180:183], v[196:199], v[32:35]
	v_mfma_f32_16x16x32_bf16 v[20:23], v[170:173], v[204:207], v[20:23]
	v_mfma_f32_16x16x32_bf16 v[16:19], v[180:183], v[204:207], v[16:19]
	v_mfma_f32_16x16x32_bf16 v[4:7], v[170:173], v[212:215], v[4:7]
	v_mfma_f32_16x16x32_bf16 v[0:3], v[180:183], v[212:215], v[0:3]
	v_mfma_f32_16x16x32_bf16 v[52:55], v[176:179], v[192:195], v[52:55]
	v_mfma_f32_16x16x32_bf16 v[48:51], v[184:187], v[192:195], v[48:51]
	v_mfma_f32_16x16x32_bf16 v[36:39], v[176:179], v[200:203], v[36:39]
	v_mfma_f32_16x16x32_bf16 v[32:35], v[184:187], v[200:203], v[32:35]
	v_mfma_f32_16x16x32_bf16 v[20:23], v[176:179], v[208:211], v[20:23]
	v_mfma_f32_16x16x32_bf16 v[16:19], v[184:187], v[208:211], v[16:19]
	v_mfma_f32_16x16x32_bf16 v[4:7], v[176:179], v[216:219], v[4:7]
	v_mfma_f32_16x16x32_bf16 v[0:3], v[184:187], v[216:219], v[0:3]
	s_barrier
	s_add_i32 s64, s64, 2
	s_add_u32 s48, s48, 0x100
	s_addc_u32 s49, s49, 0
	s_cmp_gt_u32 s64, 13
	s_cbranch_scc0 .LBB0_244
	s_cmpk_lt_u32 s23, 0x100
	s_cbranch_scc0 .LBB0_247
	s_barrier

; #define PG8_STAGE(bufoff, gbase, voff) do { _Pragma("unroll") for (int _i = 0; _i < 2; ++_i) \
;         __builtin_amdgcn_global_load_lds((const unsigned*)((const char*)(gbase) + (voff)[_i]), (LAS unsigned*)(lds + (bufoff) + ldsw + _i * 8192), 16, 0, 0); } while (0)
; #define PG8_LDA(dst, b, h) do { _Pragma("unroll") for (int m = 0; m < 4; ++m) _Pragma("unroll") for (int k = 0; k < 2; ++k) dst[m][k] = *(const LAS bf16x8*)(lds + PG8_SA(b, h) + aoff + m * 2048 + k * 1024); } while (0)
; #define PG8_LDB(dst, b, h) do { _Pragma("unroll") for (int n = 0; n < 2; ++n) _Pragma("unroll") for (int k = 0; k < 2; ++k) dst[n][k] = *(const LAS bf16x8*)(lds + PG8_SB(b, h) + boff + n * 2048 + k * 1024); } while (0)
; #define PG8_MMA(ai, bj, At, Bt) do { __builtin_amdgcn_s_setprio(1); _Pragma("unroll") for (int m = 0; m < 4; ++m) _Pragma("unroll") for (int n = 0; n < 2; ++n) _Pragma("unroll") for (int k = 0; k < 2; ++k) \
;         acc[ai][bj][m][n] = __builtin_amdgcn_mfma_f32_16x16x32_bf16(Bt[n][k], At[m][k], acc[ai][bj][m][n], 0, 0, 0); __builtin_amdgcn_s_setprio(0); } while (0)
; #define PG8_WAIT_V(n) asm volatile("s_waitcnt vmcnt(" #n ")" ::: "memory")
; #define PG8_WAIT_L(n) asm volatile("s_waitcnt lgkmcnt(" #n ")" ::: "memory")
; #define PG8_BAR __builtin_amdgcn_s_barrier()
; #define PG8_SCHED __builtin_amdgcn_sched_barrier(0)
; template <class Epi, class Sched, bool ALIGN_EPI = true, bool SP2 = true>
; __device__ __forceinline__ void gemm_phase(LAS unsigned char* lds, const Gemm g, const Sched& S, const Epi& E) {
;     ...
;             PG8_LDB(B0, 0, 0); PG8_LDB(B1, 0, 1); PG8_SCHED; PG8_LDA(At, 0, 0); PG8_STAGE(PG8_SA(1, 1), a1 + hstep, voffA);
;             PG8_WAIT_V(8); PG8_WAIT_L(0); PG8_BAR; PG8_MMA(0, 0, At, B0); PG8_MMA(0, 1, At, B1); PG8_BAR; PG8_SCHED;
;             PG8_LDA(At, 0, 1); PG8_STAGE(PG8_SB(0, 0), b2, voffB); PG8_STAGE(PG8_SB(0, 1), b2 + hstep, voffB); PG8_STAGE(PG8_SA(0, 0), a2, voffA);
;             PG8_WAIT_V(8); PG8_WAIT_L(0); PG8_BAR; PG8_MMA(1, 0, At, B0); PG8_MMA(1, 1, At, B1); PG8_BAR; PG8_SCHED;
.LBB0_271:
	ds_read_b128 v[152:155], v148
	ds_read_b128 v[156:159], v148 offset:1024
	ds_read_b128 v[166:169], v148 offset:2048
	ds_read_b128 v[170:173], v148 offset:3072
	ds_read_b128 v[176:179], v149
	ds_read_b128 v[180:183], v149 offset:1024
	ds_read_b128 v[184:187], v149 offset:2048
	ds_read_b128 v[188:191], v149 offset:3072
	s_add_u32 s46, s90, 0xfffc0080
	s_addc_u32 s47, s91, -1
	s_cmp_eq_u32 vcc_hi, 12
	s_cselect_b32 s95, s65, s47
	s_cselect_b32 s94, s84, s46
	s_cselect_b32 s93, s69, vcc_lo
	s_cselect_b32 s92, s85, s89
	v_lshl_add_u64 v[144:145], s[90:91], 0, v[138:139]
	s_add_i32 m0, s25, 0xc000
	ds_read_b128 v[192:195], v150
	ds_read_b128 v[196:199], v150 offset:1024
	ds_read_b128 v[200:203], v150 offset:2048
	ds_read_b128 v[204:207], v150 offset:3072
	ds_read_b128 v[208:211], v150 offset:4096
	ds_read_b128 v[212:215], v150 offset:5120
	ds_read_b128 v[216:219], v150 offset:6144
	ds_read_b128 v[220:223], v150 offset:7168
	global_load_lds_dwordx4 v[144:145], off
	v_lshl_add_u64 v[144:145], s[90:91], 0, v[140:141]
	s_add_i32 m0, s25, 0xe000
	s_nop 0
	global_load_lds_dwordx4 v[144:145], off
	s_waitcnt vmcnt(8)
	s_waitcnt lgkmcnt(0)
	s_barrier
	s_waitcnt lgkmcnt(0)
	v_mfma_f32_16x16x32_bf16 v[124:127], v[152:155], v[192:195], v[124:127]
	v_mfma_f32_16x16x32_bf16 v[120:123], v[166:169], v[192:195], v[120:123]
	v_mfma_f32_16x16x32_bf16 v[108:111], v[152:155], v[200:203], v[108:111]
	v_mfma_f32_16x16x32_bf16 v[104:107], v[166:169], v[200:203], v[104:107]
	v_mfma_f32_16x16x32_bf16 v[92:95], v[152:155], v[208:211], v[92:95]
	v_mfma_f32_16x16x32_bf16 v[88:91], v[166:169], v[208:211], v[88:91]
	v_mfma_f32_16x16x32_bf16 v[76:79], v[152:155], v[216:219], v[76:79]
	v_mfma_f32_16x16x32_bf16 v[72:75], v[166:169], v[216:219], v[72:75]
	v_mfma_f32_16x16x32_bf16 v[124:127], v[156:159], v[196:199], v[124:127]
	v_mfma_f32_16x16x32_bf16 v[120:123], v[170:173], v[196:199], v[120:123]
	v_mfma_f32_16x16x32_bf16 v[108:111], v[156:159], v[204:207], v[108:111]
	v_mfma_f32_16x16x32_bf16 v[104:107], v[170:173], v[204:207], v[104:107]
	v_mfma_f32_16x16x32_bf16 v[92:95], v[156:159], v[212:215], v[92:95]
	v_mfma_f32_16x16x32_bf16 v[88:91], v[170:173], v[212:215], v[88:91]
	v_mfma_f32_16x16x32_bf16 v[76:79], v[156:159], v[220:223], v[76:79]
	v_mfma_f32_16x16x32_bf16 v[72:75], v[170:173], v[220:223], v[72:75]
	v_mfma_f32_16x16x32_bf16 v[116:119], v[176:179], v[192:195], v[116:119]
	v_mfma_f32_16x16x32_bf16 v[112:115], v[184:187], v[192:195], v[112:115]
	v_mfma_f32_16x16x32_bf16 v[100:103], v[176:179], v[200:203], v[100:103]
	v_mfma_f32_16x16x32_bf16 v[96:99], v[184:187], v[200:203], v[96:99]
	v_mfma_f32_16x16x32_bf16 v[84:87], v[176:179], v[208:211], v[84:87]
	v_mfma_f32_16x16x32_bf16 v[80:83], v[184:187], v[208:211], v[80:83]
	v_mfma_f32_16x16x32_bf16 v[68:71], v[176:179], v[216:219], v[68:71]
	v_mfma_f32_16x16x32_bf16 v[64:67], v[184:187], v[216:219], v[64:67]
	v_mfma_f32_16x16x32_bf16 v[116:119], v[180:183], v[196:199], v[116:119]
	v_mfma_f32_16x16x32_bf16 v[112:115], v[188:191], v[196:199], v[112:115]
	v_mfma_f32_16x16x32_bf16 v[100:103], v[180:183], v[204:207], v[100:103]
	v_mfma_f32_16x16x32_bf16 v[96:99], v[188:191], v[204:207], v[96:99]
	v_mfma_f32_16x16x32_bf16 v[84:87], v[180:183], v[212:215], v[84:87]
	v_mfma_f32_16x16x32_bf16 v[80:83], v[188:191], v[212:215], v[80:83]
	v_mfma_f32_16x16x32_bf16 v[68:71], v[180:183], v[220:223], v[68:71]
	v_mfma_f32_16x16x32_bf16 v[64:67], v[188:191], v[220:223], v[64:67]
	s_barrier
	s_add_i32 s46, s43, s19
	v_lshl_add_u64 v[144:145], s[92:93], 0, v[134:135]
	s_mov_b32 m0, s46
	ds_read_b128 v[192:195], v150 offset:16384
	ds_read_b128 v[196:199], v150 offset:17408
	ds_read_b128 v[200:203], v150 offset:18432
	ds_read_b128 v[204:207], v150 offset:19456
	ds_read_b128 v[208:211], v150 offset:20480
	ds_read_b128 v[212:215], v150 offset:21504
	ds_read_b128 v[216:219], v150 offset:22528
	ds_read_b128 v[220:223], v150 offset:23552
	global_load_lds_dwordx4 v[144:145], off
	s_add_i32 m0, s46, 0x2000
	s_add_u32 s46, s92, 0x40000
	v_lshl_add_u64 v[224:225], s[92:93], 0, v[130:131]
	s_addc_u32 s47, s93, 0
	s_add_i32 s17, s44, s19
	global_load_lds_dwordx4 v[224:225], off
	v_lshl_add_u64 v[226:227], s[46:47], 0, v[134:135]
	s_mov_b32 m0, s17
	v_lshl_add_u64 v[228:229], s[94:95], 0, v[132:133]
	global_load_lds_dwordx4 v[226:227], off
	v_lshl_add_u64 v[226:227], s[46:47], 0, v[130:131]
	s_add_i32 m0, s17, 0x2000
	s_nop 0
	global_load_lds_dwordx4 v[226:227], off
	v_lshl_add_u64 v[226:227], s[94:95], 0, v[136:137]
	s_mov_b32 m0, s25
	s_nop 0
	global_load_lds_dwordx4 v[226:227], off
	s_mov_b32 m0, s34
	s_nop 0
	global_load_lds_dwordx4 v[228:229], off
	s_waitcnt vmcnt(8)
	s_waitcnt lgkmcnt(0)
	s_barrier
; #define PG8_STAGE(bufoff, gbase, voff) do { _Pragma("unroll") for (int _i = 0; _i < 2; ++_i) \
;         __builtin_amdgcn_global_load_lds((const unsigned*)((const char*)(gbase) + (voff)[_i]), (LAS unsigned*)(lds + (bufoff) + ldsw + _i * 8192), 16, 0, 0); } while (0)
; #define PG8_LDA(dst, b, h) do { _Pragma("unroll") for (int m = 0; m < 4; ++m) _Pragma("unroll") for (int k = 0; k < 2; ++k) dst[m][k] = *(const LAS bf16x8*)(lds + PG8_SA(b, h) + aoff + m * 2048 + k * 1024); } while (0)
; #define PG8_LDB(dst, b, h) do { _Pragma("unroll") for (int n = 0; n < 2; ++n) _Pragma("unroll") for (int k = 0; k < 2; ++k) dst[n][k] = *(const LAS bf16x8*)(lds + PG8_SB(b, h) + boff + n * 2048 + k * 1024); } while (0)
; #define PG8_MMA(ai, bj, At, Bt) do { __builtin_amdgcn_s_setprio(1); _Pragma("unroll") for (int m = 0; m < 4; ++m) _Pragma("unroll") for (int n = 0; n < 2; ++n) _Pragma("unroll") for (int k = 0; k < 2; ++k) \
;         acc[ai][bj][m][n] = __builtin_amdgcn_mfma_f32_16x16x32_bf16(Bt[n][k], At[m][k], acc[ai][bj][m][n], 0, 0, 0); __builtin_amdgcn_s_setprio(0); } while (0)
; #define PG8_WAIT_V(n) asm volatile("s_waitcnt vmcnt(" #n ")" ::: "memory")
; #define PG8_WAIT_L(n) asm volatile("s_waitcnt lgkmcnt(" #n ")" ::: "memory")
; #define PG8_BAR __builtin_amdgcn_s_barrier()
; #define PG8_SCHED __builtin_amdgcn_sched_barrier(0)
; template <class Epi, class Sched, bool ALIGN_EPI = true, bool SP2 = true>
; __device__ __forceinline__ void gemm_phase(LAS unsigned char* lds, const Gemm g, const Sched& S, const Epi& E) {
;     ...
;             PG8_WAIT_V(8); PG8_WAIT_L(0); PG8_BAR; PG8_MMA(1, 0, At, B0); PG8_MMA(1, 1, At, B1); PG8_BAR; PG8_SCHED;
;             PG8_LDB(B0, 1, 0); PG8_LDB(B1, 1, 1); PG8_SCHED; PG8_LDA(At, 1, 0); PG8_STAGE(PG8_SA(0, 1), a2 + hstep, voffA);
;             PG8_WAIT_V(8); PG8_WAIT_L(0); PG8_BAR; PG8_MMA(0, 0, At, B0); PG8_MMA(0, 1, At, B1); PG8_BAR; PG8_SCHED;
	s_waitcnt lgkmcnt(0)
	v_mfma_f32_16x16x32_bf16 v[60:63], v[152:155], v[192:195], v[60:63]
	v_mfma_f32_16x16x32_bf16 v[56:59], v[166:169], v[192:195], v[56:59]
	v_mfma_f32_16x16x32_bf16 v[44:47], v[152:155], v[200:203], v[44:47]
	v_mfma_f32_16x16x32_bf16 v[40:43], v[166:169], v[200:203], v[40:43]
	v_mfma_f32_16x16x32_bf16 v[28:31], v[152:155], v[208:211], v[28:31]
	v_mfma_f32_16x16x32_bf16 v[24:27], v[166:169], v[208:211], v[24:27]
	v_mfma_f32_16x16x32_bf16 v[12:15], v[152:155], v[216:219], v[12:15]
	v_mfma_f32_16x16x32_bf16 v[8:11], v[166:169], v[216:219], v[8:11]
	v_mfma_f32_16x16x32_bf16 v[60:63], v[156:159], v[196:199], v[60:63]
	v_mfma_f32_16x16x32_bf16 v[56:59], v[170:173], v[196:199], v[56:59]
	v_mfma_f32_16x16x32_bf16 v[44:47], v[156:159], v[204:207], v[44:47]
	v_mfma_f32_16x16x32_bf16 v[40:43], v[170:173], v[204:207], v[40:43]
	v_mfma_f32_16x16x32_bf16 v[28:31], v[156:159], v[212:215], v[28:31]
	v_mfma_f32_16x16x32_bf16 v[24:27], v[170:173], v[212:215], v[24:27]
	v_mfma_f32_16x16x32_bf16 v[12:15], v[156:159], v[220:223], v[12:15]
	v_mfma_f32_16x16x32_bf16 v[8:11], v[170:173], v[220:223], v[8:11]
	v_mfma_f32_16x16x32_bf16 v[52:55], v[176:179], v[192:195], v[52:55]
	v_mfma_f32_16x16x32_bf16 v[48:51], v[184:187], v[192:195], v[48:51]
	v_mfma_f32_16x16x32_bf16 v[36:39], v[176:179], v[200:203], v[36:39]
	v_mfma_f32_16x16x32_bf16 v[32:35], v[184:187], v[200:203], v[32:35]
	v_mfma_f32_16x16x32_bf16 v[20:23], v[176:179], v[208:211], v[20:23]
	v_mfma_f32_16x16x32_bf16 v[16:19], v[184:187], v[208:211], v[16:19]
	v_mfma_f32_16x16x32_bf16 v[4:7], v[176:179], v[216:219], v[4:7]
	v_mfma_f32_16x16x32_bf16 v[0:3], v[184:187], v[216:219], v[0:3]
	v_mfma_f32_16x16x32_bf16 v[52:55], v[180:183], v[196:199], v[52:55]
	v_mfma_f32_16x16x32_bf16 v[48:51], v[188:191], v[196:199], v[48:51]
	v_mfma_f32_16x16x32_bf16 v[36:39], v[180:183], v[204:207], v[36:39]
	v_mfma_f32_16x16x32_bf16 v[32:35], v[188:191], v[204:207], v[32:35]
	v_mfma_f32_16x16x32_bf16 v[20:23], v[180:183], v[212:215], v[20:23]
	v_mfma_f32_16x16x32_bf16 v[16:19], v[188:191], v[212:215], v[16:19]
	v_mfma_f32_16x16x32_bf16 v[4:7], v[180:183], v[220:223], v[4:7]
	v_mfma_f32_16x16x32_bf16 v[0:3], v[188:191], v[220:223], v[0:3]
	s_barrier
	s_add_i32 s17, 0, 0x18000
	v_add_u32_e32 v151, s17, v146
	s_add_i32 s16, 0, 0x1c000
	ds_read_b128 v[152:155], v151
	ds_read_b128 v[156:159], v151 offset:1024
	ds_read_b128 v[166:169], v151 offset:2048
	ds_read_b128 v[170:173], v151 offset:3072
	v_add_u32_e32 v151, s16, v146
	ds_read_b128 v[176:179], v151
	ds_read_b128 v[180:183], v151 offset:1024
	ds_read_b128 v[184:187], v151 offset:2048
	ds_read_b128 v[188:191], v151 offset:3072
	s_add_u32 s46, s94, 0x40000
	s_addc_u32 s47, s95, 0
	s_mov_b32 m0, s35
	v_lshl_add_u64 v[230:231], s[46:47], 0, v[136:137]
	ds_read_b128 v[192:195], v150 offset:32768
	ds_read_b128 v[196:199], v150 offset:33792
	ds_read_b128 v[200:203], v150 offset:34816
	ds_read_b128 v[204:207], v150 offset:35840
	ds_read_b128 v[208:211], v150 offset:36864
	ds_read_b128 v[212:215], v150 offset:37888
	ds_read_b128 v[216:219], v150 offset:38912
	ds_read_b128 v[220:223], v150 offset:39936
	global_load_lds_dwordx4 v[230:231], off
	v_lshl_add_u64 v[230:231], s[46:47], 0, v[132:133]
	s_mov_b32 m0, s38
	s_nop 0
	global_load_lds_dwordx4 v[230:231], off
	s_waitcnt vmcnt(8)
	s_waitcnt lgkmcnt(0)
	s_barrier
	s_waitcnt lgkmcnt(0)
	v_mfma_f32_16x16x32_bf16 v[124:127], v[152:155], v[192:195], v[124:127]
	v_mfma_f32_16x16x32_bf16 v[120:123], v[166:169], v[192:195], v[120:123]
	v_mfma_f32_16x16x32_bf16 v[108:111], v[152:155], v[200:203], v[108:111]
	v_mfma_f32_16x16x32_bf16 v[104:107], v[166:169], v[200:203], v[104:107]
	v_mfma_f32_16x16x32_bf16 v[92:95], v[152:155], v[208:211], v[92:95]
	v_mfma_f32_16x16x32_bf16 v[88:91], v[166:169], v[208:211], v[88:91]
	v_mfma_f32_16x16x32_bf16 v[76:79], v[152:155], v[216:219], v[76:79]
	v_mfma_f32_16x16x32_bf16 v[72:75], v[166:169], v[216:219], v[72:75]
	v_mfma_f32_16x16x32_bf16 v[124:127], v[156:159], v[196:199], v[124:127]
	v_mfma_f32_16x16x32_bf16 v[120:123], v[170:173], v[196:199], v[120:123]
	v_mfma_f32_16x16x32_bf16 v[108:111], v[156:159], v[204:207], v[108:111]
	v_mfma_f32_16x16x32_bf16 v[104:107], v[170:173], v[204:207], v[104:107]
	v_mfma_f32_16x16x32_bf16 v[92:95], v[156:159], v[212:215], v[92:95]
	v_mfma_f32_16x16x32_bf16 v[88:91], v[170:173], v[212:215], v[88:91]
	v_mfma_f32_16x16x32_bf16 v[76:79], v[156:159], v[220:223], v[76:79]
	v_mfma_f32_16x16x32_bf16 v[72:75], v[170:173], v[220:223], v[72:75]
	v_mfma_f32_16x16x32_bf16 v[116:119], v[176:179], v[192:195], v[116:119]
	v_mfma_f32_16x16x32_bf16 v[112:115], v[184:187], v[192:195], v[112:115]
	v_mfma_f32_16x16x32_bf16 v[100:103], v[176:179], v[200:203], v[100:103]
	v_mfma_f32_16x16x32_bf16 v[96:99], v[184:187], v[200:203], v[96:99]
	v_mfma_f32_16x16x32_bf16 v[84:87], v[176:179], v[208:211], v[84:87]
	v_mfma_f32_16x16x32_bf16 v[80:83], v[184:187], v[208:211], v[80:83]
	v_mfma_f32_16x16x32_bf16 v[68:71], v[176:179], v[216:219], v[68:71]
	v_mfma_f32_16x16x32_bf16 v[64:67], v[184:187], v[216:219], v[64:67]
	v_mfma_f32_16x16x32_bf16 v[116:119], v[180:183], v[196:199], v[116:119]
	v_mfma_f32_16x16x32_bf16 v[112:115], v[188:191], v[196:199], v[112:115]
	v_mfma_f32_16x16x32_bf16 v[100:103], v[180:183], v[204:207], v[100:103]
	v_mfma_f32_16x16x32_bf16 v[96:99], v[188:191], v[204:207], v[96:99]
	v_mfma_f32_16x16x32_bf16 v[84:87], v[180:183], v[212:215], v[84:87]
	v_mfma_f32_16x16x32_bf16 v[80:83], v[188:191], v[212:215], v[80:83]
	v_mfma_f32_16x16x32_bf16 v[68:71], v[180:183], v[220:223], v[68:71]
	v_mfma_f32_16x16x32_bf16 v[64:67], v[188:191], v[220:223], v[64:67]
	s_barrier
; #define PG8_STAGE(bufoff, gbase, voff) do { _Pragma("unroll") for (int _i = 0; _i < 2; ++_i) \
;         __builtin_amdgcn_global_load_lds((const unsigned*)((const char*)(gbase) + (voff)[_i]), (LAS unsigned*)(lds + (bufoff) + ldsw + _i * 8192), 16, 0, 0); } while (0)
; #define PG8_LDA(dst, b, h) do { _Pragma("unroll") for (int m = 0; m < 4; ++m) _Pragma("unroll") for (int k = 0; k < 2; ++k) dst[m][k] = *(const LAS bf16x8*)(lds + PG8_SA(b, h) + aoff + m * 2048 + k * 1024); } while (0)
; #define PG8_MMA(ai, bj, At, Bt) do { __builtin_amdgcn_s_setprio(1); _Pragma("unroll") for (int m = 0; m < 4; ++m) _Pragma("unroll") for (int n = 0; n < 2; ++n) _Pragma("unroll") for (int k = 0; k < 2; ++k) \
;         acc[ai][bj][m][n] = __builtin_amdgcn_mfma_f32_16x16x32_bf16(Bt[n][k], At[m][k], acc[ai][bj][m][n], 0, 0, 0); __builtin_amdgcn_s_setprio(0); } while (0)
; #define PG8_WAIT_V(n) asm volatile("s_waitcnt vmcnt(" #n ")" ::: "memory")
; #define PG8_WAIT_L(n) asm volatile("s_waitcnt lgkmcnt(" #n ")" ::: "memory")
; #define PG8_BAR __builtin_amdgcn_s_barrier()
; #define PG8_SCHED __builtin_amdgcn_sched_barrier(0)
; template <class Epi, class Sched, bool ALIGN_EPI = true, bool SP2 = true>
; __device__ __forceinline__ void gemm_phase(LAS unsigned char* lds, const Gemm g, const Sched& S, const Epi& E) {
;     ...
;             PG8_LDA(At, 1, 1); PG8_STAGE(PG8_SB(1, 0), b3, voffB); PG8_STAGE(PG8_SB(1, 1), b3 + hstep, voffB); PG8_STAGE(PG8_SA(1, 0), a3, voffA);
;             PG8_WAIT_V(8); PG8_WAIT_L(0); PG8_BAR; PG8_MMA(1, 0, At, B0); PG8_MMA(1, 1, At, B1); PG8_BAR; PG8_SCHED;
;     ...
;         if constexpr (ALIGN_EPI) { if (wr == 0) PG8_BAR; }
	s_add_i32 s17, s17, s19
	v_lshl_add_u64 v[144:145], v[144:145], 0, s[10:11]
	s_mov_b32 m0, s17
	ds_read_b128 v[192:195], v150 offset:49152
	ds_read_b128 v[196:199], v150 offset:50176
	ds_read_b128 v[200:203], v150 offset:51200
	ds_read_b128 v[204:207], v150 offset:52224
	ds_read_b128 v[208:211], v150 offset:53248
	ds_read_b128 v[212:215], v150 offset:54272
	ds_read_b128 v[216:219], v150 offset:55296
	ds_read_b128 v[220:223], v150 offset:56320
	global_load_lds_dwordx4 v[144:145], off
	s_add_i32 m0, s17, 0x2000
	s_add_u32 s46, s92, 0x40080
	v_lshl_add_u64 v[144:145], v[224:225], 0, s[10:11]
	s_addc_u32 s47, s93, 0
	s_add_i32 s16, s16, s19
	global_load_lds_dwordx4 v[144:145], off
	v_lshl_add_u64 v[144:145], s[46:47], 0, v[134:135]
	s_mov_b32 m0, s16
	s_nop 0
	global_load_lds_dwordx4 v[144:145], off
	v_lshl_add_u64 v[144:145], s[46:47], 0, v[130:131]
	s_add_i32 m0, s16, 0x2000
	s_nop 0
	global_load_lds_dwordx4 v[144:145], off
	v_lshl_add_u64 v[144:145], v[226:227], 0, s[10:11]
	s_mov_b32 m0, s39
	s_nop 0
	global_load_lds_dwordx4 v[144:145], off
	v_lshl_add_u64 v[144:145], v[228:229], 0, s[10:11]
	s_mov_b32 m0, s42
	s_nop 0
	global_load_lds_dwordx4 v[144:145], off
	s_waitcnt vmcnt(8)
	s_waitcnt lgkmcnt(0)
	s_barrier
	s_waitcnt lgkmcnt(0)
	v_mfma_f32_16x16x32_bf16 v[60:63], v[152:155], v[192:195], v[60:63]
	v_mfma_f32_16x16x32_bf16 v[56:59], v[166:169], v[192:195], v[56:59]
	v_mfma_f32_16x16x32_bf16 v[44:47], v[152:155], v[200:203], v[44:47]
	v_mfma_f32_16x16x32_bf16 v[40:43], v[166:169], v[200:203], v[40:43]
	v_mfma_f32_16x16x32_bf16 v[28:31], v[152:155], v[208:211], v[28:31]
	v_mfma_f32_16x16x32_bf16 v[24:27], v[166:169], v[208:211], v[24:27]
	v_mfma_f32_16x16x32_bf16 v[12:15], v[152:155], v[216:219], v[12:15]
	v_mfma_f32_16x16x32_bf16 v[8:11], v[166:169], v[216:219], v[8:11]
	v_mfma_f32_16x16x32_bf16 v[60:63], v[156:159], v[196:199], v[60:63]
	v_mfma_f32_16x16x32_bf16 v[56:59], v[170:173], v[196:199], v[56:59]
	v_mfma_f32_16x16x32_bf16 v[44:47], v[156:159], v[204:207], v[44:47]
	v_mfma_f32_16x16x32_bf16 v[40:43], v[170:173], v[204:207], v[40:43]
	v_mfma_f32_16x16x32_bf16 v[28:31], v[156:159], v[212:215], v[28:31]
	v_mfma_f32_16x16x32_bf16 v[24:27], v[170:173], v[212:215], v[24:27]
	v_mfma_f32_16x16x32_bf16 v[12:15], v[156:159], v[220:223], v[12:15]
	v_mfma_f32_16x16x32_bf16 v[8:11], v[170:173], v[220:223], v[8:11]
	v_mfma_f32_16x16x32_bf16 v[52:55], v[176:179], v[192:195], v[52:55]
	v_mfma_f32_16x16x32_bf16 v[48:51], v[184:187], v[192:195], v[48:51]
	v_mfma_f32_16x16x32_bf16 v[36:39], v[176:179], v[200:203], v[36:39]
	v_mfma_f32_16x16x32_bf16 v[32:35], v[184:187], v[200:203], v[32:35]
	v_mfma_f32_16x16x32_bf16 v[20:23], v[176:179], v[208:211], v[20:23]
	v_mfma_f32_16x16x32_bf16 v[16:19], v[184:187], v[208:211], v[16:19]
	v_mfma_f32_16x16x32_bf16 v[4:7], v[176:179], v[216:219], v[4:7]
	v_mfma_f32_16x16x32_bf16 v[0:3], v[184:187], v[216:219], v[0:3]
	v_mfma_f32_16x16x32_bf16 v[52:55], v[180:183], v[196:199], v[52:55]
	v_mfma_f32_16x16x32_bf16 v[48:51], v[188:191], v[196:199], v[48:51]
	v_mfma_f32_16x16x32_bf16 v[36:39], v[180:183], v[204:207], v[36:39]
	v_mfma_f32_16x16x32_bf16 v[32:35], v[188:191], v[204:207], v[32:35]
	v_mfma_f32_16x16x32_bf16 v[20:23], v[180:183], v[212:215], v[20:23]
	v_mfma_f32_16x16x32_bf16 v[16:19], v[188:191], v[212:215], v[16:19]
	v_mfma_f32_16x16x32_bf16 v[4:7], v[180:183], v[220:223], v[4:7]
	v_mfma_f32_16x16x32_bf16 v[0:3], v[188:191], v[220:223], v[0:3]
	s_barrier
	s_add_i32 vcc_hi, vcc_hi, 2
	s_add_u32 s90, s90, 0x100
	s_addc_u32 s91, s91, 0
	s_add_u32 s89, s89, 0x100
	s_addc_u32 vcc_lo, vcc_lo, 0
	s_cmp_gt_u32 vcc_hi, 13
	s_cbranch_scc0 .LBB0_271
	s_and_b64 vcc, exec, s[12:13]
	s_cbranch_vccz .LBB0_274
	s_barrier

; #define PG8_STAGE(bufoff, gbase, voff) do { _Pragma("unroll") for (int _i = 0; _i < 2; ++_i) \
;         __builtin_amdgcn_global_load_lds((const unsigned*)((const char*)(gbase) + (voff)[_i]), (LAS unsigned*)(lds + (bufoff) + ldsw + _i * 8192), 16, 0, 0); } while (0)
; #define PG8_LDA(dst, b, h) do { _Pragma("unroll") for (int m = 0; m < 4; ++m) _Pragma("unroll") for (int k = 0; k < 2; ++k) dst[m][k] = *(const LAS bf16x8*)(lds + PG8_SA(b, h) + aoff + m * 2048 + k * 1024); } while (0)
; #define PG8_LDB(dst, b, h) do { _Pragma("unroll") for (int n = 0; n < 2; ++n) _Pragma("unroll") for (int k = 0; k < 2; ++k) dst[n][k] = *(const LAS bf16x8*)(lds + PG8_SB(b, h) + boff + n * 2048 + k * 1024); } while (0)
; #define PG8_MMA(ai, bj, At, Bt) do { __builtin_amdgcn_s_setprio(1); _Pragma("unroll") for (int m = 0; m < 4; ++m) _Pragma("unroll") for (int n = 0; n < 2; ++n) _Pragma("unroll") for (int k = 0; k < 2; ++k) \
;         acc[ai][bj][m][n] = __builtin_amdgcn_mfma_f32_16x16x32_bf16(Bt[n][k], At[m][k], acc[ai][bj][m][n], 0, 0, 0); __builtin_amdgcn_s_setprio(0); } while (0)
; #define PG8_WAIT_V(n) asm volatile("s_waitcnt vmcnt(" #n ")" ::: "memory")
; #define PG8_WAIT_L(n) asm volatile("s_waitcnt lgkmcnt(" #n ")" ::: "memory")
; #define PG8_BAR __builtin_amdgcn_s_barrier()
; #define PG8_SCHED __builtin_amdgcn_sched_barrier(0)
; template <class Epi, class Sched, bool ALIGN_EPI = true, bool SP2 = true>
; __device__ __forceinline__ void gemm_phase(LAS unsigned char* lds, const Gemm g, const Sched& S, const Epi& E) {
;     ...
;             PG8_LDB(B0, 0, 0); PG8_LDB(B1, 0, 1); PG8_SCHED; PG8_LDA(At, 0, 0); PG8_STAGE(PG8_SA(1, 1), a1 + hstep, voffA);
;             PG8_WAIT_V(8); PG8_WAIT_L(0); PG8_BAR; PG8_MMA(0, 0, At, B0); PG8_MMA(0, 1, At, B1); PG8_BAR; PG8_SCHED;
;             PG8_LDA(At, 0, 1); PG8_STAGE(PG8_SB(0, 0), b2, voffB); PG8_STAGE(PG8_SB(0, 1), b2 + hstep, voffB); PG8_STAGE(PG8_SA(0, 0), a2, voffA);
;             PG8_WAIT_V(8); PG8_WAIT_L(0); PG8_BAR; PG8_MMA(1, 0, At, B0); PG8_MMA(1, 1, At, B1); PG8_BAR; PG8_SCHED;
.LBB0_285:
	ds_read_b128 v[148:151], v143
	ds_read_b128 v[152:155], v143 offset:1024
	ds_read_b128 v[156:159], v143 offset:2048
	ds_read_b128 v[166:169], v143 offset:3072
	ds_read_b128 v[170:173], v144
	ds_read_b128 v[176:179], v144 offset:1024
	ds_read_b128 v[180:183], v144 offset:2048
	ds_read_b128 v[184:187], v144 offset:3072
	s_add_u32 s16, s12, s14
	s_addc_u32 s17, s13, s15
	s_add_u32 s16, s16, 0xd300100
	s_addc_u32 s17, s17, 0
	s_add_u32 s46, s43, s14
	s_addc_u32 s47, s44, s15
	s_cmpk_eq_i32 s14, 0x1500
	s_cselect_b32 s63, s5, s17
	s_cselect_b32 s62, s4, s16
	s_cselect_b32 s61, s1, s47
	s_cselect_b32 s60, s0, s46
	s_mov_b32 m0, s48
	v_lshl_add_u64 v[220:221], v[138:139], 0, s[14:15]
	ds_read_b128 v[188:191], v145
	ds_read_b128 v[192:195], v145 offset:1024
	ds_read_b128 v[196:199], v145 offset:2048
	ds_read_b128 v[200:203], v145 offset:3072
	ds_read_b128 v[204:207], v145 offset:4096
	ds_read_b128 v[208:211], v145 offset:5120
	ds_read_b128 v[212:215], v145 offset:6144
	ds_read_b128 v[216:219], v145 offset:7168
	global_load_lds_dwordx4 v[220:221], off
	v_lshl_add_u64 v[220:221], v[140:141], 0, s[14:15]
	s_mov_b32 m0, s49
	s_nop 0
	global_load_lds_dwordx4 v[220:221], off
	s_waitcnt vmcnt(8)
	s_waitcnt lgkmcnt(0)
	s_barrier
	s_waitcnt lgkmcnt(0)
	v_mfma_f32_16x16x32_bf16 v[124:127], v[148:151], v[188:191], v[124:127]
	v_mfma_f32_16x16x32_bf16 v[120:123], v[156:159], v[188:191], v[120:123]
	v_mfma_f32_16x16x32_bf16 v[116:119], v[148:151], v[196:199], v[116:119]
	v_mfma_f32_16x16x32_bf16 v[112:115], v[156:159], v[196:199], v[112:115]
	v_mfma_f32_16x16x32_bf16 v[100:103], v[148:151], v[204:207], v[100:103]
	v_mfma_f32_16x16x32_bf16 v[96:99], v[156:159], v[204:207], v[96:99]
	v_mfma_f32_16x16x32_bf16 v[84:87], v[148:151], v[212:215], v[84:87]
	v_mfma_f32_16x16x32_bf16 v[80:83], v[156:159], v[212:215], v[80:83]
	v_mfma_f32_16x16x32_bf16 v[124:127], v[152:155], v[192:195], v[124:127]
	v_mfma_f32_16x16x32_bf16 v[120:123], v[166:169], v[192:195], v[120:123]
	v_mfma_f32_16x16x32_bf16 v[116:119], v[152:155], v[200:203], v[116:119]
	v_mfma_f32_16x16x32_bf16 v[112:115], v[166:169], v[200:203], v[112:115]
	v_mfma_f32_16x16x32_bf16 v[100:103], v[152:155], v[208:211], v[100:103]
	v_mfma_f32_16x16x32_bf16 v[96:99], v[166:169], v[208:211], v[96:99]
	v_mfma_f32_16x16x32_bf16 v[84:87], v[152:155], v[216:219], v[84:87]
	v_mfma_f32_16x16x32_bf16 v[80:83], v[166:169], v[216:219], v[80:83]
	v_mfma_f32_16x16x32_bf16 v[108:111], v[170:173], v[188:191], v[108:111]
	v_mfma_f32_16x16x32_bf16 v[104:107], v[180:183], v[188:191], v[104:107]
	v_mfma_f32_16x16x32_bf16 v[92:95], v[170:173], v[196:199], v[92:95]
	v_mfma_f32_16x16x32_bf16 v[88:91], v[180:183], v[196:199], v[88:91]
	v_mfma_f32_16x16x32_bf16 v[76:79], v[170:173], v[204:207], v[76:79]
	v_mfma_f32_16x16x32_bf16 v[72:75], v[180:183], v[204:207], v[72:75]
	v_mfma_f32_16x16x32_bf16 v[68:71], v[170:173], v[212:215], v[68:71]
	v_mfma_f32_16x16x32_bf16 v[64:67], v[180:183], v[212:215], v[64:67]
	v_mfma_f32_16x16x32_bf16 v[108:111], v[176:179], v[192:195], v[108:111]
	v_mfma_f32_16x16x32_bf16 v[104:107], v[184:187], v[192:195], v[104:107]
	v_mfma_f32_16x16x32_bf16 v[92:95], v[176:179], v[200:203], v[92:95]
	v_mfma_f32_16x16x32_bf16 v[88:91], v[184:187], v[200:203], v[88:91]
	v_mfma_f32_16x16x32_bf16 v[76:79], v[176:179], v[208:211], v[76:79]
	v_mfma_f32_16x16x32_bf16 v[72:75], v[184:187], v[208:211], v[72:75]
	v_mfma_f32_16x16x32_bf16 v[68:71], v[176:179], v[216:219], v[68:71]
	v_mfma_f32_16x16x32_bf16 v[64:67], v[184:187], v[216:219], v[64:67]
	s_barrier
	s_mov_b32 m0, s64
	v_lshl_add_u64 v[220:221], s[60:61], 0, v[134:135]
	s_add_u32 s46, s60, 0xb0000
	ds_read_b128 v[188:191], v145 offset:16384
	ds_read_b128 v[192:195], v145 offset:17408
	ds_read_b128 v[196:199], v145 offset:18432
	ds_read_b128 v[200:203], v145 offset:19456
	ds_read_b128 v[204:207], v145 offset:20480
	ds_read_b128 v[208:211], v145 offset:21504
	ds_read_b128 v[212:215], v145 offset:22528
	ds_read_b128 v[216:219], v145 offset:23552
	global_load_lds_dwordx4 v[220:221], off
	v_lshl_add_u64 v[222:223], s[60:61], 0, v[130:131]
	s_mov_b32 m0, s65
	s_addc_u32 s47, s61, 0
	global_load_lds_dwordx4 v[222:223], off
	v_lshl_add_u64 v[224:225], s[46:47], 0, v[134:135]
	s_mov_b32 m0, s68
	v_lshl_add_u64 v[226:227], s[62:63], 0, v[132:133]
	global_load_lds_dwordx4 v[224:225], off
	v_lshl_add_u64 v[224:225], s[46:47], 0, v[130:131]
	s_mov_b32 m0, s69
	s_nop 0
	global_load_lds_dwordx4 v[224:225], off
	v_lshl_add_u64 v[224:225], s[62:63], 0, v[136:137]
	s_mov_b32 m0, s24
	s_nop 0
	global_load_lds_dwordx4 v[224:225], off
	s_mov_b32 m0, s25
	s_nop 0
	global_load_lds_dwordx4 v[226:227], off
	s_waitcnt vmcnt(8)
	s_waitcnt lgkmcnt(0)
	s_barrier
; #define PG8_STAGE(bufoff, gbase, voff) do { _Pragma("unroll") for (int _i = 0; _i < 2; ++_i) \
;         __builtin_amdgcn_global_load_lds((const unsigned*)((const char*)(gbase) + (voff)[_i]), (LAS unsigned*)(lds + (bufoff) + ldsw + _i * 8192), 16, 0, 0); } while (0)
; #define PG8_LDA(dst, b, h) do { _Pragma("unroll") for (int m = 0; m < 4; ++m) _Pragma("unroll") for (int k = 0; k < 2; ++k) dst[m][k] = *(const LAS bf16x8*)(lds + PG8_SA(b, h) + aoff + m * 2048 + k * 1024); } while (0)
; #define PG8_LDB(dst, b, h) do { _Pragma("unroll") for (int n = 0; n < 2; ++n) _Pragma("unroll") for (int k = 0; k < 2; ++k) dst[n][k] = *(const LAS bf16x8*)(lds + PG8_SB(b, h) + boff + n * 2048 + k * 1024); } while (0)
; #define PG8_MMA(ai, bj, At, Bt) do { __builtin_amdgcn_s_setprio(1); _Pragma("unroll") for (int m = 0; m < 4; ++m) _Pragma("unroll") for (int n = 0; n < 2; ++n) _Pragma("unroll") for (int k = 0; k < 2; ++k) \
;         acc[ai][bj][m][n] = __builtin_amdgcn_mfma_f32_16x16x32_bf16(Bt[n][k], At[m][k], acc[ai][bj][m][n], 0, 0, 0); __builtin_amdgcn_s_setprio(0); } while (0)
; #define PG8_WAIT_V(n) asm volatile("s_waitcnt vmcnt(" #n ")" ::: "memory")
; #define PG8_WAIT_L(n) asm volatile("s_waitcnt lgkmcnt(" #n ")" ::: "memory")
; #define PG8_BAR __builtin_amdgcn_s_barrier()
; #define PG8_SCHED __builtin_amdgcn_sched_barrier(0)
; template <class Epi, class Sched, bool ALIGN_EPI = true, bool SP2 = true>
; __device__ __forceinline__ void gemm_phase(LAS unsigned char* lds, const Gemm g, const Sched& S, const Epi& E) {
;     ...
;             PG8_WAIT_V(8); PG8_WAIT_L(0); PG8_BAR; PG8_MMA(1, 0, At, B0); PG8_MMA(1, 1, At, B1); PG8_BAR; PG8_SCHED;
;             PG8_LDB(B0, 1, 0); PG8_LDB(B1, 1, 1); PG8_SCHED; PG8_LDA(At, 1, 0); PG8_STAGE(PG8_SA(0, 1), a2 + hstep, voffA);
;             PG8_WAIT_V(8); PG8_WAIT_L(0); PG8_BAR; PG8_MMA(0, 0, At, B0); PG8_MMA(0, 1, At, B1); PG8_BAR; PG8_SCHED;
	s_waitcnt lgkmcnt(0)
	v_mfma_f32_16x16x32_bf16 v[60:63], v[148:151], v[188:191], v[60:63]
	v_mfma_f32_16x16x32_bf16 v[56:59], v[156:159], v[188:191], v[56:59]
	v_mfma_f32_16x16x32_bf16 v[52:55], v[148:151], v[196:199], v[52:55]
	v_mfma_f32_16x16x32_bf16 v[48:51], v[156:159], v[196:199], v[48:51]
	v_mfma_f32_16x16x32_bf16 v[36:39], v[148:151], v[204:207], v[36:39]
	v_mfma_f32_16x16x32_bf16 v[32:35], v[156:159], v[204:207], v[32:35]
	v_mfma_f32_16x16x32_bf16 v[20:23], v[148:151], v[212:215], v[20:23]
	v_mfma_f32_16x16x32_bf16 v[16:19], v[156:159], v[212:215], v[16:19]
	v_mfma_f32_16x16x32_bf16 v[60:63], v[152:155], v[192:195], v[60:63]
	v_mfma_f32_16x16x32_bf16 v[56:59], v[166:169], v[192:195], v[56:59]
	v_mfma_f32_16x16x32_bf16 v[52:55], v[152:155], v[200:203], v[52:55]
	v_mfma_f32_16x16x32_bf16 v[48:51], v[166:169], v[200:203], v[48:51]
	v_mfma_f32_16x16x32_bf16 v[36:39], v[152:155], v[208:211], v[36:39]
	v_mfma_f32_16x16x32_bf16 v[32:35], v[166:169], v[208:211], v[32:35]
	v_mfma_f32_16x16x32_bf16 v[20:23], v[152:155], v[216:219], v[20:23]
	v_mfma_f32_16x16x32_bf16 v[16:19], v[166:169], v[216:219], v[16:19]
	v_mfma_f32_16x16x32_bf16 v[44:47], v[170:173], v[188:191], v[44:47]
	v_mfma_f32_16x16x32_bf16 v[40:43], v[180:183], v[188:191], v[40:43]
	v_mfma_f32_16x16x32_bf16 v[28:31], v[170:173], v[196:199], v[28:31]
	v_mfma_f32_16x16x32_bf16 v[24:27], v[180:183], v[196:199], v[24:27]
	v_mfma_f32_16x16x32_bf16 v[12:15], v[170:173], v[204:207], v[12:15]
	v_mfma_f32_16x16x32_bf16 v[8:11], v[180:183], v[204:207], v[8:11]
	v_mfma_f32_16x16x32_bf16 v[4:7], v[170:173], v[212:215], v[4:7]
	v_mfma_f32_16x16x32_bf16 v[0:3], v[180:183], v[212:215], v[0:3]
	v_mfma_f32_16x16x32_bf16 v[44:47], v[176:179], v[192:195], v[44:47]
	v_mfma_f32_16x16x32_bf16 v[40:43], v[184:187], v[192:195], v[40:43]
	v_mfma_f32_16x16x32_bf16 v[28:31], v[176:179], v[200:203], v[28:31]
	v_mfma_f32_16x16x32_bf16 v[24:27], v[184:187], v[200:203], v[24:27]
	v_mfma_f32_16x16x32_bf16 v[12:15], v[176:179], v[208:211], v[12:15]
	v_mfma_f32_16x16x32_bf16 v[8:11], v[184:187], v[208:211], v[8:11]
	v_mfma_f32_16x16x32_bf16 v[4:7], v[176:179], v[216:219], v[4:7]
	v_mfma_f32_16x16x32_bf16 v[0:3], v[184:187], v[216:219], v[0:3]
	s_barrier
	ds_read_b128 v[148:151], v146
	ds_read_b128 v[152:155], v146 offset:1024
	ds_read_b128 v[156:159], v146 offset:2048
	ds_read_b128 v[166:169], v146 offset:3072
	ds_read_b128 v[170:173], v147
	ds_read_b128 v[176:179], v147 offset:1024
	ds_read_b128 v[180:183], v147 offset:2048
	ds_read_b128 v[184:187], v147 offset:3072
	s_add_u32 s46, s62, 0xb0000
	s_addc_u32 s47, s63, 0
	s_mov_b32 m0, s34
	v_lshl_add_u64 v[228:229], s[46:47], 0, v[136:137]
	ds_read_b128 v[188:191], v145 offset:32768
	ds_read_b128 v[192:195], v145 offset:33792
	ds_read_b128 v[196:199], v145 offset:34816
	ds_read_b128 v[200:203], v145 offset:35840
	ds_read_b128 v[204:207], v145 offset:36864
	ds_read_b128 v[208:211], v145 offset:37888
	ds_read_b128 v[212:215], v145 offset:38912
	ds_read_b128 v[216:219], v145 offset:39936
	global_load_lds_dwordx4 v[228:229], off
	v_lshl_add_u64 v[228:229], s[46:47], 0, v[132:133]
	s_mov_b32 m0, s35
	s_nop 0
	global_load_lds_dwordx4 v[228:229], off
	s_waitcnt vmcnt(8)
	s_waitcnt lgkmcnt(0)
	s_barrier
	s_waitcnt lgkmcnt(0)
	v_mfma_f32_16x16x32_bf16 v[124:127], v[148:151], v[188:191], v[124:127]
	v_mfma_f32_16x16x32_bf16 v[120:123], v[156:159], v[188:191], v[120:123]
	v_mfma_f32_16x16x32_bf16 v[116:119], v[148:151], v[196:199], v[116:119]
	v_mfma_f32_16x16x32_bf16 v[112:115], v[156:159], v[196:199], v[112:115]
	v_mfma_f32_16x16x32_bf16 v[100:103], v[148:151], v[204:207], v[100:103]
	v_mfma_f32_16x16x32_bf16 v[96:99], v[156:159], v[204:207], v[96:99]
	v_mfma_f32_16x16x32_bf16 v[84:87], v[148:151], v[212:215], v[84:87]
	v_mfma_f32_16x16x32_bf16 v[80:83], v[156:159], v[212:215], v[80:83]
	v_mfma_f32_16x16x32_bf16 v[124:127], v[152:155], v[192:195], v[124:127]
	v_mfma_f32_16x16x32_bf16 v[120:123], v[166:169], v[192:195], v[120:123]
	v_mfma_f32_16x16x32_bf16 v[116:119], v[152:155], v[200:203], v[116:119]
	v_mfma_f32_16x16x32_bf16 v[112:115], v[166:169], v[200:203], v[112:115]
	v_mfma_f32_16x16x32_bf16 v[100:103], v[152:155], v[208:211], v[100:103]
	v_mfma_f32_16x16x32_bf16 v[96:99], v[166:169], v[208:211], v[96:99]
	v_mfma_f32_16x16x32_bf16 v[84:87], v[152:155], v[216:219], v[84:87]
	v_mfma_f32_16x16x32_bf16 v[80:83], v[166:169], v[216:219], v[80:83]
	v_mfma_f32_16x16x32_bf16 v[108:111], v[170:173], v[188:191], v[108:111]
	v_mfma_f32_16x16x32_bf16 v[104:107], v[180:183], v[188:191], v[104:107]
	v_mfma_f32_16x16x32_bf16 v[92:95], v[170:173], v[196:199], v[92:95]
	v_mfma_f32_16x16x32_bf16 v[88:91], v[180:183], v[196:199], v[88:91]
	v_mfma_f32_16x16x32_bf16 v[76:79], v[170:173], v[204:207], v[76:79]
	v_mfma_f32_16x16x32_bf16 v[72:75], v[180:183], v[204:207], v[72:75]
	v_mfma_f32_16x16x32_bf16 v[68:71], v[170:173], v[212:215], v[68:71]
	v_mfma_f32_16x16x32_bf16 v[64:67], v[180:183], v[212:215], v[64:67]
	v_mfma_f32_16x16x32_bf16 v[108:111], v[176:179], v[192:195], v[108:111]
	v_mfma_f32_16x16x32_bf16 v[104:107], v[184:187], v[192:195], v[104:107]
	v_mfma_f32_16x16x32_bf16 v[92:95], v[176:179], v[200:203], v[92:95]
	v_mfma_f32_16x16x32_bf16 v[88:91], v[184:187], v[200:203], v[88:91]
	v_mfma_f32_16x16x32_bf16 v[76:79], v[176:179], v[208:211], v[76:79]
	v_mfma_f32_16x16x32_bf16 v[72:75], v[184:187], v[208:211], v[72:75]
	v_mfma_f32_16x16x32_bf16 v[68:71], v[176:179], v[216:219], v[68:71]
	v_mfma_f32_16x16x32_bf16 v[64:67], v[184:187], v[216:219], v[64:67]
	s_barrier
; #define PG8_STAGE(bufoff, gbase, voff) do { _Pragma("unroll") for (int _i = 0; _i < 2; ++_i) \
;         __builtin_amdgcn_global_load_lds((const unsigned*)((const char*)(gbase) + (voff)[_i]), (LAS unsigned*)(lds + (bufoff) + ldsw + _i * 8192), 16, 0, 0); } while (0)
; #define PG8_LDA(dst, b, h) do { _Pragma("unroll") for (int m = 0; m < 4; ++m) _Pragma("unroll") for (int k = 0; k < 2; ++k) dst[m][k] = *(const LAS bf16x8*)(lds + PG8_SA(b, h) + aoff + m * 2048 + k * 1024); } while (0)
; #define PG8_MMA(ai, bj, At, Bt) do { __builtin_amdgcn_s_setprio(1); _Pragma("unroll") for (int m = 0; m < 4; ++m) _Pragma("unroll") for (int n = 0; n < 2; ++n) _Pragma("unroll") for (int k = 0; k < 2; ++k) \
;         acc[ai][bj][m][n] = __builtin_amdgcn_mfma_f32_16x16x32_bf16(Bt[n][k], At[m][k], acc[ai][bj][m][n], 0, 0, 0); __builtin_amdgcn_s_setprio(0); } while (0)
; #define PG8_WAIT_V(n) asm volatile("s_waitcnt vmcnt(" #n ")" ::: "memory")
; #define PG8_WAIT_L(n) asm volatile("s_waitcnt lgkmcnt(" #n ")" ::: "memory")
; #define PG8_BAR __builtin_amdgcn_s_barrier()
; #define PG8_SCHED __builtin_amdgcn_sched_barrier(0)
; template <class Epi, class Sched, bool ALIGN_EPI = true, bool SP2 = true>
; __device__ __forceinline__ void gemm_phase(LAS unsigned char* lds, const Gemm g, const Sched& S, const Epi& E) {
;     ...
;             PG8_LDA(At, 1, 1); PG8_STAGE(PG8_SB(1, 0), b3, voffB); PG8_STAGE(PG8_SB(1, 1), b3 + hstep, voffB); PG8_STAGE(PG8_SA(1, 0), a3, voffA);
;             PG8_WAIT_V(8); PG8_WAIT_L(0); PG8_BAR; PG8_MMA(1, 0, At, B0); PG8_MMA(1, 1, At, B1); PG8_BAR; PG8_SCHED;
;     ...
;         if constexpr (ALIGN_EPI) { if (wr == 0) PG8_BAR; }
	s_mov_b32 m0, s70
	v_lshl_add_u64 v[220:221], v[220:221], 0, s[10:11]
	s_add_u32 s46, s60, 0xb0080
	ds_read_b128 v[188:191], v145 offset:49152
	ds_read_b128 v[192:195], v145 offset:50176
	ds_read_b128 v[196:199], v145 offset:51200
	ds_read_b128 v[200:203], v145 offset:52224
	ds_read_b128 v[204:207], v145 offset:53248
	ds_read_b128 v[208:211], v145 offset:54272
	ds_read_b128 v[212:215], v145 offset:55296
	ds_read_b128 v[216:219], v145 offset:56320
	global_load_lds_dwordx4 v[220:221], off
	v_lshl_add_u64 v[220:221], v[222:223], 0, s[10:11]
	s_mov_b32 m0, s71
	s_addc_u32 s47, s61, 0
	global_load_lds_dwordx4 v[220:221], off
	v_lshl_add_u64 v[220:221], s[46:47], 0, v[134:135]
	s_mov_b32 m0, s72
	s_nop 0
	global_load_lds_dwordx4 v[220:221], off
	v_lshl_add_u64 v[220:221], s[46:47], 0, v[130:131]
	s_mov_b32 m0, s73
	s_nop 0
	global_load_lds_dwordx4 v[220:221], off
	v_lshl_add_u64 v[220:221], v[224:225], 0, s[10:11]
	s_mov_b32 m0, s39
	s_nop 0
	global_load_lds_dwordx4 v[220:221], off
	v_lshl_add_u64 v[220:221], v[226:227], 0, s[10:11]
	s_mov_b32 m0, s42
	s_nop 0
	global_load_lds_dwordx4 v[220:221], off
	s_waitcnt vmcnt(8)
	s_waitcnt lgkmcnt(0)
	s_barrier
	s_waitcnt lgkmcnt(0)
	v_mfma_f32_16x16x32_bf16 v[60:63], v[148:151], v[188:191], v[60:63]
	v_mfma_f32_16x16x32_bf16 v[56:59], v[156:159], v[188:191], v[56:59]
	v_mfma_f32_16x16x32_bf16 v[52:55], v[148:151], v[196:199], v[52:55]
	v_mfma_f32_16x16x32_bf16 v[48:51], v[156:159], v[196:199], v[48:51]
	v_mfma_f32_16x16x32_bf16 v[36:39], v[148:151], v[204:207], v[36:39]
	v_mfma_f32_16x16x32_bf16 v[32:35], v[156:159], v[204:207], v[32:35]
	v_mfma_f32_16x16x32_bf16 v[20:23], v[148:151], v[212:215], v[20:23]
	v_mfma_f32_16x16x32_bf16 v[16:19], v[156:159], v[212:215], v[16:19]
	v_mfma_f32_16x16x32_bf16 v[60:63], v[152:155], v[192:195], v[60:63]
	v_mfma_f32_16x16x32_bf16 v[56:59], v[166:169], v[192:195], v[56:59]
	v_mfma_f32_16x16x32_bf16 v[52:55], v[152:155], v[200:203], v[52:55]
	v_mfma_f32_16x16x32_bf16 v[48:51], v[166:169], v[200:203], v[48:51]
	v_mfma_f32_16x16x32_bf16 v[36:39], v[152:155], v[208:211], v[36:39]
	v_mfma_f32_16x16x32_bf16 v[32:35], v[166:169], v[208:211], v[32:35]
	v_mfma_f32_16x16x32_bf16 v[20:23], v[152:155], v[216:219], v[20:23]
	v_mfma_f32_16x16x32_bf16 v[16:19], v[166:169], v[216:219], v[16:19]
	v_mfma_f32_16x16x32_bf16 v[44:47], v[170:173], v[188:191], v[44:47]
	v_mfma_f32_16x16x32_bf16 v[40:43], v[180:183], v[188:191], v[40:43]
	v_mfma_f32_16x16x32_bf16 v[28:31], v[170:173], v[196:199], v[28:31]
	v_mfma_f32_16x16x32_bf16 v[24:27], v[180:183], v[196:199], v[24:27]
	v_mfma_f32_16x16x32_bf16 v[12:15], v[170:173], v[204:207], v[12:15]
	v_mfma_f32_16x16x32_bf16 v[8:11], v[180:183], v[204:207], v[8:11]
	v_mfma_f32_16x16x32_bf16 v[4:7], v[170:173], v[212:215], v[4:7]
	v_mfma_f32_16x16x32_bf16 v[0:3], v[180:183], v[212:215], v[0:3]
	v_mfma_f32_16x16x32_bf16 v[44:47], v[176:179], v[192:195], v[44:47]
	v_mfma_f32_16x16x32_bf16 v[40:43], v[184:187], v[192:195], v[40:43]
	v_mfma_f32_16x16x32_bf16 v[28:31], v[176:179], v[200:203], v[28:31]
	v_mfma_f32_16x16x32_bf16 v[24:27], v[184:187], v[200:203], v[24:27]
	v_mfma_f32_16x16x32_bf16 v[12:15], v[176:179], v[208:211], v[12:15]
	v_mfma_f32_16x16x32_bf16 v[8:11], v[184:187], v[208:211], v[8:11]
	v_mfma_f32_16x16x32_bf16 v[4:7], v[176:179], v[216:219], v[4:7]
	v_mfma_f32_16x16x32_bf16 v[0:3], v[184:187], v[216:219], v[0:3]
	s_barrier
	s_add_i32 s45, s45, 2
	s_add_u32 s14, s14, 0x100
	s_addc_u32 s15, s15, 0
	s_cmp_gt_u32 s45, 41
	s_cbranch_scc0 .LBB0_285
	s_cmpk_lt_u32 s23, 0x100
	s_cbranch_scc0 .LBB0_288
	s_barrier

; #define PG8_STAGE(bufoff, gbase, voff) do { _Pragma("unroll") for (int _i = 0; _i < 2; ++_i) \
;         __builtin_amdgcn_global_load_lds((const unsigned*)((const char*)(gbase) + (voff)[_i]), (LAS unsigned*)(lds + (bufoff) + ldsw + _i * 8192), 16, 0, 0); } while (0)
; #define PG8_LDA(dst, b, h) do { _Pragma("unroll") for (int m = 0; m < 4; ++m) _Pragma("unroll") for (int k = 0; k < 2; ++k) dst[m][k] = *(const LAS bf16x8*)(lds + PG8_SA(b, h) + aoff + m * 2048 + k * 1024); } while (0)
; #define PG8_LDB(dst, b, h) do { _Pragma("unroll") for (int n = 0; n < 2; ++n) _Pragma("unroll") for (int k = 0; k < 2; ++k) dst[n][k] = *(const LAS bf16x8*)(lds + PG8_SB(b, h) + boff + n * 2048 + k * 1024); } while (0)
; #define PG8_MMA(ai, bj, At, Bt) do { __builtin_amdgcn_s_setprio(1); _Pragma("unroll") for (int m = 0; m < 4; ++m) _Pragma("unroll") for (int n = 0; n < 2; ++n) _Pragma("unroll") for (int k = 0; k < 2; ++k) \
;         acc[ai][bj][m][n] = __builtin_amdgcn_mfma_f32_16x16x32_bf16(Bt[n][k], At[m][k], acc[ai][bj][m][n], 0, 0, 0); __builtin_amdgcn_s_setprio(0); } while (0)
; #define PG8_WAIT_V(n) asm volatile("s_waitcnt vmcnt(" #n ")" ::: "memory")
; #define PG8_WAIT_L(n) asm volatile("s_waitcnt lgkmcnt(" #n ")" ::: "memory")
; #define PG8_BAR __builtin_amdgcn_s_barrier()
; #define PG8_SCHED __builtin_amdgcn_sched_barrier(0)
; template <class Epi, class Sched, bool ALIGN_EPI = true, bool SP2 = true>
; __device__ __forceinline__ void gemm_phase(LAS unsigned char* lds, const Gemm g, const Sched& S, const Epi& E) {
;     ...
;             PG8_LDB(B0, 0, 0); PG8_LDB(B1, 0, 1); PG8_SCHED; PG8_LDA(At, 0, 0); PG8_STAGE(PG8_SA(1, 1), a1 + hstep, voffA);
;             PG8_WAIT_V(8); PG8_WAIT_L(0); PG8_BAR; PG8_MMA(0, 0, At, B0); PG8_MMA(0, 1, At, B1); PG8_BAR; PG8_SCHED;
;             PG8_LDA(At, 0, 1); PG8_STAGE(PG8_SB(0, 0), b2, voffB); PG8_STAGE(PG8_SB(0, 1), b2 + hstep, voffB); PG8_STAGE(PG8_SA(0, 0), a2, voffA);
;             PG8_WAIT_V(8); PG8_WAIT_L(0); PG8_BAR; PG8_MMA(1, 0, At, B0); PG8_MMA(1, 1, At, B1); PG8_BAR; PG8_SCHED;
.LBB0_364:
	ds_read_b128 v[150:153], v147
	ds_read_b128 v[154:157], v147 offset:1024
	ds_read_b128 v[166:169], v147 offset:2048
	ds_read_b128 v[170:173], v147 offset:3072
	ds_read_b128 v[176:179], v148
	ds_read_b128 v[180:183], v148 offset:1024
	ds_read_b128 v[184:187], v148 offset:2048
	ds_read_b128 v[188:191], v148 offset:3072
	s_add_u32 s64, s62, 0x100
	s_addc_u32 s65, s63, 0
	s_cmp_eq_u32 s73, 40
	s_cselect_b32 s71, s5, s65
	s_cselect_b32 s70, s4, s64
	s_cselect_b32 s69, s41, s72
	s_cselect_b32 s68, s40, s61
	v_lshl_add_u64 v[158:159], s[62:63], 0, v[136:137]
	s_add_i32 m0, s19, 0xc000
	ds_read_b128 v[192:195], v149
	ds_read_b128 v[196:199], v149 offset:1024
	ds_read_b128 v[200:203], v149 offset:2048
	ds_read_b128 v[204:207], v149 offset:3072
	ds_read_b128 v[208:211], v149 offset:4096
	ds_read_b128 v[212:215], v149 offset:5120
	ds_read_b128 v[216:219], v149 offset:6144
	ds_read_b128 v[220:223], v149 offset:7168
	global_load_lds_dwordx4 v[158:159], off
	v_lshl_add_u64 v[158:159], s[62:63], 0, v[138:139]
	s_add_i32 m0, s19, 0xe000
	s_nop 0
	global_load_lds_dwordx4 v[158:159], off
	s_waitcnt vmcnt(8)
	s_waitcnt lgkmcnt(0)
	s_barrier
	s_waitcnt lgkmcnt(0)
	v_mfma_f32_16x16x32_bf16 v[124:127], v[150:153], v[192:195], v[124:127]
	v_mfma_f32_16x16x32_bf16 v[120:123], v[166:169], v[192:195], v[120:123]
	v_mfma_f32_16x16x32_bf16 v[116:119], v[150:153], v[200:203], v[116:119]
	v_mfma_f32_16x16x32_bf16 v[112:115], v[166:169], v[200:203], v[112:115]
	v_mfma_f32_16x16x32_bf16 v[100:103], v[150:153], v[208:211], v[100:103]
	v_mfma_f32_16x16x32_bf16 v[96:99], v[166:169], v[208:211], v[96:99]
	v_mfma_f32_16x16x32_bf16 v[84:87], v[150:153], v[216:219], v[84:87]
	v_mfma_f32_16x16x32_bf16 v[80:83], v[166:169], v[216:219], v[80:83]
	v_mfma_f32_16x16x32_bf16 v[124:127], v[154:157], v[196:199], v[124:127]
	v_mfma_f32_16x16x32_bf16 v[120:123], v[170:173], v[196:199], v[120:123]
	v_mfma_f32_16x16x32_bf16 v[116:119], v[154:157], v[204:207], v[116:119]
	v_mfma_f32_16x16x32_bf16 v[112:115], v[170:173], v[204:207], v[112:115]
	v_mfma_f32_16x16x32_bf16 v[100:103], v[154:157], v[212:215], v[100:103]
	v_mfma_f32_16x16x32_bf16 v[96:99], v[170:173], v[212:215], v[96:99]
	v_mfma_f32_16x16x32_bf16 v[84:87], v[154:157], v[220:223], v[84:87]
	v_mfma_f32_16x16x32_bf16 v[80:83], v[170:173], v[220:223], v[80:83]
	v_mfma_f32_16x16x32_bf16 v[108:111], v[176:179], v[192:195], v[108:111]
	v_mfma_f32_16x16x32_bf16 v[104:107], v[184:187], v[192:195], v[104:107]
	v_mfma_f32_16x16x32_bf16 v[92:95], v[176:179], v[200:203], v[92:95]
	v_mfma_f32_16x16x32_bf16 v[88:91], v[184:187], v[200:203], v[88:91]
	v_mfma_f32_16x16x32_bf16 v[76:79], v[176:179], v[208:211], v[76:79]
	v_mfma_f32_16x16x32_bf16 v[72:75], v[184:187], v[208:211], v[72:75]
	v_mfma_f32_16x16x32_bf16 v[68:71], v[176:179], v[216:219], v[68:71]
	v_mfma_f32_16x16x32_bf16 v[64:67], v[184:187], v[216:219], v[64:67]
	v_mfma_f32_16x16x32_bf16 v[108:111], v[180:183], v[196:199], v[108:111]
	v_mfma_f32_16x16x32_bf16 v[104:107], v[188:191], v[196:199], v[104:107]
	v_mfma_f32_16x16x32_bf16 v[92:95], v[180:183], v[204:207], v[92:95]
	v_mfma_f32_16x16x32_bf16 v[88:91], v[188:191], v[204:207], v[88:91]
	v_mfma_f32_16x16x32_bf16 v[76:79], v[180:183], v[212:215], v[76:79]
	v_mfma_f32_16x16x32_bf16 v[72:75], v[188:191], v[212:215], v[72:75]
	v_mfma_f32_16x16x32_bf16 v[68:71], v[180:183], v[220:223], v[68:71]
	v_mfma_f32_16x16x32_bf16 v[64:67], v[188:191], v[220:223], v[64:67]
	s_barrier
	s_add_i32 s17, s44, s18
	v_lshl_add_u64 v[158:159], s[68:69], 0, v[130:131]
	s_mov_b32 m0, s17
	ds_read_b128 v[192:195], v149 offset:16384
	ds_read_b128 v[196:199], v149 offset:17408
	ds_read_b128 v[200:203], v149 offset:18432
	ds_read_b128 v[204:207], v149 offset:19456
	ds_read_b128 v[208:211], v149 offset:20480
	ds_read_b128 v[212:215], v149 offset:21504
	ds_read_b128 v[216:219], v149 offset:22528
	ds_read_b128 v[220:223], v149 offset:23552
	global_load_lds_dwordx4 v[158:159], off
	s_add_i32 m0, s17, 0x2000
	s_add_u32 s46, s68, 0xb0000
	v_lshl_add_u64 v[224:225], s[68:69], 0, v[134:135]
	s_addc_u32 s47, s69, 0
	s_add_i32 s17, s45, s18
	global_load_lds_dwordx4 v[224:225], off
	v_lshl_add_u64 v[226:227], s[46:47], 0, v[130:131]
	s_mov_b32 m0, s17
	v_lshl_add_u64 v[228:229], s[70:71], 0, v[132:133]
	global_load_lds_dwordx4 v[226:227], off
	v_lshl_add_u64 v[226:227], s[46:47], 0, v[134:135]
	s_add_i32 m0, s17, 0x2000
	s_nop 0
	global_load_lds_dwordx4 v[226:227], off
	v_lshl_add_u64 v[226:227], s[70:71], 0, v[128:129]
	s_mov_b32 m0, s19
	s_nop 0
	global_load_lds_dwordx4 v[226:227], off
	s_mov_b32 m0, s23
	s_nop 0
	global_load_lds_dwordx4 v[228:229], off
	s_waitcnt vmcnt(8)
	s_waitcnt lgkmcnt(0)
	s_barrier
; #define PG8_STAGE(bufoff, gbase, voff) do { _Pragma("unroll") for (int _i = 0; _i < 2; ++_i) \
;         __builtin_amdgcn_global_load_lds((const unsigned*)((const char*)(gbase) + (voff)[_i]), (LAS unsigned*)(lds + (bufoff) + ldsw + _i * 8192), 16, 0, 0); } while (0)
; #define PG8_LDA(dst, b, h) do { _Pragma("unroll") for (int m = 0; m < 4; ++m) _Pragma("unroll") for (int k = 0; k < 2; ++k) dst[m][k] = *(const LAS bf16x8*)(lds + PG8_SA(b, h) + aoff + m * 2048 + k * 1024); } while (0)
; #define PG8_LDB(dst, b, h) do { _Pragma("unroll") for (int n = 0; n < 2; ++n) _Pragma("unroll") for (int k = 0; k < 2; ++k) dst[n][k] = *(const LAS bf16x8*)(lds + PG8_SB(b, h) + boff + n * 2048 + k * 1024); } while (0)
; #define PG8_MMA(ai, bj, At, Bt) do { __builtin_amdgcn_s_setprio(1); _Pragma("unroll") for (int m = 0; m < 4; ++m) _Pragma("unroll") for (int n = 0; n < 2; ++n) _Pragma("unroll") for (int k = 0; k < 2; ++k) \
;         acc[ai][bj][m][n] = __builtin_amdgcn_mfma_f32_16x16x32_bf16(Bt[n][k], At[m][k], acc[ai][bj][m][n], 0, 0, 0); __builtin_amdgcn_s_setprio(0); } while (0)
; #define PG8_WAIT_V(n) asm volatile("s_waitcnt vmcnt(" #n ")" ::: "memory")
; #define PG8_WAIT_L(n) asm volatile("s_waitcnt lgkmcnt(" #n ")" ::: "memory")
; #define PG8_BAR __builtin_amdgcn_s_barrier()
; #define PG8_SCHED __builtin_amdgcn_sched_barrier(0)
; template <class Epi, class Sched, bool ALIGN_EPI = true, bool SP2 = true>
; __device__ __forceinline__ void gemm_phase(LAS unsigned char* lds, const Gemm g, const Sched& S, const Epi& E) {
;     ...
;             PG8_WAIT_V(8); PG8_WAIT_L(0); PG8_BAR; PG8_MMA(1, 0, At, B0); PG8_MMA(1, 1, At, B1); PG8_BAR; PG8_SCHED;
;             PG8_LDB(B0, 1, 0); PG8_LDB(B1, 1, 1); PG8_SCHED; PG8_LDA(At, 1, 0); PG8_STAGE(PG8_SA(0, 1), a2 + hstep, voffA);
;             PG8_WAIT_V(8); PG8_WAIT_L(0); PG8_BAR; PG8_MMA(0, 0, At, B0); PG8_MMA(0, 1, At, B1); PG8_BAR; PG8_SCHED;
	s_waitcnt lgkmcnt(0)
	v_mfma_f32_16x16x32_bf16 v[60:63], v[150:153], v[192:195], v[60:63]
	v_mfma_f32_16x16x32_bf16 v[56:59], v[166:169], v[192:195], v[56:59]
	v_mfma_f32_16x16x32_bf16 v[52:55], v[150:153], v[200:203], v[52:55]
	v_mfma_f32_16x16x32_bf16 v[48:51], v[166:169], v[200:203], v[48:51]
	v_mfma_f32_16x16x32_bf16 v[36:39], v[150:153], v[208:211], v[36:39]
	v_mfma_f32_16x16x32_bf16 v[32:35], v[166:169], v[208:211], v[32:35]
	v_mfma_f32_16x16x32_bf16 v[20:23], v[150:153], v[216:219], v[20:23]
	v_mfma_f32_16x16x32_bf16 v[16:19], v[166:169], v[216:219], v[16:19]
	v_mfma_f32_16x16x32_bf16 v[60:63], v[154:157], v[196:199], v[60:63]
	v_mfma_f32_16x16x32_bf16 v[56:59], v[170:173], v[196:199], v[56:59]
	v_mfma_f32_16x16x32_bf16 v[52:55], v[154:157], v[204:207], v[52:55]
	v_mfma_f32_16x16x32_bf16 v[48:51], v[170:173], v[204:207], v[48:51]
	v_mfma_f32_16x16x32_bf16 v[36:39], v[154:157], v[212:215], v[36:39]
	v_mfma_f32_16x16x32_bf16 v[32:35], v[170:173], v[212:215], v[32:35]
	v_mfma_f32_16x16x32_bf16 v[20:23], v[154:157], v[220:223], v[20:23]
	v_mfma_f32_16x16x32_bf16 v[16:19], v[170:173], v[220:223], v[16:19]
	v_mfma_f32_16x16x32_bf16 v[44:47], v[176:179], v[192:195], v[44:47]
	v_mfma_f32_16x16x32_bf16 v[40:43], v[184:187], v[192:195], v[40:43]
	v_mfma_f32_16x16x32_bf16 v[28:31], v[176:179], v[200:203], v[28:31]
	v_mfma_f32_16x16x32_bf16 v[24:27], v[184:187], v[200:203], v[24:27]
	v_mfma_f32_16x16x32_bf16 v[12:15], v[176:179], v[208:211], v[12:15]
	v_mfma_f32_16x16x32_bf16 v[8:11], v[184:187], v[208:211], v[8:11]
	v_mfma_f32_16x16x32_bf16 v[4:7], v[176:179], v[216:219], v[4:7]
	v_mfma_f32_16x16x32_bf16 v[0:3], v[184:187], v[216:219], v[0:3]
	v_mfma_f32_16x16x32_bf16 v[44:47], v[180:183], v[196:199], v[44:47]
	v_mfma_f32_16x16x32_bf16 v[40:43], v[188:191], v[196:199], v[40:43]
	v_mfma_f32_16x16x32_bf16 v[28:31], v[180:183], v[204:207], v[28:31]
	v_mfma_f32_16x16x32_bf16 v[24:27], v[188:191], v[204:207], v[24:27]
	v_mfma_f32_16x16x32_bf16 v[12:15], v[180:183], v[212:215], v[12:15]
	v_mfma_f32_16x16x32_bf16 v[8:11], v[188:191], v[212:215], v[8:11]
	v_mfma_f32_16x16x32_bf16 v[4:7], v[180:183], v[220:223], v[4:7]
	v_mfma_f32_16x16x32_bf16 v[0:3], v[188:191], v[220:223], v[0:3]
	s_barrier
	s_add_i32 s17, 0, 0x18000
	v_add_u32_e32 v163, s17, v145
	s_add_i32 s62, 0, 0x1c000
	ds_read_b128 v[150:153], v163
	ds_read_b128 v[154:157], v163 offset:1024
	ds_read_b128 v[166:169], v163 offset:2048
	ds_read_b128 v[170:173], v163 offset:3072
	v_add_u32_e32 v163, s62, v145
	ds_read_b128 v[176:179], v163
	ds_read_b128 v[180:183], v163 offset:1024
	ds_read_b128 v[184:187], v163 offset:2048
	ds_read_b128 v[188:191], v163 offset:3072
	s_add_u32 s46, s70, 0xb0000
	s_addc_u32 s47, s71, 0
	s_mov_b32 m0, s24
	v_lshl_add_u64 v[230:231], s[46:47], 0, v[128:129]
	ds_read_b128 v[192:195], v149 offset:32768
	ds_read_b128 v[196:199], v149 offset:33792
	ds_read_b128 v[200:203], v149 offset:34816
	ds_read_b128 v[204:207], v149 offset:35840
	ds_read_b128 v[208:211], v149 offset:36864
	ds_read_b128 v[212:215], v149 offset:37888
	ds_read_b128 v[216:219], v149 offset:38912
	ds_read_b128 v[220:223], v149 offset:39936
	global_load_lds_dwordx4 v[230:231], off
	v_lshl_add_u64 v[230:231], s[46:47], 0, v[132:133]
	s_mov_b32 m0, s25
	s_nop 0
	global_load_lds_dwordx4 v[230:231], off
	s_waitcnt vmcnt(8)
	s_waitcnt lgkmcnt(0)
	s_barrier
	s_waitcnt lgkmcnt(0)
	v_mfma_f32_16x16x32_bf16 v[124:127], v[150:153], v[192:195], v[124:127]
	v_mfma_f32_16x16x32_bf16 v[120:123], v[166:169], v[192:195], v[120:123]
	v_mfma_f32_16x16x32_bf16 v[116:119], v[150:153], v[200:203], v[116:119]
	v_mfma_f32_16x16x32_bf16 v[112:115], v[166:169], v[200:203], v[112:115]
	v_mfma_f32_16x16x32_bf16 v[100:103], v[150:153], v[208:211], v[100:103]
	v_mfma_f32_16x16x32_bf16 v[96:99], v[166:169], v[208:211], v[96:99]
	v_mfma_f32_16x16x32_bf16 v[84:87], v[150:153], v[216:219], v[84:87]
	v_mfma_f32_16x16x32_bf16 v[80:83], v[166:169], v[216:219], v[80:83]
	v_mfma_f32_16x16x32_bf16 v[124:127], v[154:157], v[196:199], v[124:127]
	v_mfma_f32_16x16x32_bf16 v[120:123], v[170:173], v[196:199], v[120:123]
	v_mfma_f32_16x16x32_bf16 v[116:119], v[154:157], v[204:207], v[116:119]
	v_mfma_f32_16x16x32_bf16 v[112:115], v[170:173], v[204:207], v[112:115]
	v_mfma_f32_16x16x32_bf16 v[100:103], v[154:157], v[212:215], v[100:103]
	v_mfma_f32_16x16x32_bf16 v[96:99], v[170:173], v[212:215], v[96:99]
	v_mfma_f32_16x16x32_bf16 v[84:87], v[154:157], v[220:223], v[84:87]
	v_mfma_f32_16x16x32_bf16 v[80:83], v[170:173], v[220:223], v[80:83]
	v_mfma_f32_16x16x32_bf16 v[108:111], v[176:179], v[192:195], v[108:111]
	v_mfma_f32_16x16x32_bf16 v[104:107], v[184:187], v[192:195], v[104:107]
	v_mfma_f32_16x16x32_bf16 v[92:95], v[176:179], v[200:203], v[92:95]
	v_mfma_f32_16x16x32_bf16 v[88:91], v[184:187], v[200:203], v[88:91]
	v_mfma_f32_16x16x32_bf16 v[76:79], v[176:179], v[208:211], v[76:79]
	v_mfma_f32_16x16x32_bf16 v[72:75], v[184:187], v[208:211], v[72:75]
	v_mfma_f32_16x16x32_bf16 v[68:71], v[176:179], v[216:219], v[68:71]
	v_mfma_f32_16x16x32_bf16 v[64:67], v[184:187], v[216:219], v[64:67]
	v_mfma_f32_16x16x32_bf16 v[108:111], v[180:183], v[196:199], v[108:111]
	v_mfma_f32_16x16x32_bf16 v[104:107], v[188:191], v[196:199], v[104:107]
	v_mfma_f32_16x16x32_bf16 v[92:95], v[180:183], v[204:207], v[92:95]
	v_mfma_f32_16x16x32_bf16 v[88:91], v[188:191], v[204:207], v[88:91]
	v_mfma_f32_16x16x32_bf16 v[76:79], v[180:183], v[212:215], v[76:79]
	v_mfma_f32_16x16x32_bf16 v[72:75], v[188:191], v[212:215], v[72:75]
	v_mfma_f32_16x16x32_bf16 v[68:71], v[180:183], v[220:223], v[68:71]
	v_mfma_f32_16x16x32_bf16 v[64:67], v[188:191], v[220:223], v[64:67]
	s_barrier
; #define PG8_STAGE(bufoff, gbase, voff) do { _Pragma("unroll") for (int _i = 0; _i < 2; ++_i) \
;         __builtin_amdgcn_global_load_lds((const unsigned*)((const char*)(gbase) + (voff)[_i]), (LAS unsigned*)(lds + (bufoff) + ldsw + _i * 8192), 16, 0, 0); } while (0)
; #define PG8_LDA(dst, b, h) do { _Pragma("unroll") for (int m = 0; m < 4; ++m) _Pragma("unroll") for (int k = 0; k < 2; ++k) dst[m][k] = *(const LAS bf16x8*)(lds + PG8_SA(b, h) + aoff + m * 2048 + k * 1024); } while (0)
; #define PG8_MMA(ai, bj, At, Bt) do { __builtin_amdgcn_s_setprio(1); _Pragma("unroll") for (int m = 0; m < 4; ++m) _Pragma("unroll") for (int n = 0; n < 2; ++n) _Pragma("unroll") for (int k = 0; k < 2; ++k) \
;         acc[ai][bj][m][n] = __builtin_amdgcn_mfma_f32_16x16x32_bf16(Bt[n][k], At[m][k], acc[ai][bj][m][n], 0, 0, 0); __builtin_amdgcn_s_setprio(0); } while (0)
; #define PG8_WAIT_V(n) asm volatile("s_waitcnt vmcnt(" #n ")" ::: "memory")
; #define PG8_WAIT_L(n) asm volatile("s_waitcnt lgkmcnt(" #n ")" ::: "memory")
; #define PG8_BAR __builtin_amdgcn_s_barrier()
; #define PG8_SCHED __builtin_amdgcn_sched_barrier(0)
; template <class Epi, class Sched, bool ALIGN_EPI = true, bool SP2 = true>
; __device__ __forceinline__ void gemm_phase(LAS unsigned char* lds, const Gemm g, const Sched& S, const Epi& E) {
;     ...
;             PG8_LDA(At, 1, 1); PG8_STAGE(PG8_SB(1, 0), b3, voffB); PG8_STAGE(PG8_SB(1, 1), b3 + hstep, voffB); PG8_STAGE(PG8_SA(1, 0), a3, voffA);
;             PG8_WAIT_V(8); PG8_WAIT_L(0); PG8_BAR; PG8_MMA(1, 0, At, B0); PG8_MMA(1, 1, At, B1); PG8_BAR; PG8_SCHED;
;     ...
;         if constexpr (ALIGN_EPI) { if (wr == 0) PG8_BAR; }
	s_add_i32 s17, s17, s18
	v_lshl_add_u64 v[158:159], v[158:159], 0, s[12:13]
	s_mov_b32 m0, s17
	ds_read_b128 v[192:195], v149 offset:49152
	ds_read_b128 v[196:199], v149 offset:50176
	ds_read_b128 v[200:203], v149 offset:51200
	ds_read_b128 v[204:207], v149 offset:52224
	ds_read_b128 v[208:211], v149 offset:53248
	ds_read_b128 v[212:215], v149 offset:54272
	ds_read_b128 v[216:219], v149 offset:55296
	ds_read_b128 v[220:223], v149 offset:56320
	global_load_lds_dwordx4 v[158:159], off
	s_add_i32 m0, s17, 0x2000
	s_add_u32 s46, s68, 0xb0080
	v_lshl_add_u64 v[158:159], v[224:225], 0, s[12:13]
	s_addc_u32 s47, s69, 0
	s_add_i32 s17, s62, s18
	global_load_lds_dwordx4 v[158:159], off
	v_lshl_add_u64 v[158:159], s[46:47], 0, v[130:131]
	s_mov_b32 m0, s17
	s_nop 0
	global_load_lds_dwordx4 v[158:159], off
	v_lshl_add_u64 v[158:159], s[46:47], 0, v[134:135]
	s_add_i32 m0, s17, 0x2000
	s_nop 0
	global_load_lds_dwordx4 v[158:159], off
	v_lshl_add_u64 v[158:159], v[226:227], 0, s[12:13]
	s_mov_b32 m0, s35
	s_nop 0
	global_load_lds_dwordx4 v[158:159], off
	v_lshl_add_u64 v[158:159], v[228:229], 0, s[12:13]
	s_mov_b32 m0, s38
	s_nop 0
	global_load_lds_dwordx4 v[158:159], off
	s_waitcnt vmcnt(8)
	s_waitcnt lgkmcnt(0)
	s_barrier
	s_waitcnt lgkmcnt(0)
	v_mfma_f32_16x16x32_bf16 v[60:63], v[150:153], v[192:195], v[60:63]
	v_mfma_f32_16x16x32_bf16 v[56:59], v[166:169], v[192:195], v[56:59]
	v_mfma_f32_16x16x32_bf16 v[52:55], v[150:153], v[200:203], v[52:55]
	v_mfma_f32_16x16x32_bf16 v[48:51], v[166:169], v[200:203], v[48:51]
	v_mfma_f32_16x16x32_bf16 v[36:39], v[150:153], v[208:211], v[36:39]
	v_mfma_f32_16x16x32_bf16 v[32:35], v[166:169], v[208:211], v[32:35]
	v_mfma_f32_16x16x32_bf16 v[20:23], v[150:153], v[216:219], v[20:23]
	v_mfma_f32_16x16x32_bf16 v[16:19], v[166:169], v[216:219], v[16:19]
	v_mfma_f32_16x16x32_bf16 v[60:63], v[154:157], v[196:199], v[60:63]
	v_mfma_f32_16x16x32_bf16 v[56:59], v[170:173], v[196:199], v[56:59]
	v_mfma_f32_16x16x32_bf16 v[52:55], v[154:157], v[204:207], v[52:55]
	v_mfma_f32_16x16x32_bf16 v[48:51], v[170:173], v[204:207], v[48:51]
	v_mfma_f32_16x16x32_bf16 v[36:39], v[154:157], v[212:215], v[36:39]
	v_mfma_f32_16x16x32_bf16 v[32:35], v[170:173], v[212:215], v[32:35]
	v_mfma_f32_16x16x32_bf16 v[20:23], v[154:157], v[220:223], v[20:23]
	v_mfma_f32_16x16x32_bf16 v[16:19], v[170:173], v[220:223], v[16:19]
	v_mfma_f32_16x16x32_bf16 v[44:47], v[176:179], v[192:195], v[44:47]
	v_mfma_f32_16x16x32_bf16 v[40:43], v[184:187], v[192:195], v[40:43]
	v_mfma_f32_16x16x32_bf16 v[28:31], v[176:179], v[200:203], v[28:31]
	v_mfma_f32_16x16x32_bf16 v[24:27], v[184:187], v[200:203], v[24:27]
	v_mfma_f32_16x16x32_bf16 v[12:15], v[176:179], v[208:211], v[12:15]
	v_mfma_f32_16x16x32_bf16 v[8:11], v[184:187], v[208:211], v[8:11]
	v_mfma_f32_16x16x32_bf16 v[4:7], v[176:179], v[216:219], v[4:7]
	v_mfma_f32_16x16x32_bf16 v[0:3], v[184:187], v[216:219], v[0:3]
	v_mfma_f32_16x16x32_bf16 v[44:47], v[180:183], v[196:199], v[44:47]
	v_mfma_f32_16x16x32_bf16 v[40:43], v[188:191], v[196:199], v[40:43]
	v_mfma_f32_16x16x32_bf16 v[28:31], v[180:183], v[204:207], v[28:31]
	v_mfma_f32_16x16x32_bf16 v[24:27], v[188:191], v[204:207], v[24:27]
	v_mfma_f32_16x16x32_bf16 v[12:15], v[180:183], v[212:215], v[12:15]
	v_mfma_f32_16x16x32_bf16 v[8:11], v[188:191], v[212:215], v[8:11]
	v_mfma_f32_16x16x32_bf16 v[4:7], v[180:183], v[220:223], v[4:7]
	v_mfma_f32_16x16x32_bf16 v[0:3], v[188:191], v[220:223], v[0:3]
	s_barrier
	s_add_i32 s73, s73, 2
	s_add_u32 s61, s61, 0x100
	s_addc_u32 s72, s72, 0
	s_cmp_gt_u32 s73, 41
	s_mov_b64 s[62:63], s[64:65]
	s_cbranch_scc0 .LBB0_364
	s_and_b64 vcc, exec, s[14:15]
	s_cbranch_vccz .LBB0_367
	s_barrier

; #define PG8_STAGE(bufoff, gbase, voff) do { _Pragma("unroll") for (int _i = 0; _i < 2; ++_i) \
;         __builtin_amdgcn_global_load_lds((const unsigned*)((const char*)(gbase) + (voff)[_i]), (LAS unsigned*)(lds + (bufoff) + ldsw + _i * 8192), 16, 0, 0); } while (0)
; #define PG8_LDA(dst, b, h) do { _Pragma("unroll") for (int m = 0; m < 4; ++m) _Pragma("unroll") for (int k = 0; k < 2; ++k) dst[m][k] = *(const LAS bf16x8*)(lds + PG8_SA(b, h) + aoff + m * 2048 + k * 1024); } while (0)
; #define PG8_LDB(dst, b, h) do { _Pragma("unroll") for (int n = 0; n < 2; ++n) _Pragma("unroll") for (int k = 0; k < 2; ++k) dst[n][k] = *(const LAS bf16x8*)(lds + PG8_SB(b, h) + boff + n * 2048 + k * 1024); } while (0)
; #define PG8_MMA(ai, bj, At, Bt) do { __builtin_amdgcn_s_setprio(1); _Pragma("unroll") for (int m = 0; m < 4; ++m) _Pragma("unroll") for (int n = 0; n < 2; ++n) _Pragma("unroll") for (int k = 0; k < 2; ++k) \
;         acc[ai][bj][m][n] = __builtin_amdgcn_mfma_f32_16x16x32_bf16(Bt[n][k], At[m][k], acc[ai][bj][m][n], 0, 0, 0); __builtin_amdgcn_s_setprio(0); } while (0)
; #define PG8_WAIT_V(n) asm volatile("s_waitcnt vmcnt(" #n ")" ::: "memory")
; #define PG8_WAIT_L(n) asm volatile("s_waitcnt lgkmcnt(" #n ")" ::: "memory")
; #define PG8_BAR __builtin_amdgcn_s_barrier()
; #define PG8_SCHED __builtin_amdgcn_sched_barrier(0)
; template <class Epi, class Sched, bool ALIGN_EPI = true, bool SP2 = true>
; __device__ __forceinline__ void gemm_phase(LAS unsigned char* lds, const Gemm g, const Sched& S, const Epi& E) {
;     ...
;             PG8_LDB(B0, 0, 0); PG8_LDB(B1, 0, 1); PG8_SCHED; PG8_LDA(At, 0, 0); PG8_STAGE(PG8_SA(1, 1), a1 + hstep, voffA);
;             PG8_WAIT_V(8); PG8_WAIT_L(0); PG8_BAR; PG8_MMA(0, 0, At, B0); PG8_MMA(0, 1, At, B1); PG8_BAR; PG8_SCHED;
;             PG8_LDA(At, 0, 1); PG8_STAGE(PG8_SB(0, 0), b2, voffB); PG8_STAGE(PG8_SB(0, 1), b2 + hstep, voffB); PG8_STAGE(PG8_SA(0, 0), a2, voffA);
;             PG8_WAIT_V(8); PG8_WAIT_L(0); PG8_BAR; PG8_MMA(1, 0, At, B0); PG8_MMA(1, 1, At, B1); PG8_BAR; PG8_SCHED;
.LBB0_432:
	ds_read_b128 v[148:151], v143
	ds_read_b128 v[152:155], v143 offset:1024
	ds_read_b128 v[156:159], v143 offset:2048
	ds_read_b128 v[166:169], v143 offset:3072
	ds_read_b128 v[170:173], v144
	ds_read_b128 v[176:179], v144 offset:1024
	ds_read_b128 v[180:183], v144 offset:2048
	ds_read_b128 v[184:187], v144 offset:3072
	s_add_u32 s46, s12, s14
	s_addc_u32 s64, s13, s15
	s_add_u32 s46, s46, 0x7a00100
	s_addc_u32 s64, s64, 0
	s_add_u32 s71, s35, s14
	s_addc_u32 s65, s38, s15
	s_cmpk_eq_i32 s14, 0x700
	s_cselect_b32 s69, s7, s64
	s_cselect_b32 s68, s6, s46
	s_cselect_b32 s65, s5, s65
	s_cselect_b32 s64, s4, s71
	s_mov_b32 m0, s42
	v_lshl_add_u64 v[220:221], v[136:137], 0, s[14:15]
	ds_read_b128 v[188:191], v145
	ds_read_b128 v[192:195], v145 offset:1024
	ds_read_b128 v[196:199], v145 offset:2048
	ds_read_b128 v[200:203], v145 offset:3072
	ds_read_b128 v[204:207], v145 offset:4096
	ds_read_b128 v[208:211], v145 offset:5120
	ds_read_b128 v[212:215], v145 offset:6144
	ds_read_b128 v[216:219], v145 offset:7168
	global_load_lds_dwordx4 v[220:221], off
	v_lshl_add_u64 v[220:221], v[138:139], 0, s[14:15]
	s_mov_b32 m0, s43
	s_nop 0
	global_load_lds_dwordx4 v[220:221], off
	s_waitcnt vmcnt(8)
	s_waitcnt lgkmcnt(0)
	s_barrier
	s_waitcnt lgkmcnt(0)
	v_mfma_f32_16x16x32_bf16 v[124:127], v[148:151], v[188:191], v[124:127]
	v_mfma_f32_16x16x32_bf16 v[120:123], v[156:159], v[188:191], v[120:123]
	v_mfma_f32_16x16x32_bf16 v[108:111], v[148:151], v[196:199], v[108:111]
	v_mfma_f32_16x16x32_bf16 v[104:107], v[156:159], v[196:199], v[104:107]
	v_mfma_f32_16x16x32_bf16 v[92:95], v[148:151], v[204:207], v[92:95]
	v_mfma_f32_16x16x32_bf16 v[88:91], v[156:159], v[204:207], v[88:91]
	v_mfma_f32_16x16x32_bf16 v[76:79], v[148:151], v[212:215], v[76:79]
	v_mfma_f32_16x16x32_bf16 v[72:75], v[156:159], v[212:215], v[72:75]
	v_mfma_f32_16x16x32_bf16 v[124:127], v[152:155], v[192:195], v[124:127]
	v_mfma_f32_16x16x32_bf16 v[120:123], v[166:169], v[192:195], v[120:123]
	v_mfma_f32_16x16x32_bf16 v[108:111], v[152:155], v[200:203], v[108:111]
	v_mfma_f32_16x16x32_bf16 v[104:107], v[166:169], v[200:203], v[104:107]
	v_mfma_f32_16x16x32_bf16 v[92:95], v[152:155], v[208:211], v[92:95]
	v_mfma_f32_16x16x32_bf16 v[88:91], v[166:169], v[208:211], v[88:91]
	v_mfma_f32_16x16x32_bf16 v[76:79], v[152:155], v[216:219], v[76:79]
	v_mfma_f32_16x16x32_bf16 v[72:75], v[166:169], v[216:219], v[72:75]
	v_mfma_f32_16x16x32_bf16 v[116:119], v[170:173], v[188:191], v[116:119]
	v_mfma_f32_16x16x32_bf16 v[112:115], v[180:183], v[188:191], v[112:115]
	v_mfma_f32_16x16x32_bf16 v[100:103], v[170:173], v[196:199], v[100:103]
	v_mfma_f32_16x16x32_bf16 v[96:99], v[180:183], v[196:199], v[96:99]
	v_mfma_f32_16x16x32_bf16 v[84:87], v[170:173], v[204:207], v[84:87]
	v_mfma_f32_16x16x32_bf16 v[80:83], v[180:183], v[204:207], v[80:83]
	v_mfma_f32_16x16x32_bf16 v[68:71], v[170:173], v[212:215], v[68:71]
	v_mfma_f32_16x16x32_bf16 v[64:67], v[180:183], v[212:215], v[64:67]
	v_mfma_f32_16x16x32_bf16 v[116:119], v[176:179], v[192:195], v[116:119]
	v_mfma_f32_16x16x32_bf16 v[112:115], v[184:187], v[192:195], v[112:115]
	v_mfma_f32_16x16x32_bf16 v[100:103], v[176:179], v[200:203], v[100:103]
	v_mfma_f32_16x16x32_bf16 v[96:99], v[184:187], v[200:203], v[96:99]
	v_mfma_f32_16x16x32_bf16 v[84:87], v[176:179], v[208:211], v[84:87]
	v_mfma_f32_16x16x32_bf16 v[80:83], v[184:187], v[208:211], v[80:83]
	v_mfma_f32_16x16x32_bf16 v[68:71], v[176:179], v[216:219], v[68:71]
	v_mfma_f32_16x16x32_bf16 v[64:67], v[184:187], v[216:219], v[64:67]
	s_barrier
	s_mov_b32 m0, s44
	v_lshl_add_u64 v[220:221], s[64:65], 0, v[132:133]
	s_add_u32 s72, s64, 0x40000
	ds_read_b128 v[188:191], v145 offset:16384
	ds_read_b128 v[192:195], v145 offset:17408
	ds_read_b128 v[196:199], v145 offset:18432
	ds_read_b128 v[200:203], v145 offset:19456
	ds_read_b128 v[204:207], v145 offset:20480
	ds_read_b128 v[208:211], v145 offset:21504
	ds_read_b128 v[212:215], v145 offset:22528
	ds_read_b128 v[216:219], v145 offset:23552
	global_load_lds_dwordx4 v[220:221], off
	v_lshl_add_u64 v[222:223], s[64:65], 0, v[128:129]
	s_mov_b32 m0, s45
	s_addc_u32 s73, s65, 0
	global_load_lds_dwordx4 v[222:223], off
	v_lshl_add_u64 v[224:225], s[72:73], 0, v[132:133]
	s_mov_b32 m0, s47
	v_lshl_add_u64 v[226:227], s[68:69], 0, v[130:131]
	global_load_lds_dwordx4 v[224:225], off
	v_lshl_add_u64 v[224:225], s[72:73], 0, v[128:129]
	s_mov_b32 m0, s48
	s_nop 0
	global_load_lds_dwordx4 v[224:225], off
	v_lshl_add_u64 v[224:225], s[68:69], 0, v[134:135]
	s_mov_b32 m0, s1
	s_nop 0
	global_load_lds_dwordx4 v[224:225], off
	s_mov_b32 m0, s18
	s_nop 0
	global_load_lds_dwordx4 v[226:227], off
	s_waitcnt vmcnt(8)
	s_waitcnt lgkmcnt(0)
	s_barrier
; #define PG8_STAGE(bufoff, gbase, voff) do { _Pragma("unroll") for (int _i = 0; _i < 2; ++_i) \
;         __builtin_amdgcn_global_load_lds((const unsigned*)((const char*)(gbase) + (voff)[_i]), (LAS unsigned*)(lds + (bufoff) + ldsw + _i * 8192), 16, 0, 0); } while (0)
; #define PG8_LDA(dst, b, h) do { _Pragma("unroll") for (int m = 0; m < 4; ++m) _Pragma("unroll") for (int k = 0; k < 2; ++k) dst[m][k] = *(const LAS bf16x8*)(lds + PG8_SA(b, h) + aoff + m * 2048 + k * 1024); } while (0)
; #define PG8_LDB(dst, b, h) do { _Pragma("unroll") for (int n = 0; n < 2; ++n) _Pragma("unroll") for (int k = 0; k < 2; ++k) dst[n][k] = *(const LAS bf16x8*)(lds + PG8_SB(b, h) + boff + n * 2048 + k * 1024); } while (0)
; #define PG8_MMA(ai, bj, At, Bt) do { __builtin_amdgcn_s_setprio(1); _Pragma("unroll") for (int m = 0; m < 4; ++m) _Pragma("unroll") for (int n = 0; n < 2; ++n) _Pragma("unroll") for (int k = 0; k < 2; ++k) \
;         acc[ai][bj][m][n] = __builtin_amdgcn_mfma_f32_16x16x32_bf16(Bt[n][k], At[m][k], acc[ai][bj][m][n], 0, 0, 0); __builtin_amdgcn_s_setprio(0); } while (0)
; #define PG8_WAIT_V(n) asm volatile("s_waitcnt vmcnt(" #n ")" ::: "memory")
; #define PG8_WAIT_L(n) asm volatile("s_waitcnt lgkmcnt(" #n ")" ::: "memory")
; #define PG8_BAR __builtin_amdgcn_s_barrier()
; #define PG8_SCHED __builtin_amdgcn_sched_barrier(0)
; template <class Epi, class Sched, bool ALIGN_EPI = true, bool SP2 = true>
; __device__ __forceinline__ void gemm_phase(LAS unsigned char* lds, const Gemm g, const Sched& S, const Epi& E) {
;     ...
;             PG8_WAIT_V(8); PG8_WAIT_L(0); PG8_BAR; PG8_MMA(1, 0, At, B0); PG8_MMA(1, 1, At, B1); PG8_BAR; PG8_SCHED;
;             PG8_LDB(B0, 1, 0); PG8_LDB(B1, 1, 1); PG8_SCHED; PG8_LDA(At, 1, 0); PG8_STAGE(PG8_SA(0, 1), a2 + hstep, voffA);
;             PG8_WAIT_V(8); PG8_WAIT_L(0); PG8_BAR; PG8_MMA(0, 0, At, B0); PG8_MMA(0, 1, At, B1); PG8_BAR; PG8_SCHED;
	s_waitcnt lgkmcnt(0)
	v_mfma_f32_16x16x32_bf16 v[60:63], v[148:151], v[188:191], v[60:63]
	v_mfma_f32_16x16x32_bf16 v[56:59], v[156:159], v[188:191], v[56:59]
	v_mfma_f32_16x16x32_bf16 v[44:47], v[148:151], v[196:199], v[44:47]
	v_mfma_f32_16x16x32_bf16 v[40:43], v[156:159], v[196:199], v[40:43]
	v_mfma_f32_16x16x32_bf16 v[28:31], v[148:151], v[204:207], v[28:31]
	v_mfma_f32_16x16x32_bf16 v[24:27], v[156:159], v[204:207], v[24:27]
	v_mfma_f32_16x16x32_bf16 v[12:15], v[148:151], v[212:215], v[12:15]
	v_mfma_f32_16x16x32_bf16 v[8:11], v[156:159], v[212:215], v[8:11]
	v_mfma_f32_16x16x32_bf16 v[60:63], v[152:155], v[192:195], v[60:63]
	v_mfma_f32_16x16x32_bf16 v[56:59], v[166:169], v[192:195], v[56:59]
	v_mfma_f32_16x16x32_bf16 v[44:47], v[152:155], v[200:203], v[44:47]
	v_mfma_f32_16x16x32_bf16 v[40:43], v[166:169], v[200:203], v[40:43]
	v_mfma_f32_16x16x32_bf16 v[28:31], v[152:155], v[208:211], v[28:31]
	v_mfma_f32_16x16x32_bf16 v[24:27], v[166:169], v[208:211], v[24:27]
	v_mfma_f32_16x16x32_bf16 v[12:15], v[152:155], v[216:219], v[12:15]
	v_mfma_f32_16x16x32_bf16 v[8:11], v[166:169], v[216:219], v[8:11]
	v_mfma_f32_16x16x32_bf16 v[52:55], v[170:173], v[188:191], v[52:55]
	v_mfma_f32_16x16x32_bf16 v[48:51], v[180:183], v[188:191], v[48:51]
	v_mfma_f32_16x16x32_bf16 v[36:39], v[170:173], v[196:199], v[36:39]
	v_mfma_f32_16x16x32_bf16 v[32:35], v[180:183], v[196:199], v[32:35]
	v_mfma_f32_16x16x32_bf16 v[20:23], v[170:173], v[204:207], v[20:23]
	v_mfma_f32_16x16x32_bf16 v[16:19], v[180:183], v[204:207], v[16:19]
	v_mfma_f32_16x16x32_bf16 v[4:7], v[170:173], v[212:215], v[4:7]
	v_mfma_f32_16x16x32_bf16 v[0:3], v[180:183], v[212:215], v[0:3]
	v_mfma_f32_16x16x32_bf16 v[52:55], v[176:179], v[192:195], v[52:55]
	v_mfma_f32_16x16x32_bf16 v[48:51], v[184:187], v[192:195], v[48:51]
	v_mfma_f32_16x16x32_bf16 v[36:39], v[176:179], v[200:203], v[36:39]
	v_mfma_f32_16x16x32_bf16 v[32:35], v[184:187], v[200:203], v[32:35]
	v_mfma_f32_16x16x32_bf16 v[20:23], v[176:179], v[208:211], v[20:23]
	v_mfma_f32_16x16x32_bf16 v[16:19], v[184:187], v[208:211], v[16:19]
	v_mfma_f32_16x16x32_bf16 v[4:7], v[176:179], v[216:219], v[4:7]
	v_mfma_f32_16x16x32_bf16 v[0:3], v[184:187], v[216:219], v[0:3]
	s_barrier
	ds_read_b128 v[148:151], v146
	ds_read_b128 v[152:155], v146 offset:1024
	ds_read_b128 v[156:159], v146 offset:2048
	ds_read_b128 v[166:169], v146 offset:3072
	ds_read_b128 v[170:173], v147
	ds_read_b128 v[176:179], v147 offset:1024
	ds_read_b128 v[180:183], v147 offset:2048
	ds_read_b128 v[184:187], v147 offset:3072
	s_add_u32 s68, s68, 0x40000
	s_addc_u32 s69, s69, 0
	s_mov_b32 m0, s19
	v_lshl_add_u64 v[228:229], s[68:69], 0, v[134:135]
	ds_read_b128 v[188:191], v145 offset:32768
	ds_read_b128 v[192:195], v145 offset:33792
	ds_read_b128 v[196:199], v145 offset:34816
	ds_read_b128 v[200:203], v145 offset:35840
	ds_read_b128 v[204:207], v145 offset:36864
	ds_read_b128 v[208:211], v145 offset:37888
	ds_read_b128 v[212:215], v145 offset:38912
	ds_read_b128 v[216:219], v145 offset:39936
	global_load_lds_dwordx4 v[228:229], off
	v_lshl_add_u64 v[228:229], s[68:69], 0, v[130:131]
	s_mov_b32 m0, s21
	s_nop 0
	global_load_lds_dwordx4 v[228:229], off
	s_waitcnt vmcnt(8)
	s_waitcnt lgkmcnt(0)
	s_barrier
	s_waitcnt lgkmcnt(0)
	v_mfma_f32_16x16x32_bf16 v[124:127], v[148:151], v[188:191], v[124:127]
	v_mfma_f32_16x16x32_bf16 v[120:123], v[156:159], v[188:191], v[120:123]
	v_mfma_f32_16x16x32_bf16 v[108:111], v[148:151], v[196:199], v[108:111]
	v_mfma_f32_16x16x32_bf16 v[104:107], v[156:159], v[196:199], v[104:107]
	v_mfma_f32_16x16x32_bf16 v[92:95], v[148:151], v[204:207], v[92:95]
	v_mfma_f32_16x16x32_bf16 v[88:91], v[156:159], v[204:207], v[88:91]
	v_mfma_f32_16x16x32_bf16 v[76:79], v[148:151], v[212:215], v[76:79]
	v_mfma_f32_16x16x32_bf16 v[72:75], v[156:159], v[212:215], v[72:75]
	v_mfma_f32_16x16x32_bf16 v[124:127], v[152:155], v[192:195], v[124:127]
	v_mfma_f32_16x16x32_bf16 v[120:123], v[166:169], v[192:195], v[120:123]
	v_mfma_f32_16x16x32_bf16 v[108:111], v[152:155], v[200:203], v[108:111]
	v_mfma_f32_16x16x32_bf16 v[104:107], v[166:169], v[200:203], v[104:107]
	v_mfma_f32_16x16x32_bf16 v[92:95], v[152:155], v[208:211], v[92:95]
	v_mfma_f32_16x16x32_bf16 v[88:91], v[166:169], v[208:211], v[88:91]
	v_mfma_f32_16x16x32_bf16 v[76:79], v[152:155], v[216:219], v[76:79]
	v_mfma_f32_16x16x32_bf16 v[72:75], v[166:169], v[216:219], v[72:75]
	v_mfma_f32_16x16x32_bf16 v[116:119], v[170:173], v[188:191], v[116:119]
	v_mfma_f32_16x16x32_bf16 v[112:115], v[180:183], v[188:191], v[112:115]
	v_mfma_f32_16x16x32_bf16 v[100:103], v[170:173], v[196:199], v[100:103]
	v_mfma_f32_16x16x32_bf16 v[96:99], v[180:183], v[196:199], v[96:99]
	v_mfma_f32_16x16x32_bf16 v[84:87], v[170:173], v[204:207], v[84:87]
	v_mfma_f32_16x16x32_bf16 v[80:83], v[180:183], v[204:207], v[80:83]
	v_mfma_f32_16x16x32_bf16 v[68:71], v[170:173], v[212:215], v[68:71]
	v_mfma_f32_16x16x32_bf16 v[64:67], v[180:183], v[212:215], v[64:67]
	v_mfma_f32_16x16x32_bf16 v[116:119], v[176:179], v[192:195], v[116:119]
	v_mfma_f32_16x16x32_bf16 v[112:115], v[184:187], v[192:195], v[112:115]
	v_mfma_f32_16x16x32_bf16 v[100:103], v[176:179], v[200:203], v[100:103]
	v_mfma_f32_16x16x32_bf16 v[96:99], v[184:187], v[200:203], v[96:99]
	v_mfma_f32_16x16x32_bf16 v[84:87], v[176:179], v[208:211], v[84:87]
	v_mfma_f32_16x16x32_bf16 v[80:83], v[184:187], v[208:211], v[80:83]
	v_mfma_f32_16x16x32_bf16 v[68:71], v[176:179], v[216:219], v[68:71]
	v_mfma_f32_16x16x32_bf16 v[64:67], v[184:187], v[216:219], v[64:67]
	s_barrier
; #define PG8_STAGE(bufoff, gbase, voff) do { _Pragma("unroll") for (int _i = 0; _i < 2; ++_i) \
;         __builtin_amdgcn_global_load_lds((const unsigned*)((const char*)(gbase) + (voff)[_i]), (LAS unsigned*)(lds + (bufoff) + ldsw + _i * 8192), 16, 0, 0); } while (0)
; #define PG8_LDA(dst, b, h) do { _Pragma("unroll") for (int m = 0; m < 4; ++m) _Pragma("unroll") for (int k = 0; k < 2; ++k) dst[m][k] = *(const LAS bf16x8*)(lds + PG8_SA(b, h) + aoff + m * 2048 + k * 1024); } while (0)
; #define PG8_MMA(ai, bj, At, Bt) do { __builtin_amdgcn_s_setprio(1); _Pragma("unroll") for (int m = 0; m < 4; ++m) _Pragma("unroll") for (int n = 0; n < 2; ++n) _Pragma("unroll") for (int k = 0; k < 2; ++k) \
;         acc[ai][bj][m][n] = __builtin_amdgcn_mfma_f32_16x16x32_bf16(Bt[n][k], At[m][k], acc[ai][bj][m][n], 0, 0, 0); __builtin_amdgcn_s_setprio(0); } while (0)
; #define PG8_WAIT_V(n) asm volatile("s_waitcnt vmcnt(" #n ")" ::: "memory")
; #define PG8_WAIT_L(n) asm volatile("s_waitcnt lgkmcnt(" #n ")" ::: "memory")
; #define PG8_BAR __builtin_amdgcn_s_barrier()
; #define PG8_SCHED __builtin_amdgcn_sched_barrier(0)
; template <class Epi, class Sched, bool ALIGN_EPI = true, bool SP2 = true>
; __device__ __forceinline__ void gemm_phase(LAS unsigned char* lds, const Gemm g, const Sched& S, const Epi& E) {
;     ...
;             PG8_LDA(At, 1, 1); PG8_STAGE(PG8_SB(1, 0), b3, voffB); PG8_STAGE(PG8_SB(1, 1), b3 + hstep, voffB); PG8_STAGE(PG8_SA(1, 0), a3, voffA);
;             PG8_WAIT_V(8); PG8_WAIT_L(0); PG8_BAR; PG8_MMA(1, 0, At, B0); PG8_MMA(1, 1, At, B1); PG8_BAR; PG8_SCHED;
;     ...
;         if constexpr (ALIGN_EPI) { if (wr == 0) PG8_BAR; }
	s_mov_b32 m0, s49
	v_lshl_add_u64 v[220:221], v[220:221], 0, s[8:9]
	s_add_u32 s64, s64, 0x40080
	ds_read_b128 v[188:191], v145 offset:49152
	ds_read_b128 v[192:195], v145 offset:50176
	ds_read_b128 v[196:199], v145 offset:51200
	ds_read_b128 v[200:203], v145 offset:52224
	ds_read_b128 v[204:207], v145 offset:53248
	ds_read_b128 v[208:211], v145 offset:54272
	ds_read_b128 v[212:215], v145 offset:55296
	ds_read_b128 v[216:219], v145 offset:56320
	global_load_lds_dwordx4 v[220:221], off
	v_lshl_add_u64 v[220:221], v[222:223], 0, s[8:9]
	s_mov_b32 m0, s60
	s_addc_u32 s65, s65, 0
	global_load_lds_dwordx4 v[220:221], off
	v_lshl_add_u64 v[220:221], s[64:65], 0, v[132:133]
	s_mov_b32 m0, s61
	s_nop 0
	global_load_lds_dwordx4 v[220:221], off
	v_lshl_add_u64 v[220:221], s[64:65], 0, v[128:129]
	s_mov_b32 m0, s70
	s_nop 0
	global_load_lds_dwordx4 v[220:221], off
	v_lshl_add_u64 v[220:221], v[224:225], 0, s[8:9]
	s_mov_b32 m0, s25
	s_nop 0
	global_load_lds_dwordx4 v[220:221], off
	v_lshl_add_u64 v[220:221], v[226:227], 0, s[8:9]
	s_mov_b32 m0, s34
	s_nop 0
	global_load_lds_dwordx4 v[220:221], off
	s_waitcnt vmcnt(8)
	s_waitcnt lgkmcnt(0)
	s_barrier
	s_waitcnt lgkmcnt(0)
	v_mfma_f32_16x16x32_bf16 v[60:63], v[148:151], v[188:191], v[60:63]
	v_mfma_f32_16x16x32_bf16 v[56:59], v[156:159], v[188:191], v[56:59]
	v_mfma_f32_16x16x32_bf16 v[44:47], v[148:151], v[196:199], v[44:47]
	v_mfma_f32_16x16x32_bf16 v[40:43], v[156:159], v[196:199], v[40:43]
	v_mfma_f32_16x16x32_bf16 v[28:31], v[148:151], v[204:207], v[28:31]
	v_mfma_f32_16x16x32_bf16 v[24:27], v[156:159], v[204:207], v[24:27]
	v_mfma_f32_16x16x32_bf16 v[12:15], v[148:151], v[212:215], v[12:15]
	v_mfma_f32_16x16x32_bf16 v[8:11], v[156:159], v[212:215], v[8:11]
	v_mfma_f32_16x16x32_bf16 v[60:63], v[152:155], v[192:195], v[60:63]
	v_mfma_f32_16x16x32_bf16 v[56:59], v[166:169], v[192:195], v[56:59]
	v_mfma_f32_16x16x32_bf16 v[44:47], v[152:155], v[200:203], v[44:47]
	v_mfma_f32_16x16x32_bf16 v[40:43], v[166:169], v[200:203], v[40:43]
	v_mfma_f32_16x16x32_bf16 v[28:31], v[152:155], v[208:211], v[28:31]
	v_mfma_f32_16x16x32_bf16 v[24:27], v[166:169], v[208:211], v[24:27]
	v_mfma_f32_16x16x32_bf16 v[12:15], v[152:155], v[216:219], v[12:15]
	v_mfma_f32_16x16x32_bf16 v[8:11], v[166:169], v[216:219], v[8:11]
	v_mfma_f32_16x16x32_bf16 v[52:55], v[170:173], v[188:191], v[52:55]
	v_mfma_f32_16x16x32_bf16 v[48:51], v[180:183], v[188:191], v[48:51]
	v_mfma_f32_16x16x32_bf16 v[36:39], v[170:173], v[196:199], v[36:39]
	v_mfma_f32_16x16x32_bf16 v[32:35], v[180:183], v[196:199], v[32:35]
	v_mfma_f32_16x16x32_bf16 v[20:23], v[170:173], v[204:207], v[20:23]
	v_mfma_f32_16x16x32_bf16 v[16:19], v[180:183], v[204:207], v[16:19]
	v_mfma_f32_16x16x32_bf16 v[4:7], v[170:173], v[212:215], v[4:7]
	v_mfma_f32_16x16x32_bf16 v[0:3], v[180:183], v[212:215], v[0:3]
	v_mfma_f32_16x16x32_bf16 v[52:55], v[176:179], v[192:195], v[52:55]
	v_mfma_f32_16x16x32_bf16 v[48:51], v[184:187], v[192:195], v[48:51]
	v_mfma_f32_16x16x32_bf16 v[36:39], v[176:179], v[200:203], v[36:39]
	v_mfma_f32_16x16x32_bf16 v[32:35], v[184:187], v[200:203], v[32:35]
	v_mfma_f32_16x16x32_bf16 v[20:23], v[176:179], v[208:211], v[20:23]
	v_mfma_f32_16x16x32_bf16 v[16:19], v[184:187], v[208:211], v[16:19]
	v_mfma_f32_16x16x32_bf16 v[4:7], v[176:179], v[216:219], v[4:7]
	v_mfma_f32_16x16x32_bf16 v[0:3], v[184:187], v[216:219], v[0:3]
	s_barrier
	s_add_i32 s39, s39, 2
	s_add_u32 s14, s14, 0x100
	s_addc_u32 s15, s15, 0
	s_cmp_gt_u32 s39, 13
	s_cbranch_scc0 .LBB0_432
	s_cmpk_lt_u32 s16, 0x100
	s_cbranch_scc0 .LBB0_435
	s_barrier

; #define PG8_STAGE(bufoff, gbase, voff) do { _Pragma("unroll") for (int _i = 0; _i < 2; ++_i) \
;         __builtin_amdgcn_global_load_lds((const unsigned*)((const char*)(gbase) + (voff)[_i]), (LAS unsigned*)(lds + (bufoff) + ldsw + _i * 8192), 16, 0, 0); } while (0)
; #define PG8_LDA(dst, b, h) do { _Pragma("unroll") for (int m = 0; m < 4; ++m) _Pragma("unroll") for (int k = 0; k < 2; ++k) dst[m][k] = *(const LAS bf16x8*)(lds + PG8_SA(b, h) + aoff + m * 2048 + k * 1024); } while (0)
; #define PG8_LDB(dst, b, h) do { _Pragma("unroll") for (int n = 0; n < 2; ++n) _Pragma("unroll") for (int k = 0; k < 2; ++k) dst[n][k] = *(const LAS bf16x8*)(lds + PG8_SB(b, h) + boff + n * 2048 + k * 1024); } while (0)
; #define PG8_MMA(ai, bj, At, Bt) do { __builtin_amdgcn_s_setprio(1); _Pragma("unroll") for (int m = 0; m < 4; ++m) _Pragma("unroll") for (int n = 0; n < 2; ++n) _Pragma("unroll") for (int k = 0; k < 2; ++k) \
;         acc[ai][bj][m][n] = __builtin_amdgcn_mfma_f32_16x16x32_bf16(Bt[n][k], At[m][k], acc[ai][bj][m][n], 0, 0, 0); __builtin_amdgcn_s_setprio(0); } while (0)
; #define PG8_WAIT_V(n) asm volatile("s_waitcnt vmcnt(" #n ")" ::: "memory")
; #define PG8_WAIT_L(n) asm volatile("s_waitcnt lgkmcnt(" #n ")" ::: "memory")
; #define PG8_BAR __builtin_amdgcn_s_barrier()
; #define PG8_SCHED __builtin_amdgcn_sched_barrier(0)
; template <class Epi, class Sched, bool ALIGN_EPI = true, bool SP2 = true>
; __device__ __forceinline__ void gemm_phase(LAS unsigned char* lds, const Gemm g, const Sched& S, const Epi& E) {
;     ...
;             PG8_LDB(B0, 0, 0); PG8_LDB(B1, 0, 1); PG8_SCHED; PG8_LDA(At, 0, 0); PG8_STAGE(PG8_SA(1, 1), a1 + hstep, voffA);
;             PG8_WAIT_V(8); PG8_WAIT_L(0); PG8_BAR; PG8_MMA(0, 0, At, B0); PG8_MMA(0, 1, At, B1); PG8_BAR; PG8_SCHED;
;             PG8_LDA(At, 0, 1); PG8_STAGE(PG8_SB(0, 0), b2, voffB); PG8_STAGE(PG8_SB(0, 1), b2 + hstep, voffB); PG8_STAGE(PG8_SA(0, 0), a2, voffA);
;             PG8_WAIT_V(8); PG8_WAIT_L(0); PG8_BAR; PG8_MMA(1, 0, At, B0); PG8_MMA(1, 1, At, B1); PG8_BAR; PG8_SCHED;
.LBB0_547:
	ds_read_b128 v[150:153], v156
	ds_read_b128 v[166:169], v156 offset:1024
	ds_read_b128 v[170:173], v156 offset:2048
	ds_read_b128 v[176:179], v156 offset:3072
	ds_read_b128 v[180:183], v157
	ds_read_b128 v[184:187], v157 offset:1024
	ds_read_b128 v[188:191], v157 offset:2048
	ds_read_b128 v[192:195], v157 offset:3072
	s_add_u32 s12, s10, 0xfffc0080
	s_addc_u32 s13, s11, -1
	s_cmp_eq_u32 s94, 12
	s_cselect_b32 s15, s7, s13
	s_cselect_b32 s14, s9, s12
	s_cselect_b32 s13, s64, s89
	s_cselect_b32 s12, s79, s85
	v_lshl_add_u64 v[228:229], s[10:11], 0, v[142:143]
	s_add_i32 m0, s17, 0xc000
	ds_read_b128 v[196:199], v158
	ds_read_b128 v[200:203], v158 offset:1024
	ds_read_b128 v[204:207], v158 offset:2048
	ds_read_b128 v[208:211], v158 offset:3072
	ds_read_b128 v[212:215], v158 offset:4096
	ds_read_b128 v[216:219], v158 offset:5120
	ds_read_b128 v[220:223], v158 offset:6144
	ds_read_b128 v[224:227], v158 offset:7168
	global_load_lds_dwordx4 v[228:229], off
	v_lshl_add_u64 v[228:229], s[10:11], 0, v[144:145]
	s_add_i32 m0, s17, 0xe000
	s_nop 0
	global_load_lds_dwordx4 v[228:229], off
	s_waitcnt vmcnt(8)
	s_waitcnt lgkmcnt(0)
	s_barrier
	s_waitcnt lgkmcnt(0)
	v_mfma_f32_16x16x32_bf16 v[124:127], v[150:153], v[196:199], v[124:127]
	v_mfma_f32_16x16x32_bf16 v[120:123], v[170:173], v[196:199], v[120:123]
	v_mfma_f32_16x16x32_bf16 v[108:111], v[150:153], v[204:207], v[108:111]
	v_mfma_f32_16x16x32_bf16 v[104:107], v[170:173], v[204:207], v[104:107]
	v_mfma_f32_16x16x32_bf16 v[92:95], v[150:153], v[212:215], v[92:95]
	v_mfma_f32_16x16x32_bf16 v[88:91], v[170:173], v[212:215], v[88:91]
	v_mfma_f32_16x16x32_bf16 v[76:79], v[150:153], v[220:223], v[76:79]
	v_mfma_f32_16x16x32_bf16 v[72:75], v[170:173], v[220:223], v[72:75]
	v_mfma_f32_16x16x32_bf16 v[124:127], v[166:169], v[200:203], v[124:127]
	v_mfma_f32_16x16x32_bf16 v[120:123], v[176:179], v[200:203], v[120:123]
	v_mfma_f32_16x16x32_bf16 v[108:111], v[166:169], v[208:211], v[108:111]
	v_mfma_f32_16x16x32_bf16 v[104:107], v[176:179], v[208:211], v[104:107]
	v_mfma_f32_16x16x32_bf16 v[92:95], v[166:169], v[216:219], v[92:95]
	v_mfma_f32_16x16x32_bf16 v[88:91], v[176:179], v[216:219], v[88:91]
	v_mfma_f32_16x16x32_bf16 v[76:79], v[166:169], v[224:227], v[76:79]
	v_mfma_f32_16x16x32_bf16 v[72:75], v[176:179], v[224:227], v[72:75]
	v_mfma_f32_16x16x32_bf16 v[116:119], v[180:183], v[196:199], v[116:119]
	v_mfma_f32_16x16x32_bf16 v[112:115], v[188:191], v[196:199], v[112:115]
	v_mfma_f32_16x16x32_bf16 v[100:103], v[180:183], v[204:207], v[100:103]
	v_mfma_f32_16x16x32_bf16 v[96:99], v[188:191], v[204:207], v[96:99]
	v_mfma_f32_16x16x32_bf16 v[84:87], v[180:183], v[212:215], v[84:87]
	v_mfma_f32_16x16x32_bf16 v[80:83], v[188:191], v[212:215], v[80:83]
	v_mfma_f32_16x16x32_bf16 v[68:71], v[180:183], v[220:223], v[68:71]
	v_mfma_f32_16x16x32_bf16 v[64:67], v[188:191], v[220:223], v[64:67]
	v_mfma_f32_16x16x32_bf16 v[116:119], v[184:187], v[200:203], v[116:119]
	v_mfma_f32_16x16x32_bf16 v[112:115], v[192:195], v[200:203], v[112:115]
	v_mfma_f32_16x16x32_bf16 v[100:103], v[184:187], v[208:211], v[100:103]
	v_mfma_f32_16x16x32_bf16 v[96:99], v[192:195], v[208:211], v[96:99]
	v_mfma_f32_16x16x32_bf16 v[84:87], v[184:187], v[216:219], v[84:87]
	v_mfma_f32_16x16x32_bf16 v[80:83], v[192:195], v[216:219], v[80:83]
	v_mfma_f32_16x16x32_bf16 v[68:71], v[184:187], v[224:227], v[68:71]
	v_mfma_f32_16x16x32_bf16 v[64:67], v[192:195], v[224:227], v[64:67]
	s_barrier
	s_add_i32 s95, s35, s16
	v_lshl_add_u64 v[228:229], s[12:13], 0, v[130:131]
	s_mov_b32 m0, s95
	ds_read_b128 v[196:199], v158 offset:16384
	ds_read_b128 v[200:203], v158 offset:17408
	ds_read_b128 v[204:207], v158 offset:18432
	ds_read_b128 v[208:211], v158 offset:19456
	ds_read_b128 v[212:215], v158 offset:20480
	ds_read_b128 v[216:219], v158 offset:21504
	ds_read_b128 v[220:223], v158 offset:22528
	ds_read_b128 v[224:227], v158 offset:23552
	global_load_lds_dwordx4 v[228:229], off
	s_add_i32 m0, s95, 0x2000
	s_add_u32 vcc_lo, s12, 0x40000
	v_lshl_add_u64 v[230:231], s[12:13], 0, v[134:135]
	s_addc_u32 vcc_hi, s13, 0
	s_add_i32 s95, s18, s16
	global_load_lds_dwordx4 v[230:231], off
	v_lshl_add_u64 v[232:233], vcc, 0, v[130:131]
	s_mov_b32 m0, s95
	v_lshl_add_u64 v[234:235], s[14:15], 0, v[132:133]
	global_load_lds_dwordx4 v[232:233], off
	v_lshl_add_u64 v[232:233], vcc, 0, v[134:135]
	s_add_i32 m0, s95, 0x2000
	s_nop 0
	global_load_lds_dwordx4 v[232:233], off
	v_lshl_add_u64 v[232:233], s[14:15], 0, v[128:129]
	s_mov_b32 m0, s17
	s_nop 0
	global_load_lds_dwordx4 v[232:233], off
	s_mov_b32 m0, s21
	s_nop 0
	global_load_lds_dwordx4 v[234:235], off
	s_waitcnt vmcnt(8)
	s_waitcnt lgkmcnt(0)
	s_barrier
; #define PG8_STAGE(bufoff, gbase, voff) do { _Pragma("unroll") for (int _i = 0; _i < 2; ++_i) \
;         __builtin_amdgcn_global_load_lds((const unsigned*)((const char*)(gbase) + (voff)[_i]), (LAS unsigned*)(lds + (bufoff) + ldsw + _i * 8192), 16, 0, 0); } while (0)
; #define PG8_LDA(dst, b, h) do { _Pragma("unroll") for (int m = 0; m < 4; ++m) _Pragma("unroll") for (int k = 0; k < 2; ++k) dst[m][k] = *(const LAS bf16x8*)(lds + PG8_SA(b, h) + aoff + m * 2048 + k * 1024); } while (0)
; #define PG8_LDB(dst, b, h) do { _Pragma("unroll") for (int n = 0; n < 2; ++n) _Pragma("unroll") for (int k = 0; k < 2; ++k) dst[n][k] = *(const LAS bf16x8*)(lds + PG8_SB(b, h) + boff + n * 2048 + k * 1024); } while (0)
; #define PG8_MMA(ai, bj, At, Bt) do { __builtin_amdgcn_s_setprio(1); _Pragma("unroll") for (int m = 0; m < 4; ++m) _Pragma("unroll") for (int n = 0; n < 2; ++n) _Pragma("unroll") for (int k = 0; k < 2; ++k) \
;         acc[ai][bj][m][n] = __builtin_amdgcn_mfma_f32_16x16x32_bf16(Bt[n][k], At[m][k], acc[ai][bj][m][n], 0, 0, 0); __builtin_amdgcn_s_setprio(0); } while (0)
; #define PG8_WAIT_V(n) asm volatile("s_waitcnt vmcnt(" #n ")" ::: "memory")
; #define PG8_WAIT_L(n) asm volatile("s_waitcnt lgkmcnt(" #n ")" ::: "memory")
; #define PG8_BAR __builtin_amdgcn_s_barrier()
; #define PG8_SCHED __builtin_amdgcn_sched_barrier(0)
; template <class Epi, class Sched, bool ALIGN_EPI = true, bool SP2 = true>
; __device__ __forceinline__ void gemm_phase(LAS unsigned char* lds, const Gemm g, const Sched& S, const Epi& E) {
;     ...
;             PG8_WAIT_V(8); PG8_WAIT_L(0); PG8_BAR; PG8_MMA(1, 0, At, B0); PG8_MMA(1, 1, At, B1); PG8_BAR; PG8_SCHED;
;             PG8_LDB(B0, 1, 0); PG8_LDB(B1, 1, 1); PG8_SCHED; PG8_LDA(At, 1, 0); PG8_STAGE(PG8_SA(0, 1), a2 + hstep, voffA);
;             PG8_WAIT_V(8); PG8_WAIT_L(0); PG8_BAR; PG8_MMA(0, 0, At, B0); PG8_MMA(0, 1, At, B1); PG8_BAR; PG8_SCHED;
	s_waitcnt lgkmcnt(0)
	v_mfma_f32_16x16x32_bf16 v[60:63], v[150:153], v[196:199], v[60:63]
	v_mfma_f32_16x16x32_bf16 v[56:59], v[170:173], v[196:199], v[56:59]
	v_mfma_f32_16x16x32_bf16 v[44:47], v[150:153], v[204:207], v[44:47]
	v_mfma_f32_16x16x32_bf16 v[40:43], v[170:173], v[204:207], v[40:43]
	v_mfma_f32_16x16x32_bf16 v[28:31], v[150:153], v[212:215], v[28:31]
	v_mfma_f32_16x16x32_bf16 v[24:27], v[170:173], v[212:215], v[24:27]
	v_mfma_f32_16x16x32_bf16 v[12:15], v[150:153], v[220:223], v[12:15]
	v_mfma_f32_16x16x32_bf16 v[8:11], v[170:173], v[220:223], v[8:11]
	v_mfma_f32_16x16x32_bf16 v[60:63], v[166:169], v[200:203], v[60:63]
	v_mfma_f32_16x16x32_bf16 v[56:59], v[176:179], v[200:203], v[56:59]
	v_mfma_f32_16x16x32_bf16 v[44:47], v[166:169], v[208:211], v[44:47]
	v_mfma_f32_16x16x32_bf16 v[40:43], v[176:179], v[208:211], v[40:43]
	v_mfma_f32_16x16x32_bf16 v[28:31], v[166:169], v[216:219], v[28:31]
	v_mfma_f32_16x16x32_bf16 v[24:27], v[176:179], v[216:219], v[24:27]
	v_mfma_f32_16x16x32_bf16 v[12:15], v[166:169], v[224:227], v[12:15]
	v_mfma_f32_16x16x32_bf16 v[8:11], v[176:179], v[224:227], v[8:11]
	v_mfma_f32_16x16x32_bf16 v[52:55], v[180:183], v[196:199], v[52:55]
	v_mfma_f32_16x16x32_bf16 v[48:51], v[188:191], v[196:199], v[48:51]
	v_mfma_f32_16x16x32_bf16 v[36:39], v[180:183], v[204:207], v[36:39]
	v_mfma_f32_16x16x32_bf16 v[32:35], v[188:191], v[204:207], v[32:35]
	v_mfma_f32_16x16x32_bf16 v[20:23], v[180:183], v[212:215], v[20:23]
	v_mfma_f32_16x16x32_bf16 v[16:19], v[188:191], v[212:215], v[16:19]
	v_mfma_f32_16x16x32_bf16 v[4:7], v[180:183], v[220:223], v[4:7]
	v_mfma_f32_16x16x32_bf16 v[0:3], v[188:191], v[220:223], v[0:3]
	v_mfma_f32_16x16x32_bf16 v[52:55], v[184:187], v[200:203], v[52:55]
	v_mfma_f32_16x16x32_bf16 v[48:51], v[192:195], v[200:203], v[48:51]
	v_mfma_f32_16x16x32_bf16 v[36:39], v[184:187], v[208:211], v[36:39]
	v_mfma_f32_16x16x32_bf16 v[32:35], v[192:195], v[208:211], v[32:35]
	v_mfma_f32_16x16x32_bf16 v[20:23], v[184:187], v[216:219], v[20:23]
	v_mfma_f32_16x16x32_bf16 v[16:19], v[192:195], v[216:219], v[16:19]
	v_mfma_f32_16x16x32_bf16 v[4:7], v[184:187], v[224:227], v[4:7]
	v_mfma_f32_16x16x32_bf16 v[0:3], v[192:195], v[224:227], v[0:3]
	s_barrier
	s_add_i32 s95, 0, 0x18000
	v_add_u32_e32 v136, s95, v154
	s_add_i32 vcc_lo, 0, 0x1c000
	ds_read_b128 v[150:153], v136
	ds_read_b128 v[166:169], v136 offset:1024
	ds_read_b128 v[170:173], v136 offset:2048
	ds_read_b128 v[176:179], v136 offset:3072
	v_add_u32_e32 v136, vcc_lo, v154
	ds_read_b128 v[180:183], v136
	ds_read_b128 v[184:187], v136 offset:1024
	ds_read_b128 v[188:191], v136 offset:2048
	ds_read_b128 v[192:195], v136 offset:3072
	s_add_u32 s14, s14, 0x40000
	s_addc_u32 s15, s15, 0
	s_mov_b32 m0, s23
	v_lshl_add_u64 v[236:237], s[14:15], 0, v[128:129]
	ds_read_b128 v[196:199], v158 offset:32768
	ds_read_b128 v[200:203], v158 offset:33792
	ds_read_b128 v[204:207], v158 offset:34816
	ds_read_b128 v[208:211], v158 offset:35840
	ds_read_b128 v[212:215], v158 offset:36864
	ds_read_b128 v[216:219], v158 offset:37888
	ds_read_b128 v[220:223], v158 offset:38912
	ds_read_b128 v[224:227], v158 offset:39936
	global_load_lds_dwordx4 v[236:237], off
	v_lshl_add_u64 v[236:237], s[14:15], 0, v[132:133]
	s_mov_b32 m0, s46
	s_nop 0
	global_load_lds_dwordx4 v[236:237], off
	s_waitcnt vmcnt(8)
	s_waitcnt lgkmcnt(0)
	s_barrier
	s_waitcnt lgkmcnt(0)
	v_mfma_f32_16x16x32_bf16 v[124:127], v[150:153], v[196:199], v[124:127]
	v_mfma_f32_16x16x32_bf16 v[120:123], v[170:173], v[196:199], v[120:123]
	v_mfma_f32_16x16x32_bf16 v[108:111], v[150:153], v[204:207], v[108:111]
	v_mfma_f32_16x16x32_bf16 v[104:107], v[170:173], v[204:207], v[104:107]
	v_mfma_f32_16x16x32_bf16 v[92:95], v[150:153], v[212:215], v[92:95]
	v_mfma_f32_16x16x32_bf16 v[88:91], v[170:173], v[212:215], v[88:91]
	v_mfma_f32_16x16x32_bf16 v[76:79], v[150:153], v[220:223], v[76:79]
	v_mfma_f32_16x16x32_bf16 v[72:75], v[170:173], v[220:223], v[72:75]
	v_mfma_f32_16x16x32_bf16 v[124:127], v[166:169], v[200:203], v[124:127]
	v_mfma_f32_16x16x32_bf16 v[120:123], v[176:179], v[200:203], v[120:123]
	v_mfma_f32_16x16x32_bf16 v[108:111], v[166:169], v[208:211], v[108:111]
	v_mfma_f32_16x16x32_bf16 v[104:107], v[176:179], v[208:211], v[104:107]
	v_mfma_f32_16x16x32_bf16 v[92:95], v[166:169], v[216:219], v[92:95]
	v_mfma_f32_16x16x32_bf16 v[88:91], v[176:179], v[216:219], v[88:91]
	v_mfma_f32_16x16x32_bf16 v[76:79], v[166:169], v[224:227], v[76:79]
	v_mfma_f32_16x16x32_bf16 v[72:75], v[176:179], v[224:227], v[72:75]
	v_mfma_f32_16x16x32_bf16 v[116:119], v[180:183], v[196:199], v[116:119]
	v_mfma_f32_16x16x32_bf16 v[112:115], v[188:191], v[196:199], v[112:115]
	v_mfma_f32_16x16x32_bf16 v[100:103], v[180:183], v[204:207], v[100:103]
	v_mfma_f32_16x16x32_bf16 v[96:99], v[188:191], v[204:207], v[96:99]
	v_mfma_f32_16x16x32_bf16 v[84:87], v[180:183], v[212:215], v[84:87]
	v_mfma_f32_16x16x32_bf16 v[80:83], v[188:191], v[212:215], v[80:83]
	v_mfma_f32_16x16x32_bf16 v[68:71], v[180:183], v[220:223], v[68:71]
	v_mfma_f32_16x16x32_bf16 v[64:67], v[188:191], v[220:223], v[64:67]
	v_mfma_f32_16x16x32_bf16 v[116:119], v[184:187], v[200:203], v[116:119]
	v_mfma_f32_16x16x32_bf16 v[112:115], v[192:195], v[200:203], v[112:115]
	v_mfma_f32_16x16x32_bf16 v[100:103], v[184:187], v[208:211], v[100:103]
	v_mfma_f32_16x16x32_bf16 v[96:99], v[192:195], v[208:211], v[96:99]
	v_mfma_f32_16x16x32_bf16 v[84:87], v[184:187], v[216:219], v[84:87]
	v_mfma_f32_16x16x32_bf16 v[80:83], v[192:195], v[216:219], v[80:83]
	v_mfma_f32_16x16x32_bf16 v[68:71], v[184:187], v[224:227], v[68:71]
	v_mfma_f32_16x16x32_bf16 v[64:67], v[192:195], v[224:227], v[64:67]
	s_barrier
; #define PG8_STAGE(bufoff, gbase, voff) do { _Pragma("unroll") for (int _i = 0; _i < 2; ++_i) \
;         __builtin_amdgcn_global_load_lds((const unsigned*)((const char*)(gbase) + (voff)[_i]), (LAS unsigned*)(lds + (bufoff) + ldsw + _i * 8192), 16, 0, 0); } while (0)
; #define PG8_LDA(dst, b, h) do { _Pragma("unroll") for (int m = 0; m < 4; ++m) _Pragma("unroll") for (int k = 0; k < 2; ++k) dst[m][k] = *(const LAS bf16x8*)(lds + PG8_SA(b, h) + aoff + m * 2048 + k * 1024); } while (0)
; #define PG8_MMA(ai, bj, At, Bt) do { __builtin_amdgcn_s_setprio(1); _Pragma("unroll") for (int m = 0; m < 4; ++m) _Pragma("unroll") for (int n = 0; n < 2; ++n) _Pragma("unroll") for (int k = 0; k < 2; ++k) \
;         acc[ai][bj][m][n] = __builtin_amdgcn_mfma_f32_16x16x32_bf16(Bt[n][k], At[m][k], acc[ai][bj][m][n], 0, 0, 0); __builtin_amdgcn_s_setprio(0); } while (0)
; #define PG8_WAIT_V(n) asm volatile("s_waitcnt vmcnt(" #n ")" ::: "memory")
; #define PG8_WAIT_L(n) asm volatile("s_waitcnt lgkmcnt(" #n ")" ::: "memory")
; #define PG8_BAR __builtin_amdgcn_s_barrier()
; #define PG8_SCHED __builtin_amdgcn_sched_barrier(0)
; template <class Epi, class Sched, bool ALIGN_EPI = true, bool SP2 = true>
; __device__ __forceinline__ void gemm_phase(LAS unsigned char* lds, const Gemm g, const Sched& S, const Epi& E) {
;     ...
;             PG8_LDA(At, 1, 1); PG8_STAGE(PG8_SB(1, 0), b3, voffB); PG8_STAGE(PG8_SB(1, 1), b3 + hstep, voffB); PG8_STAGE(PG8_SA(1, 0), a3, voffA);
;             PG8_WAIT_V(8); PG8_WAIT_L(0); PG8_BAR; PG8_MMA(1, 0, At, B0); PG8_MMA(1, 1, At, B1); PG8_BAR; PG8_SCHED;
;     ...
;         if constexpr (ALIGN_EPI) { if (wr == 0) PG8_BAR; }
	s_add_i32 s14, s95, s16
	v_lshl_add_u64 v[228:229], v[228:229], 0, s[70:71]
	s_mov_b32 m0, s14
	ds_read_b128 v[196:199], v158 offset:49152
	ds_read_b128 v[200:203], v158 offset:50176
	ds_read_b128 v[204:207], v158 offset:51200
	ds_read_b128 v[208:211], v158 offset:52224
	ds_read_b128 v[212:215], v158 offset:53248
	ds_read_b128 v[216:219], v158 offset:54272
	ds_read_b128 v[220:223], v158 offset:55296
	ds_read_b128 v[224:227], v158 offset:56320
	global_load_lds_dwordx4 v[228:229], off
	s_add_i32 m0, s14, 0x2000
	s_add_u32 s12, s12, 0x40080
	v_lshl_add_u64 v[228:229], v[230:231], 0, s[70:71]
	s_addc_u32 s13, s13, 0
	s_add_i32 s14, vcc_lo, s16
	global_load_lds_dwordx4 v[228:229], off
	v_lshl_add_u64 v[228:229], s[12:13], 0, v[130:131]
	s_mov_b32 m0, s14
	s_nop 0
	global_load_lds_dwordx4 v[228:229], off
	v_lshl_add_u64 v[228:229], s[12:13], 0, v[134:135]
	s_add_i32 m0, s14, 0x2000
	s_nop 0
	global_load_lds_dwordx4 v[228:229], off
	v_lshl_add_u64 v[228:229], v[232:233], 0, s[70:71]
	s_mov_b32 m0, s49
	s_nop 0
	global_load_lds_dwordx4 v[228:229], off
	v_lshl_add_u64 v[228:229], v[234:235], 0, s[70:71]
	s_mov_b32 m0, s60
	s_nop 0
	global_load_lds_dwordx4 v[228:229], off
	s_waitcnt vmcnt(8)
	s_waitcnt lgkmcnt(0)
	s_barrier
	s_waitcnt lgkmcnt(0)
	v_mfma_f32_16x16x32_bf16 v[60:63], v[150:153], v[196:199], v[60:63]
	v_mfma_f32_16x16x32_bf16 v[56:59], v[170:173], v[196:199], v[56:59]
	v_mfma_f32_16x16x32_bf16 v[44:47], v[150:153], v[204:207], v[44:47]
	v_mfma_f32_16x16x32_bf16 v[40:43], v[170:173], v[204:207], v[40:43]
	v_mfma_f32_16x16x32_bf16 v[28:31], v[150:153], v[212:215], v[28:31]
	v_mfma_f32_16x16x32_bf16 v[24:27], v[170:173], v[212:215], v[24:27]
	v_mfma_f32_16x16x32_bf16 v[12:15], v[150:153], v[220:223], v[12:15]
	v_mfma_f32_16x16x32_bf16 v[8:11], v[170:173], v[220:223], v[8:11]
	v_mfma_f32_16x16x32_bf16 v[60:63], v[166:169], v[200:203], v[60:63]
	v_mfma_f32_16x16x32_bf16 v[56:59], v[176:179], v[200:203], v[56:59]
	v_mfma_f32_16x16x32_bf16 v[44:47], v[166:169], v[208:211], v[44:47]
	v_mfma_f32_16x16x32_bf16 v[40:43], v[176:179], v[208:211], v[40:43]
	v_mfma_f32_16x16x32_bf16 v[28:31], v[166:169], v[216:219], v[28:31]
	v_mfma_f32_16x16x32_bf16 v[24:27], v[176:179], v[216:219], v[24:27]
	v_mfma_f32_16x16x32_bf16 v[12:15], v[166:169], v[224:227], v[12:15]
	v_mfma_f32_16x16x32_bf16 v[8:11], v[176:179], v[224:227], v[8:11]
	v_mfma_f32_16x16x32_bf16 v[52:55], v[180:183], v[196:199], v[52:55]
	v_mfma_f32_16x16x32_bf16 v[48:51], v[188:191], v[196:199], v[48:51]
	v_mfma_f32_16x16x32_bf16 v[36:39], v[180:183], v[204:207], v[36:39]
	v_mfma_f32_16x16x32_bf16 v[32:35], v[188:191], v[204:207], v[32:35]
	v_mfma_f32_16x16x32_bf16 v[20:23], v[180:183], v[212:215], v[20:23]
	v_mfma_f32_16x16x32_bf16 v[16:19], v[188:191], v[212:215], v[16:19]
	v_mfma_f32_16x16x32_bf16 v[4:7], v[180:183], v[220:223], v[4:7]
	v_mfma_f32_16x16x32_bf16 v[0:3], v[188:191], v[220:223], v[0:3]
	v_mfma_f32_16x16x32_bf16 v[52:55], v[184:187], v[200:203], v[52:55]
	v_mfma_f32_16x16x32_bf16 v[48:51], v[192:195], v[200:203], v[48:51]
	v_mfma_f32_16x16x32_bf16 v[36:39], v[184:187], v[208:211], v[36:39]
	v_mfma_f32_16x16x32_bf16 v[32:35], v[192:195], v[208:211], v[32:35]
	v_mfma_f32_16x16x32_bf16 v[20:23], v[184:187], v[216:219], v[20:23]
	v_mfma_f32_16x16x32_bf16 v[16:19], v[192:195], v[216:219], v[16:19]
	v_mfma_f32_16x16x32_bf16 v[4:7], v[184:187], v[224:227], v[4:7]
	v_mfma_f32_16x16x32_bf16 v[0:3], v[192:195], v[224:227], v[0:3]
	s_barrier
	s_add_i32 s94, s94, 2
	s_add_u32 s10, s10, 0x100
	s_addc_u32 s11, s11, 0
	s_add_u32 s85, s85, 0x100
	s_addc_u32 s89, s89, 0
	s_cmp_gt_u32 s94, 13
	s_cbranch_scc0 .LBB0_547
	s_and_b64 vcc, exec, s[72:73]
	s_cbranch_vccz .LBB0_550
	s_barrier

; #define PG8_STAGE(bufoff, gbase, voff) do { _Pragma("unroll") for (int _i = 0; _i < 2; ++_i) \
;         __builtin_amdgcn_global_load_lds((const unsigned*)((const char*)(gbase) + (voff)[_i]), (LAS unsigned*)(lds + (bufoff) + ldsw + _i * 8192), 16, 0, 0); } while (0)
; #define PG8_LDA(dst, b, h) do { _Pragma("unroll") for (int m = 0; m < 4; ++m) _Pragma("unroll") for (int k = 0; k < 2; ++k) dst[m][k] = *(const LAS bf16x8*)(lds + PG8_SA(b, h) + aoff + m * 2048 + k * 1024); } while (0)
; #define PG8_LDB(dst, b, h) do { _Pragma("unroll") for (int n = 0; n < 2; ++n) _Pragma("unroll") for (int k = 0; k < 2; ++k) dst[n][k] = *(const LAS bf16x8*)(lds + PG8_SB(b, h) + boff + n * 2048 + k * 1024); } while (0)
; #define PG8_MMA(ai, bj, At, Bt) do { __builtin_amdgcn_s_setprio(1); _Pragma("unroll") for (int m = 0; m < 4; ++m) _Pragma("unroll") for (int n = 0; n < 2; ++n) _Pragma("unroll") for (int k = 0; k < 2; ++k) \
;         acc[ai][bj][m][n] = __builtin_amdgcn_mfma_f32_16x16x32_bf16(Bt[n][k], At[m][k], acc[ai][bj][m][n], 0, 0, 0); __builtin_amdgcn_s_setprio(0); } while (0)
; #define PG8_WAIT_V(n) asm volatile("s_waitcnt vmcnt(" #n ")" ::: "memory")
; #define PG8_WAIT_L(n) asm volatile("s_waitcnt lgkmcnt(" #n ")" ::: "memory")
; #define PG8_BAR __builtin_amdgcn_s_barrier()
; #define PG8_SCHED __builtin_amdgcn_sched_barrier(0)
; template <class Epi, class Sched, bool ALIGN_EPI = true, bool SP2 = true>
; __device__ __forceinline__ void gemm_phase(LAS unsigned char* lds, const Gemm g, const Sched& S, const Epi& E) {
;     ...
;             PG8_LDB(B0, 0, 0); PG8_LDB(B1, 0, 1); PG8_SCHED; PG8_LDA(At, 0, 0); PG8_STAGE(PG8_SA(1, 1), a1 + hstep, voffA);
;             PG8_WAIT_V(8); PG8_WAIT_L(0); PG8_BAR; PG8_MMA(0, 0, At, B0); PG8_MMA(0, 1, At, B1); PG8_BAR; PG8_SCHED;
;             PG8_LDA(At, 0, 1); PG8_STAGE(PG8_SB(0, 0), b2, voffB); PG8_STAGE(PG8_SB(0, 1), b2 + hstep, voffB); PG8_STAGE(PG8_SA(0, 0), a2, voffA);
;             PG8_WAIT_V(8); PG8_WAIT_L(0); PG8_BAR; PG8_MMA(1, 0, At, B0); PG8_MMA(1, 1, At, B1); PG8_BAR; PG8_SCHED;
.LBB0_808:
	ds_read_b128 v[148:151], v153
	ds_read_b128 v[156:159], v153 offset:1024
	ds_read_b128 v[166:169], v153 offset:2048
	ds_read_b128 v[170:173], v153 offset:3072
	ds_read_b128 v[176:179], v154
	ds_read_b128 v[180:183], v154 offset:1024
	ds_read_b128 v[184:187], v154 offset:2048
	ds_read_b128 v[188:191], v154 offset:3072
	s_add_u32 s49, s68, 0xfffc0080
	s_addc_u32 s55, s69, -1
	s_cmp_eq_u32 s48, 12
	s_cselect_b32 s73, s5, s55
	s_cselect_b32 s72, s7, s49
	s_cselect_b32 s71, s10, s47
	s_cselect_b32 s70, s45, s46
	v_lshl_add_u64 v[224:225], s[68:69], 0, v[140:141]
	s_add_i32 m0, s18, 0xc000
	ds_read_b128 v[192:195], v155
	ds_read_b128 v[196:199], v155 offset:1024
	ds_read_b128 v[200:203], v155 offset:2048
	ds_read_b128 v[204:207], v155 offset:3072
	ds_read_b128 v[208:211], v155 offset:4096
	ds_read_b128 v[212:215], v155 offset:5120
	ds_read_b128 v[216:219], v155 offset:6144
	ds_read_b128 v[220:223], v155 offset:7168
	global_load_lds_dwordx4 v[224:225], off
	v_lshl_add_u64 v[224:225], s[68:69], 0, v[142:143]
	s_add_i32 m0, s18, 0xe000
	s_nop 0
	global_load_lds_dwordx4 v[224:225], off
	s_waitcnt vmcnt(8)
	s_waitcnt lgkmcnt(0)
	s_barrier
	s_waitcnt lgkmcnt(0)
	v_mfma_f32_16x16x32_bf16 v[124:127], v[148:151], v[192:195], v[124:127]
	v_mfma_f32_16x16x32_bf16 v[120:123], v[166:169], v[192:195], v[120:123]
	v_mfma_f32_16x16x32_bf16 v[108:111], v[148:151], v[200:203], v[108:111]
	v_mfma_f32_16x16x32_bf16 v[104:107], v[166:169], v[200:203], v[104:107]
	v_mfma_f32_16x16x32_bf16 v[92:95], v[148:151], v[208:211], v[92:95]
	v_mfma_f32_16x16x32_bf16 v[88:91], v[166:169], v[208:211], v[88:91]
	v_mfma_f32_16x16x32_bf16 v[76:79], v[148:151], v[216:219], v[76:79]
	v_mfma_f32_16x16x32_bf16 v[72:75], v[166:169], v[216:219], v[72:75]
	v_mfma_f32_16x16x32_bf16 v[124:127], v[156:159], v[196:199], v[124:127]
	v_mfma_f32_16x16x32_bf16 v[120:123], v[170:173], v[196:199], v[120:123]
	v_mfma_f32_16x16x32_bf16 v[108:111], v[156:159], v[204:207], v[108:111]
	v_mfma_f32_16x16x32_bf16 v[104:107], v[170:173], v[204:207], v[104:107]
	v_mfma_f32_16x16x32_bf16 v[92:95], v[156:159], v[212:215], v[92:95]
	v_mfma_f32_16x16x32_bf16 v[88:91], v[170:173], v[212:215], v[88:91]
	v_mfma_f32_16x16x32_bf16 v[76:79], v[156:159], v[220:223], v[76:79]
	v_mfma_f32_16x16x32_bf16 v[72:75], v[170:173], v[220:223], v[72:75]
	v_mfma_f32_16x16x32_bf16 v[116:119], v[176:179], v[192:195], v[116:119]
	v_mfma_f32_16x16x32_bf16 v[112:115], v[184:187], v[192:195], v[112:115]
	v_mfma_f32_16x16x32_bf16 v[100:103], v[176:179], v[200:203], v[100:103]
	v_mfma_f32_16x16x32_bf16 v[96:99], v[184:187], v[200:203], v[96:99]
	v_mfma_f32_16x16x32_bf16 v[84:87], v[176:179], v[208:211], v[84:87]
	v_mfma_f32_16x16x32_bf16 v[80:83], v[184:187], v[208:211], v[80:83]
	v_mfma_f32_16x16x32_bf16 v[68:71], v[176:179], v[216:219], v[68:71]
	v_mfma_f32_16x16x32_bf16 v[64:67], v[184:187], v[216:219], v[64:67]
	v_mfma_f32_16x16x32_bf16 v[116:119], v[180:183], v[196:199], v[116:119]
	v_mfma_f32_16x16x32_bf16 v[112:115], v[188:191], v[196:199], v[112:115]
	v_mfma_f32_16x16x32_bf16 v[100:103], v[180:183], v[204:207], v[100:103]
	v_mfma_f32_16x16x32_bf16 v[96:99], v[188:191], v[204:207], v[96:99]
	v_mfma_f32_16x16x32_bf16 v[84:87], v[180:183], v[212:215], v[84:87]
	v_mfma_f32_16x16x32_bf16 v[80:83], v[188:191], v[212:215], v[80:83]
	v_mfma_f32_16x16x32_bf16 v[68:71], v[180:183], v[220:223], v[68:71]
	v_mfma_f32_16x16x32_bf16 v[64:67], v[188:191], v[220:223], v[64:67]
	s_barrier
	s_add_i32 s49, s42, s17
	v_lshl_add_u64 v[224:225], s[70:71], 0, v[130:131]
	s_mov_b32 m0, s49
	ds_read_b128 v[192:195], v155 offset:16384
	ds_read_b128 v[196:199], v155 offset:17408
	ds_read_b128 v[200:203], v155 offset:18432
	ds_read_b128 v[204:207], v155 offset:19456
	ds_read_b128 v[208:211], v155 offset:20480
	ds_read_b128 v[212:215], v155 offset:21504
	ds_read_b128 v[216:219], v155 offset:22528
	ds_read_b128 v[220:223], v155 offset:23552
	global_load_lds_dwordx4 v[224:225], off
	s_add_i32 m0, s49, 0x2000
	s_add_u32 s60, s70, 0x40000
	v_lshl_add_u64 v[226:227], s[70:71], 0, v[134:135]
	s_addc_u32 s61, s71, 0
	s_add_i32 s49, s43, s17
	global_load_lds_dwordx4 v[226:227], off
	v_lshl_add_u64 v[228:229], s[60:61], 0, v[130:131]
	s_mov_b32 m0, s49
	v_lshl_add_u64 v[230:231], s[72:73], 0, v[132:133]
	global_load_lds_dwordx4 v[228:229], off
	v_lshl_add_u64 v[228:229], s[60:61], 0, v[134:135]
	s_add_i32 m0, s49, 0x2000
	s_nop 0
	global_load_lds_dwordx4 v[228:229], off
	v_lshl_add_u64 v[228:229], s[72:73], 0, v[128:129]
	s_mov_b32 m0, s18
	s_nop 0
	global_load_lds_dwordx4 v[228:229], off
	s_mov_b32 m0, s19
	s_nop 0
	global_load_lds_dwordx4 v[230:231], off
	s_waitcnt vmcnt(8)
	s_waitcnt lgkmcnt(0)
	s_barrier
; #define PG8_STAGE(bufoff, gbase, voff) do { _Pragma("unroll") for (int _i = 0; _i < 2; ++_i) \
;         __builtin_amdgcn_global_load_lds((const unsigned*)((const char*)(gbase) + (voff)[_i]), (LAS unsigned*)(lds + (bufoff) + ldsw + _i * 8192), 16, 0, 0); } while (0)
; #define PG8_LDA(dst, b, h) do { _Pragma("unroll") for (int m = 0; m < 4; ++m) _Pragma("unroll") for (int k = 0; k < 2; ++k) dst[m][k] = *(const LAS bf16x8*)(lds + PG8_SA(b, h) + aoff + m * 2048 + k * 1024); } while (0)
; #define PG8_LDB(dst, b, h) do { _Pragma("unroll") for (int n = 0; n < 2; ++n) _Pragma("unroll") for (int k = 0; k < 2; ++k) dst[n][k] = *(const LAS bf16x8*)(lds + PG8_SB(b, h) + boff + n * 2048 + k * 1024); } while (0)
; #define PG8_MMA(ai, bj, At, Bt) do { __builtin_amdgcn_s_setprio(1); _Pragma("unroll") for (int m = 0; m < 4; ++m) _Pragma("unroll") for (int n = 0; n < 2; ++n) _Pragma("unroll") for (int k = 0; k < 2; ++k) \
;         acc[ai][bj][m][n] = __builtin_amdgcn_mfma_f32_16x16x32_bf16(Bt[n][k], At[m][k], acc[ai][bj][m][n], 0, 0, 0); __builtin_amdgcn_s_setprio(0); } while (0)
; #define PG8_WAIT_V(n) asm volatile("s_waitcnt vmcnt(" #n ")" ::: "memory")
; #define PG8_WAIT_L(n) asm volatile("s_waitcnt lgkmcnt(" #n ")" ::: "memory")
; #define PG8_BAR __builtin_amdgcn_s_barrier()
; #define PG8_SCHED __builtin_amdgcn_sched_barrier(0)
; template <class Epi, class Sched, bool ALIGN_EPI = true, bool SP2 = true>
; __device__ __forceinline__ void gemm_phase(LAS unsigned char* lds, const Gemm g, const Sched& S, const Epi& E) {
;     ...
;             PG8_WAIT_V(8); PG8_WAIT_L(0); PG8_BAR; PG8_MMA(1, 0, At, B0); PG8_MMA(1, 1, At, B1); PG8_BAR; PG8_SCHED;
;             PG8_LDB(B0, 1, 0); PG8_LDB(B1, 1, 1); PG8_SCHED; PG8_LDA(At, 1, 0); PG8_STAGE(PG8_SA(0, 1), a2 + hstep, voffA);
;             PG8_WAIT_V(8); PG8_WAIT_L(0); PG8_BAR; PG8_MMA(0, 0, At, B0); PG8_MMA(0, 1, At, B1); PG8_BAR; PG8_SCHED;
	s_waitcnt lgkmcnt(0)
	v_mfma_f32_16x16x32_bf16 v[60:63], v[148:151], v[192:195], v[60:63]
	v_mfma_f32_16x16x32_bf16 v[56:59], v[166:169], v[192:195], v[56:59]
	v_mfma_f32_16x16x32_bf16 v[44:47], v[148:151], v[200:203], v[44:47]
	v_mfma_f32_16x16x32_bf16 v[40:43], v[166:169], v[200:203], v[40:43]
	v_mfma_f32_16x16x32_bf16 v[28:31], v[148:151], v[208:211], v[28:31]
	v_mfma_f32_16x16x32_bf16 v[24:27], v[166:169], v[208:211], v[24:27]
	v_mfma_f32_16x16x32_bf16 v[12:15], v[148:151], v[216:219], v[12:15]
	v_mfma_f32_16x16x32_bf16 v[8:11], v[166:169], v[216:219], v[8:11]
	v_mfma_f32_16x16x32_bf16 v[60:63], v[156:159], v[196:199], v[60:63]
	v_mfma_f32_16x16x32_bf16 v[56:59], v[170:173], v[196:199], v[56:59]
	v_mfma_f32_16x16x32_bf16 v[44:47], v[156:159], v[204:207], v[44:47]
	v_mfma_f32_16x16x32_bf16 v[40:43], v[170:173], v[204:207], v[40:43]
	v_mfma_f32_16x16x32_bf16 v[28:31], v[156:159], v[212:215], v[28:31]
	v_mfma_f32_16x16x32_bf16 v[24:27], v[170:173], v[212:215], v[24:27]
	v_mfma_f32_16x16x32_bf16 v[12:15], v[156:159], v[220:223], v[12:15]
	v_mfma_f32_16x16x32_bf16 v[8:11], v[170:173], v[220:223], v[8:11]
	v_mfma_f32_16x16x32_bf16 v[52:55], v[176:179], v[192:195], v[52:55]
	v_mfma_f32_16x16x32_bf16 v[48:51], v[184:187], v[192:195], v[48:51]
	v_mfma_f32_16x16x32_bf16 v[36:39], v[176:179], v[200:203], v[36:39]
	v_mfma_f32_16x16x32_bf16 v[32:35], v[184:187], v[200:203], v[32:35]
	v_mfma_f32_16x16x32_bf16 v[20:23], v[176:179], v[208:211], v[20:23]
	v_mfma_f32_16x16x32_bf16 v[16:19], v[184:187], v[208:211], v[16:19]
	v_mfma_f32_16x16x32_bf16 v[4:7], v[176:179], v[216:219], v[4:7]
	v_mfma_f32_16x16x32_bf16 v[0:3], v[184:187], v[216:219], v[0:3]
	v_mfma_f32_16x16x32_bf16 v[52:55], v[180:183], v[196:199], v[52:55]
	v_mfma_f32_16x16x32_bf16 v[48:51], v[188:191], v[196:199], v[48:51]
	v_mfma_f32_16x16x32_bf16 v[36:39], v[180:183], v[204:207], v[36:39]
	v_mfma_f32_16x16x32_bf16 v[32:35], v[188:191], v[204:207], v[32:35]
	v_mfma_f32_16x16x32_bf16 v[20:23], v[180:183], v[212:215], v[20:23]
	v_mfma_f32_16x16x32_bf16 v[16:19], v[188:191], v[212:215], v[16:19]
	v_mfma_f32_16x16x32_bf16 v[4:7], v[180:183], v[220:223], v[4:7]
	v_mfma_f32_16x16x32_bf16 v[0:3], v[188:191], v[220:223], v[0:3]
	s_barrier
	s_add_i32 s49, 0, 0x18000
	v_add_u32_e32 v136, s49, v152
	s_add_i32 s55, 0, 0x1c000
	ds_read_b128 v[148:151], v136
	ds_read_b128 v[156:159], v136 offset:1024
	ds_read_b128 v[166:169], v136 offset:2048
	ds_read_b128 v[170:173], v136 offset:3072
	v_add_u32_e32 v136, s55, v152
	ds_read_b128 v[176:179], v136
	ds_read_b128 v[180:183], v136 offset:1024
	ds_read_b128 v[184:187], v136 offset:2048
	ds_read_b128 v[188:191], v136 offset:3072
	s_add_u32 s60, s72, 0x40000
	s_addc_u32 s61, s73, 0
	s_mov_b32 m0, s23
	v_lshl_add_u64 v[232:233], s[60:61], 0, v[128:129]
	ds_read_b128 v[192:195], v155 offset:32768
	ds_read_b128 v[196:199], v155 offset:33792
	ds_read_b128 v[200:203], v155 offset:34816
	ds_read_b128 v[204:207], v155 offset:35840
	ds_read_b128 v[208:211], v155 offset:36864
	ds_read_b128 v[212:215], v155 offset:37888
	ds_read_b128 v[216:219], v155 offset:38912
	ds_read_b128 v[220:223], v155 offset:39936
	global_load_lds_dwordx4 v[232:233], off
	v_lshl_add_u64 v[232:233], s[60:61], 0, v[132:133]
	s_mov_b32 m0, s24
	s_nop 0
	global_load_lds_dwordx4 v[232:233], off
	s_waitcnt vmcnt(8)
	s_waitcnt lgkmcnt(0)
	s_barrier
	s_waitcnt lgkmcnt(0)
	v_mfma_f32_16x16x32_bf16 v[124:127], v[148:151], v[192:195], v[124:127]
	v_mfma_f32_16x16x32_bf16 v[120:123], v[166:169], v[192:195], v[120:123]
	v_mfma_f32_16x16x32_bf16 v[108:111], v[148:151], v[200:203], v[108:111]
	v_mfma_f32_16x16x32_bf16 v[104:107], v[166:169], v[200:203], v[104:107]
	v_mfma_f32_16x16x32_bf16 v[92:95], v[148:151], v[208:211], v[92:95]
	v_mfma_f32_16x16x32_bf16 v[88:91], v[166:169], v[208:211], v[88:91]
	v_mfma_f32_16x16x32_bf16 v[76:79], v[148:151], v[216:219], v[76:79]
	v_mfma_f32_16x16x32_bf16 v[72:75], v[166:169], v[216:219], v[72:75]
	v_mfma_f32_16x16x32_bf16 v[124:127], v[156:159], v[196:199], v[124:127]
	v_mfma_f32_16x16x32_bf16 v[120:123], v[170:173], v[196:199], v[120:123]
	v_mfma_f32_16x16x32_bf16 v[108:111], v[156:159], v[204:207], v[108:111]
	v_mfma_f32_16x16x32_bf16 v[104:107], v[170:173], v[204:207], v[104:107]
	v_mfma_f32_16x16x32_bf16 v[92:95], v[156:159], v[212:215], v[92:95]
	v_mfma_f32_16x16x32_bf16 v[88:91], v[170:173], v[212:215], v[88:91]
	v_mfma_f32_16x16x32_bf16 v[76:79], v[156:159], v[220:223], v[76:79]
	v_mfma_f32_16x16x32_bf16 v[72:75], v[170:173], v[220:223], v[72:75]
	v_mfma_f32_16x16x32_bf16 v[116:119], v[176:179], v[192:195], v[116:119]
	v_mfma_f32_16x16x32_bf16 v[112:115], v[184:187], v[192:195], v[112:115]
	v_mfma_f32_16x16x32_bf16 v[100:103], v[176:179], v[200:203], v[100:103]
	v_mfma_f32_16x16x32_bf16 v[96:99], v[184:187], v[200:203], v[96:99]
	v_mfma_f32_16x16x32_bf16 v[84:87], v[176:179], v[208:211], v[84:87]
	v_mfma_f32_16x16x32_bf16 v[80:83], v[184:187], v[208:211], v[80:83]
	v_mfma_f32_16x16x32_bf16 v[68:71], v[176:179], v[216:219], v[68:71]
	v_mfma_f32_16x16x32_bf16 v[64:67], v[184:187], v[216:219], v[64:67]
	v_mfma_f32_16x16x32_bf16 v[116:119], v[180:183], v[196:199], v[116:119]
	v_mfma_f32_16x16x32_bf16 v[112:115], v[188:191], v[196:199], v[112:115]
	v_mfma_f32_16x16x32_bf16 v[100:103], v[180:183], v[204:207], v[100:103]
	v_mfma_f32_16x16x32_bf16 v[96:99], v[188:191], v[204:207], v[96:99]
	v_mfma_f32_16x16x32_bf16 v[84:87], v[180:183], v[212:215], v[84:87]
	v_mfma_f32_16x16x32_bf16 v[80:83], v[188:191], v[212:215], v[80:83]
	v_mfma_f32_16x16x32_bf16 v[68:71], v[180:183], v[220:223], v[68:71]
	v_mfma_f32_16x16x32_bf16 v[64:67], v[188:191], v[220:223], v[64:67]
	s_barrier
; #define PG8_STAGE(bufoff, gbase, voff) do { _Pragma("unroll") for (int _i = 0; _i < 2; ++_i) \
;         __builtin_amdgcn_global_load_lds((const unsigned*)((const char*)(gbase) + (voff)[_i]), (LAS unsigned*)(lds + (bufoff) + ldsw + _i * 8192), 16, 0, 0); } while (0)
; #define PG8_LDA(dst, b, h) do { _Pragma("unroll") for (int m = 0; m < 4; ++m) _Pragma("unroll") for (int k = 0; k < 2; ++k) dst[m][k] = *(const LAS bf16x8*)(lds + PG8_SA(b, h) + aoff + m * 2048 + k * 1024); } while (0)
; #define PG8_MMA(ai, bj, At, Bt) do { __builtin_amdgcn_s_setprio(1); _Pragma("unroll") for (int m = 0; m < 4; ++m) _Pragma("unroll") for (int n = 0; n < 2; ++n) _Pragma("unroll") for (int k = 0; k < 2; ++k) \
;         acc[ai][bj][m][n] = __builtin_amdgcn_mfma_f32_16x16x32_bf16(Bt[n][k], At[m][k], acc[ai][bj][m][n], 0, 0, 0); __builtin_amdgcn_s_setprio(0); } while (0)
; #define PG8_WAIT_V(n) asm volatile("s_waitcnt vmcnt(" #n ")" ::: "memory")
; #define PG8_WAIT_L(n) asm volatile("s_waitcnt lgkmcnt(" #n ")" ::: "memory")
; #define PG8_BAR __builtin_amdgcn_s_barrier()
; #define PG8_SCHED __builtin_amdgcn_sched_barrier(0)
; template <class Epi, class Sched, bool ALIGN_EPI = true, bool SP2 = true>
; __device__ __forceinline__ void gemm_phase(LAS unsigned char* lds, const Gemm g, const Sched& S, const Epi& E) {
;     ...
;             PG8_LDA(At, 1, 1); PG8_STAGE(PG8_SB(1, 0), b3, voffB); PG8_STAGE(PG8_SB(1, 1), b3 + hstep, voffB); PG8_STAGE(PG8_SA(1, 0), a3, voffA);
;             PG8_WAIT_V(8); PG8_WAIT_L(0); PG8_BAR; PG8_MMA(1, 0, At, B0); PG8_MMA(1, 1, At, B1); PG8_BAR; PG8_SCHED;
;     ...
;         if constexpr (ALIGN_EPI) { if (wr == 0) PG8_BAR; }
	s_add_i32 s49, s49, s17
	v_lshl_add_u64 v[224:225], v[224:225], 0, s[14:15]
	s_mov_b32 m0, s49
	ds_read_b128 v[192:195], v155 offset:49152
	ds_read_b128 v[196:199], v155 offset:50176
	ds_read_b128 v[200:203], v155 offset:51200
	ds_read_b128 v[204:207], v155 offset:52224
	ds_read_b128 v[208:211], v155 offset:53248
	ds_read_b128 v[212:215], v155 offset:54272
	ds_read_b128 v[216:219], v155 offset:55296
	ds_read_b128 v[220:223], v155 offset:56320
	global_load_lds_dwordx4 v[224:225], off
	s_add_i32 m0, s49, 0x2000
	s_add_u32 s60, s70, 0x40080
	v_lshl_add_u64 v[224:225], v[226:227], 0, s[14:15]
	s_addc_u32 s61, s71, 0
	s_add_i32 s49, s55, s17
	global_load_lds_dwordx4 v[224:225], off
	v_lshl_add_u64 v[224:225], s[60:61], 0, v[130:131]
	s_mov_b32 m0, s49
	s_nop 0
	global_load_lds_dwordx4 v[224:225], off
	v_lshl_add_u64 v[224:225], s[60:61], 0, v[134:135]
	s_add_i32 m0, s49, 0x2000
	s_nop 0
	global_load_lds_dwordx4 v[224:225], off
	v_lshl_add_u64 v[224:225], v[228:229], 0, s[14:15]
	s_mov_b32 m0, s25
	s_nop 0
	global_load_lds_dwordx4 v[224:225], off
	v_lshl_add_u64 v[224:225], v[230:231], 0, s[14:15]
	s_mov_b32 m0, s34
	s_nop 0
	global_load_lds_dwordx4 v[224:225], off
	s_waitcnt vmcnt(8)
	s_waitcnt lgkmcnt(0)
	s_barrier
	s_waitcnt lgkmcnt(0)
	v_mfma_f32_16x16x32_bf16 v[60:63], v[148:151], v[192:195], v[60:63]
	v_mfma_f32_16x16x32_bf16 v[56:59], v[166:169], v[192:195], v[56:59]
	v_mfma_f32_16x16x32_bf16 v[44:47], v[148:151], v[200:203], v[44:47]
	v_mfma_f32_16x16x32_bf16 v[40:43], v[166:169], v[200:203], v[40:43]
	v_mfma_f32_16x16x32_bf16 v[28:31], v[148:151], v[208:211], v[28:31]
	v_mfma_f32_16x16x32_bf16 v[24:27], v[166:169], v[208:211], v[24:27]
	v_mfma_f32_16x16x32_bf16 v[12:15], v[148:151], v[216:219], v[12:15]
	v_mfma_f32_16x16x32_bf16 v[8:11], v[166:169], v[216:219], v[8:11]
	v_mfma_f32_16x16x32_bf16 v[60:63], v[156:159], v[196:199], v[60:63]
	v_mfma_f32_16x16x32_bf16 v[56:59], v[170:173], v[196:199], v[56:59]
	v_mfma_f32_16x16x32_bf16 v[44:47], v[156:159], v[204:207], v[44:47]
	v_mfma_f32_16x16x32_bf16 v[40:43], v[170:173], v[204:207], v[40:43]
	v_mfma_f32_16x16x32_bf16 v[28:31], v[156:159], v[212:215], v[28:31]
	v_mfma_f32_16x16x32_bf16 v[24:27], v[170:173], v[212:215], v[24:27]
	v_mfma_f32_16x16x32_bf16 v[12:15], v[156:159], v[220:223], v[12:15]
	v_mfma_f32_16x16x32_bf16 v[8:11], v[170:173], v[220:223], v[8:11]
	v_mfma_f32_16x16x32_bf16 v[52:55], v[176:179], v[192:195], v[52:55]
	v_mfma_f32_16x16x32_bf16 v[48:51], v[184:187], v[192:195], v[48:51]
	v_mfma_f32_16x16x32_bf16 v[36:39], v[176:179], v[200:203], v[36:39]
	v_mfma_f32_16x16x32_bf16 v[32:35], v[184:187], v[200:203], v[32:35]
	v_mfma_f32_16x16x32_bf16 v[20:23], v[176:179], v[208:211], v[20:23]
	v_mfma_f32_16x16x32_bf16 v[16:19], v[184:187], v[208:211], v[16:19]
	v_mfma_f32_16x16x32_bf16 v[4:7], v[176:179], v[216:219], v[4:7]
	v_mfma_f32_16x16x32_bf16 v[0:3], v[184:187], v[216:219], v[0:3]
	v_mfma_f32_16x16x32_bf16 v[52:55], v[180:183], v[196:199], v[52:55]
	v_mfma_f32_16x16x32_bf16 v[48:51], v[188:191], v[196:199], v[48:51]
	v_mfma_f32_16x16x32_bf16 v[36:39], v[180:183], v[204:207], v[36:39]
	v_mfma_f32_16x16x32_bf16 v[32:35], v[188:191], v[204:207], v[32:35]
	v_mfma_f32_16x16x32_bf16 v[20:23], v[180:183], v[212:215], v[20:23]
	v_mfma_f32_16x16x32_bf16 v[16:19], v[188:191], v[212:215], v[16:19]
	v_mfma_f32_16x16x32_bf16 v[4:7], v[180:183], v[220:223], v[4:7]
	v_mfma_f32_16x16x32_bf16 v[0:3], v[188:191], v[220:223], v[0:3]
	s_barrier
	s_add_i32 s48, s48, 2
	s_add_u32 s68, s68, 0x100
	s_addc_u32 s69, s69, 0
	s_add_u32 s46, s46, 0x100
	s_addc_u32 s47, s47, 0
	s_cmp_gt_u32 s48, 13
	s_cbranch_scc0 .LBB0_808
	s_and_b64 vcc, exec, s[52:53]
	s_cbranch_vccz .LBB0_811
	s_barrier

; #define PG8_STAGE(bufoff, gbase, voff) do { _Pragma("unroll") for (int _i = 0; _i < 2; ++_i) \
;         __builtin_amdgcn_global_load_lds((const unsigned*)((const char*)(gbase) + (voff)[_i]), (LAS unsigned*)(lds + (bufoff) + ldsw + _i * 8192), 16, 0, 0); } while (0)
; #define PG8_LDA(dst, b, h) do { _Pragma("unroll") for (int m = 0; m < 4; ++m) _Pragma("unroll") for (int k = 0; k < 2; ++k) dst[m][k] = *(const LAS bf16x8*)(lds + PG8_SA(b, h) + aoff + m * 2048 + k * 1024); } while (0)
; #define PG8_LDB(dst, b, h) do { _Pragma("unroll") for (int n = 0; n < 2; ++n) _Pragma("unroll") for (int k = 0; k < 2; ++k) dst[n][k] = *(const LAS bf16x8*)(lds + PG8_SB(b, h) + boff + n * 2048 + k * 1024); } while (0)
; #define PG8_MMA(ai, bj, At, Bt) do { __builtin_amdgcn_s_setprio(1); _Pragma("unroll") for (int m = 0; m < 4; ++m) _Pragma("unroll") for (int n = 0; n < 2; ++n) _Pragma("unroll") for (int k = 0; k < 2; ++k) \
;         acc[ai][bj][m][n] = __builtin_amdgcn_mfma_f32_16x16x32_bf16(Bt[n][k], At[m][k], acc[ai][bj][m][n], 0, 0, 0); __builtin_amdgcn_s_setprio(0); } while (0)
; #define PG8_WAIT_V(n) asm volatile("s_waitcnt vmcnt(" #n ")" ::: "memory")
; #define PG8_WAIT_L(n) asm volatile("s_waitcnt lgkmcnt(" #n ")" ::: "memory")
; #define PG8_BAR __builtin_amdgcn_s_barrier()
; #define PG8_SCHED __builtin_amdgcn_sched_barrier(0)
; template <class Epi, class Sched, bool ALIGN_EPI = true, bool SP2 = true>
; __device__ __forceinline__ void gemm_phase(LAS unsigned char* lds, const Gemm g, const Sched& S, const Epi& E) {
;     ...
;             PG8_LDB(B0, 0, 0); PG8_LDB(B1, 0, 1); PG8_SCHED; PG8_LDA(At, 0, 0); PG8_STAGE(PG8_SA(1, 1), a1 + hstep, voffA);
;             PG8_WAIT_V(8); PG8_WAIT_L(0); PG8_BAR; PG8_MMA(0, 0, At, B0); PG8_MMA(0, 1, At, B1); PG8_BAR; PG8_SCHED;
;             PG8_LDA(At, 0, 1); PG8_STAGE(PG8_SB(0, 0), b2, voffB); PG8_STAGE(PG8_SB(0, 1), b2 + hstep, voffB); PG8_STAGE(PG8_SA(0, 0), a2, voffA);
;             PG8_WAIT_V(8); PG8_WAIT_L(0); PG8_BAR; PG8_MMA(1, 0, At, B0); PG8_MMA(1, 1, At, B1); PG8_BAR; PG8_SCHED;
.LBB0_1012:
	ds_read_b128 v[128:131], v169
	ds_read_b128 v[132:135], v169 offset:1024
	ds_read_b128 v[136:139], v169 offset:2048
	ds_read_b128 v[156:159], v169 offset:3072
	ds_read_b128 v[176:179], v170
	ds_read_b128 v[180:183], v170 offset:1024
	ds_read_b128 v[184:187], v170 offset:2048
	ds_read_b128 v[188:191], v170 offset:3072
	s_add_u32 s68, s64, 0xfffc0080
	s_addc_u32 s69, s65, -1
	s_cmp_eq_u32 s63, 12
	s_cselect_b32 s71, s46, s69
	s_cselect_b32 s70, s47, s68
	s_cselect_b32 s69, s48, s57
	s_cselect_b32 s68, s49, s55
	v_lshl_add_u64 v[166:167], s[64:65], 0, v[148:149]
	s_add_i32 m0, s17, 0xc000
	ds_read_b128 v[192:195], v171
	ds_read_b128 v[196:199], v171 offset:1024
	ds_read_b128 v[200:203], v171 offset:2048
	ds_read_b128 v[204:207], v171 offset:3072
	ds_read_b128 v[208:211], v171 offset:4096
	ds_read_b128 v[212:215], v171 offset:5120
	ds_read_b128 v[216:219], v171 offset:6144
	ds_read_b128 v[220:223], v171 offset:7168
	global_load_lds_dwordx4 v[166:167], off
	v_lshl_add_u64 v[166:167], s[64:65], 0, v[150:151]
	s_add_i32 m0, s17, 0xe000
	s_nop 0
	global_load_lds_dwordx4 v[166:167], off
	s_waitcnt vmcnt(8)
	s_waitcnt lgkmcnt(0)
	s_barrier
	s_waitcnt lgkmcnt(0)
	v_mfma_f32_16x16x32_bf16 v[124:127], v[128:131], v[192:195], v[124:127]
	v_mfma_f32_16x16x32_bf16 v[120:123], v[136:139], v[192:195], v[120:123]
	v_mfma_f32_16x16x32_bf16 v[112:115], v[128:131], v[200:203], v[112:115]
	v_mfma_f32_16x16x32_bf16 v[104:107], v[136:139], v[200:203], v[104:107]
	v_mfma_f32_16x16x32_bf16 v[92:95], v[128:131], v[208:211], v[92:95]
	v_mfma_f32_16x16x32_bf16 v[88:91], v[136:139], v[208:211], v[88:91]
	v_mfma_f32_16x16x32_bf16 v[76:79], v[128:131], v[216:219], v[76:79]
	v_mfma_f32_16x16x32_bf16 v[72:75], v[136:139], v[216:219], v[72:75]
	v_mfma_f32_16x16x32_bf16 v[124:127], v[132:135], v[196:199], v[124:127]
	v_mfma_f32_16x16x32_bf16 v[120:123], v[156:159], v[196:199], v[120:123]
	v_mfma_f32_16x16x32_bf16 v[112:115], v[132:135], v[204:207], v[112:115]
	v_mfma_f32_16x16x32_bf16 v[104:107], v[156:159], v[204:207], v[104:107]
	v_mfma_f32_16x16x32_bf16 v[92:95], v[132:135], v[212:215], v[92:95]
	v_mfma_f32_16x16x32_bf16 v[88:91], v[156:159], v[212:215], v[88:91]
	v_mfma_f32_16x16x32_bf16 v[76:79], v[132:135], v[220:223], v[76:79]
	v_mfma_f32_16x16x32_bf16 v[72:75], v[156:159], v[220:223], v[72:75]
	v_mfma_f32_16x16x32_bf16 v[116:119], v[176:179], v[192:195], v[116:119]
	v_mfma_f32_16x16x32_bf16 v[108:111], v[184:187], v[192:195], v[108:111]
	v_mfma_f32_16x16x32_bf16 v[100:103], v[176:179], v[200:203], v[100:103]
	v_mfma_f32_16x16x32_bf16 v[96:99], v[184:187], v[200:203], v[96:99]
	v_mfma_f32_16x16x32_bf16 v[84:87], v[176:179], v[208:211], v[84:87]
	v_mfma_f32_16x16x32_bf16 v[80:83], v[184:187], v[208:211], v[80:83]
	v_mfma_f32_16x16x32_bf16 v[68:71], v[176:179], v[216:219], v[68:71]
	v_mfma_f32_16x16x32_bf16 v[64:67], v[184:187], v[216:219], v[64:67]
	v_mfma_f32_16x16x32_bf16 v[116:119], v[180:183], v[196:199], v[116:119]
	v_mfma_f32_16x16x32_bf16 v[108:111], v[188:191], v[196:199], v[108:111]
	v_mfma_f32_16x16x32_bf16 v[100:103], v[180:183], v[204:207], v[100:103]
	v_mfma_f32_16x16x32_bf16 v[96:99], v[188:191], v[204:207], v[96:99]
	v_mfma_f32_16x16x32_bf16 v[84:87], v[180:183], v[212:215], v[84:87]
	v_mfma_f32_16x16x32_bf16 v[80:83], v[188:191], v[212:215], v[80:83]
	v_mfma_f32_16x16x32_bf16 v[68:71], v[180:183], v[220:223], v[68:71]
	v_mfma_f32_16x16x32_bf16 v[64:67], v[188:191], v[220:223], v[64:67]
	s_barrier
	s_add_i32 s72, s39, s16
	v_lshl_add_u64 v[166:167], s[68:69], 0, v[142:143]
	s_mov_b32 m0, s72
	ds_read_b128 v[192:195], v171 offset:16384
	ds_read_b128 v[196:199], v171 offset:17408
	ds_read_b128 v[200:203], v171 offset:18432
	ds_read_b128 v[204:207], v171 offset:19456
	ds_read_b128 v[208:211], v171 offset:20480
	ds_read_b128 v[212:215], v171 offset:21504
	ds_read_b128 v[216:219], v171 offset:22528
	ds_read_b128 v[220:223], v171 offset:23552
	global_load_lds_dwordx4 v[166:167], off
	s_add_i32 m0, s72, 0x2000
	s_add_u32 s72, s68, 0x40000
	v_lshl_add_u64 v[172:173], s[68:69], 0, v[146:147]
	s_addc_u32 s73, s69, 0
	s_add_i32 s74, s42, s16
	global_load_lds_dwordx4 v[172:173], off
	v_lshl_add_u64 v[224:225], s[72:73], 0, v[142:143]
	s_mov_b32 m0, s74
	v_lshl_add_u64 v[226:227], s[70:71], 0, v[144:145]
	global_load_lds_dwordx4 v[224:225], off
	v_lshl_add_u64 v[224:225], s[72:73], 0, v[146:147]
	s_add_i32 m0, s74, 0x2000
	s_nop 0
	global_load_lds_dwordx4 v[224:225], off
	v_lshl_add_u64 v[224:225], s[70:71], 0, v[140:141]
	s_mov_b32 m0, s17
	s_nop 0
	global_load_lds_dwordx4 v[224:225], off
	s_mov_b32 m0, s18
	s_nop 0
	global_load_lds_dwordx4 v[226:227], off
	s_waitcnt vmcnt(8)
	s_waitcnt lgkmcnt(0)
	s_barrier
; #define PG8_STAGE(bufoff, gbase, voff) do { _Pragma("unroll") for (int _i = 0; _i < 2; ++_i) \
;         __builtin_amdgcn_global_load_lds((const unsigned*)((const char*)(gbase) + (voff)[_i]), (LAS unsigned*)(lds + (bufoff) + ldsw + _i * 8192), 16, 0, 0); } while (0)
; #define PG8_LDA(dst, b, h) do { _Pragma("unroll") for (int m = 0; m < 4; ++m) _Pragma("unroll") for (int k = 0; k < 2; ++k) dst[m][k] = *(const LAS bf16x8*)(lds + PG8_SA(b, h) + aoff + m * 2048 + k * 1024); } while (0)
; #define PG8_LDB(dst, b, h) do { _Pragma("unroll") for (int n = 0; n < 2; ++n) _Pragma("unroll") for (int k = 0; k < 2; ++k) dst[n][k] = *(const LAS bf16x8*)(lds + PG8_SB(b, h) + boff + n * 2048 + k * 1024); } while (0)
; #define PG8_MMA(ai, bj, At, Bt) do { __builtin_amdgcn_s_setprio(1); _Pragma("unroll") for (int m = 0; m < 4; ++m) _Pragma("unroll") for (int n = 0; n < 2; ++n) _Pragma("unroll") for (int k = 0; k < 2; ++k) \
;         acc[ai][bj][m][n] = __builtin_amdgcn_mfma_f32_16x16x32_bf16(Bt[n][k], At[m][k], acc[ai][bj][m][n], 0, 0, 0); __builtin_amdgcn_s_setprio(0); } while (0)
; #define PG8_WAIT_V(n) asm volatile("s_waitcnt vmcnt(" #n ")" ::: "memory")
; #define PG8_WAIT_L(n) asm volatile("s_waitcnt lgkmcnt(" #n ")" ::: "memory")
; #define PG8_BAR __builtin_amdgcn_s_barrier()
; #define PG8_SCHED __builtin_amdgcn_sched_barrier(0)
; template <class Epi, class Sched, bool ALIGN_EPI = true, bool SP2 = true>
; __device__ __forceinline__ void gemm_phase(LAS unsigned char* lds, const Gemm g, const Sched& S, const Epi& E) {
;     ...
;             PG8_WAIT_V(8); PG8_WAIT_L(0); PG8_BAR; PG8_MMA(1, 0, At, B0); PG8_MMA(1, 1, At, B1); PG8_BAR; PG8_SCHED;
;             PG8_LDB(B0, 1, 0); PG8_LDB(B1, 1, 1); PG8_SCHED; PG8_LDA(At, 1, 0); PG8_STAGE(PG8_SA(0, 1), a2 + hstep, voffA);
;             PG8_WAIT_V(8); PG8_WAIT_L(0); PG8_BAR; PG8_MMA(0, 0, At, B0); PG8_MMA(0, 1, At, B1); PG8_BAR; PG8_SCHED;
	s_waitcnt lgkmcnt(0)
	v_mfma_f32_16x16x32_bf16 v[60:63], v[128:131], v[192:195], v[60:63]
	v_mfma_f32_16x16x32_bf16 v[56:59], v[136:139], v[192:195], v[56:59]
	v_mfma_f32_16x16x32_bf16 v[48:51], v[128:131], v[200:203], v[48:51]
	v_mfma_f32_16x16x32_bf16 v[40:43], v[136:139], v[200:203], v[40:43]
	v_mfma_f32_16x16x32_bf16 v[36:39], v[128:131], v[208:211], v[36:39]
	v_mfma_f32_16x16x32_bf16 v[28:31], v[136:139], v[208:211], v[28:31]
	v_mfma_f32_16x16x32_bf16 v[20:23], v[128:131], v[216:219], v[20:23]
	v_mfma_f32_16x16x32_bf16 v[12:15], v[136:139], v[216:219], v[12:15]
	v_mfma_f32_16x16x32_bf16 v[60:63], v[132:135], v[196:199], v[60:63]
	v_mfma_f32_16x16x32_bf16 v[56:59], v[156:159], v[196:199], v[56:59]
	v_mfma_f32_16x16x32_bf16 v[48:51], v[132:135], v[204:207], v[48:51]
	v_mfma_f32_16x16x32_bf16 v[40:43], v[156:159], v[204:207], v[40:43]
	v_mfma_f32_16x16x32_bf16 v[36:39], v[132:135], v[212:215], v[36:39]
	v_mfma_f32_16x16x32_bf16 v[28:31], v[156:159], v[212:215], v[28:31]
	v_mfma_f32_16x16x32_bf16 v[20:23], v[132:135], v[220:223], v[20:23]
	v_mfma_f32_16x16x32_bf16 v[12:15], v[156:159], v[220:223], v[12:15]
	v_mfma_f32_16x16x32_bf16 v[52:55], v[176:179], v[192:195], v[52:55]
	v_mfma_f32_16x16x32_bf16 v[44:47], v[184:187], v[192:195], v[44:47]
	v_mfma_f32_16x16x32_bf16 v[32:35], v[176:179], v[200:203], v[32:35]
	v_mfma_f32_16x16x32_bf16 v[24:27], v[184:187], v[200:203], v[24:27]
	v_mfma_f32_16x16x32_bf16 v[16:19], v[176:179], v[208:211], v[16:19]
	v_mfma_f32_16x16x32_bf16 v[8:11], v[184:187], v[208:211], v[8:11]
	v_mfma_f32_16x16x32_bf16 v[4:7], v[176:179], v[216:219], v[4:7]
	v_mfma_f32_16x16x32_bf16 v[0:3], v[184:187], v[216:219], v[0:3]
	v_mfma_f32_16x16x32_bf16 v[52:55], v[180:183], v[196:199], v[52:55]
	v_mfma_f32_16x16x32_bf16 v[44:47], v[188:191], v[196:199], v[44:47]
	v_mfma_f32_16x16x32_bf16 v[32:35], v[180:183], v[204:207], v[32:35]
	v_mfma_f32_16x16x32_bf16 v[24:27], v[188:191], v[204:207], v[24:27]
	v_mfma_f32_16x16x32_bf16 v[16:19], v[180:183], v[212:215], v[16:19]
	v_mfma_f32_16x16x32_bf16 v[8:11], v[188:191], v[212:215], v[8:11]
	v_mfma_f32_16x16x32_bf16 v[4:7], v[180:183], v[220:223], v[4:7]
	v_mfma_f32_16x16x32_bf16 v[0:3], v[188:191], v[220:223], v[0:3]
	s_barrier
	s_add_i32 s72, 0, 0x18000
	s_add_i32 s73, 0, 0x1c000
	v_add_u32_e32 v156, s72, v165
	v_add_u32_e32 v175, s73, v165
	ds_read_b128 v[128:131], v156
	ds_read_b128 v[132:135], v156 offset:1024
	ds_read_b128 v[136:139], v156 offset:2048
	ds_read_b128 v[156:159], v156 offset:3072
	ds_read_b128 v[176:179], v175
	ds_read_b128 v[180:183], v175 offset:1024
	ds_read_b128 v[184:187], v175 offset:2048
	ds_read_b128 v[188:191], v175 offset:3072
	s_add_u32 s70, s70, 0x40000
	s_addc_u32 s71, s71, 0
	s_mov_b32 m0, s19
	v_lshl_add_u64 v[228:229], s[70:71], 0, v[140:141]
	ds_read_b128 v[192:195], v171 offset:32768
	ds_read_b128 v[196:199], v171 offset:33792
	ds_read_b128 v[200:203], v171 offset:34816
	ds_read_b128 v[204:207], v171 offset:35840
	ds_read_b128 v[208:211], v171 offset:36864
	ds_read_b128 v[212:215], v171 offset:37888
	ds_read_b128 v[216:219], v171 offset:38912
	ds_read_b128 v[220:223], v171 offset:39936
	global_load_lds_dwordx4 v[228:229], off
	v_lshl_add_u64 v[228:229], s[70:71], 0, v[144:145]
	s_mov_b32 m0, s23
	s_nop 0
	global_load_lds_dwordx4 v[228:229], off
	s_waitcnt vmcnt(8)
	s_waitcnt lgkmcnt(0)
	s_barrier
	s_waitcnt lgkmcnt(0)
	v_mfma_f32_16x16x32_bf16 v[124:127], v[128:131], v[192:195], v[124:127]
	v_mfma_f32_16x16x32_bf16 v[120:123], v[136:139], v[192:195], v[120:123]
	v_mfma_f32_16x16x32_bf16 v[112:115], v[128:131], v[200:203], v[112:115]
	v_mfma_f32_16x16x32_bf16 v[104:107], v[136:139], v[200:203], v[104:107]
	v_mfma_f32_16x16x32_bf16 v[92:95], v[128:131], v[208:211], v[92:95]
	v_mfma_f32_16x16x32_bf16 v[88:91], v[136:139], v[208:211], v[88:91]
	v_mfma_f32_16x16x32_bf16 v[76:79], v[128:131], v[216:219], v[76:79]
	v_mfma_f32_16x16x32_bf16 v[72:75], v[136:139], v[216:219], v[72:75]
	v_mfma_f32_16x16x32_bf16 v[124:127], v[132:135], v[196:199], v[124:127]
	v_mfma_f32_16x16x32_bf16 v[120:123], v[156:159], v[196:199], v[120:123]
	v_mfma_f32_16x16x32_bf16 v[112:115], v[132:135], v[204:207], v[112:115]
	v_mfma_f32_16x16x32_bf16 v[104:107], v[156:159], v[204:207], v[104:107]
	v_mfma_f32_16x16x32_bf16 v[92:95], v[132:135], v[212:215], v[92:95]
	v_mfma_f32_16x16x32_bf16 v[88:91], v[156:159], v[212:215], v[88:91]
	v_mfma_f32_16x16x32_bf16 v[76:79], v[132:135], v[220:223], v[76:79]
	v_mfma_f32_16x16x32_bf16 v[72:75], v[156:159], v[220:223], v[72:75]
	v_mfma_f32_16x16x32_bf16 v[116:119], v[176:179], v[192:195], v[116:119]
	v_mfma_f32_16x16x32_bf16 v[108:111], v[184:187], v[192:195], v[108:111]
	v_mfma_f32_16x16x32_bf16 v[100:103], v[176:179], v[200:203], v[100:103]
	v_mfma_f32_16x16x32_bf16 v[96:99], v[184:187], v[200:203], v[96:99]
	v_mfma_f32_16x16x32_bf16 v[84:87], v[176:179], v[208:211], v[84:87]
	v_mfma_f32_16x16x32_bf16 v[80:83], v[184:187], v[208:211], v[80:83]
	v_mfma_f32_16x16x32_bf16 v[68:71], v[176:179], v[216:219], v[68:71]
	v_mfma_f32_16x16x32_bf16 v[64:67], v[184:187], v[216:219], v[64:67]
	v_mfma_f32_16x16x32_bf16 v[116:119], v[180:183], v[196:199], v[116:119]
	v_mfma_f32_16x16x32_bf16 v[108:111], v[188:191], v[196:199], v[108:111]
	v_mfma_f32_16x16x32_bf16 v[100:103], v[180:183], v[204:207], v[100:103]
	v_mfma_f32_16x16x32_bf16 v[96:99], v[188:191], v[204:207], v[96:99]
	v_mfma_f32_16x16x32_bf16 v[84:87], v[180:183], v[212:215], v[84:87]
	v_mfma_f32_16x16x32_bf16 v[80:83], v[188:191], v[212:215], v[80:83]
	v_mfma_f32_16x16x32_bf16 v[68:71], v[180:183], v[220:223], v[68:71]
	v_mfma_f32_16x16x32_bf16 v[64:67], v[188:191], v[220:223], v[64:67]
	s_barrier
; #define PG8_STAGE(bufoff, gbase, voff) do { _Pragma("unroll") for (int _i = 0; _i < 2; ++_i) \
;         __builtin_amdgcn_global_load_lds((const unsigned*)((const char*)(gbase) + (voff)[_i]), (LAS unsigned*)(lds + (bufoff) + ldsw + _i * 8192), 16, 0, 0); } while (0)
; #define PG8_LDA(dst, b, h) do { _Pragma("unroll") for (int m = 0; m < 4; ++m) _Pragma("unroll") for (int k = 0; k < 2; ++k) dst[m][k] = *(const LAS bf16x8*)(lds + PG8_SA(b, h) + aoff + m * 2048 + k * 1024); } while (0)
; #define PG8_MMA(ai, bj, At, Bt) do { __builtin_amdgcn_s_setprio(1); _Pragma("unroll") for (int m = 0; m < 4; ++m) _Pragma("unroll") for (int n = 0; n < 2; ++n) _Pragma("unroll") for (int k = 0; k < 2; ++k) \
;         acc[ai][bj][m][n] = __builtin_amdgcn_mfma_f32_16x16x32_bf16(Bt[n][k], At[m][k], acc[ai][bj][m][n], 0, 0, 0); __builtin_amdgcn_s_setprio(0); } while (0)
; #define PG8_WAIT_V(n) asm volatile("s_waitcnt vmcnt(" #n ")" ::: "memory")
; #define PG8_WAIT_L(n) asm volatile("s_waitcnt lgkmcnt(" #n ")" ::: "memory")
; #define PG8_BAR __builtin_amdgcn_s_barrier()
; #define PG8_SCHED __builtin_amdgcn_sched_barrier(0)
; template <class Epi, class Sched, bool ALIGN_EPI = true, bool SP2 = true>
; __device__ __forceinline__ void gemm_phase(LAS unsigned char* lds, const Gemm g, const Sched& S, const Epi& E) {
;     ...
;             PG8_LDA(At, 1, 1); PG8_STAGE(PG8_SB(1, 0), b3, voffB); PG8_STAGE(PG8_SB(1, 1), b3 + hstep, voffB); PG8_STAGE(PG8_SA(1, 0), a3, voffA);
;             PG8_WAIT_V(8); PG8_WAIT_L(0); PG8_BAR; PG8_MMA(1, 0, At, B0); PG8_MMA(1, 1, At, B1); PG8_BAR; PG8_SCHED;
;     ...
;         if constexpr (ALIGN_EPI) { if (wr == 0) PG8_BAR; }
	s_add_i32 s70, s72, s16
	v_lshl_add_u64 v[166:167], v[166:167], 0, s[10:11]
	s_mov_b32 m0, s70
	ds_read_b128 v[192:195], v171 offset:49152
	ds_read_b128 v[196:199], v171 offset:50176
	ds_read_b128 v[200:203], v171 offset:51200
	ds_read_b128 v[204:207], v171 offset:52224
	ds_read_b128 v[208:211], v171 offset:53248
	ds_read_b128 v[212:215], v171 offset:54272
	ds_read_b128 v[216:219], v171 offset:55296
	ds_read_b128 v[220:223], v171 offset:56320
	global_load_lds_dwordx4 v[166:167], off
	s_add_i32 m0, s70, 0x2000
	s_add_u32 s68, s68, 0x40080
	v_lshl_add_u64 v[166:167], v[172:173], 0, s[10:11]
	s_addc_u32 s69, s69, 0
	s_add_i32 s70, s73, s16
	global_load_lds_dwordx4 v[166:167], off
	v_lshl_add_u64 v[166:167], s[68:69], 0, v[142:143]
	s_mov_b32 m0, s70
	s_nop 0
	global_load_lds_dwordx4 v[166:167], off
	v_lshl_add_u64 v[166:167], s[68:69], 0, v[146:147]
	s_add_i32 m0, s70, 0x2000
	s_nop 0
	global_load_lds_dwordx4 v[166:167], off
	v_lshl_add_u64 v[166:167], v[224:225], 0, s[10:11]
	s_mov_b32 m0, s25
	s_nop 0
	global_load_lds_dwordx4 v[166:167], off
	v_lshl_add_u64 v[166:167], v[226:227], 0, s[10:11]
	s_mov_b32 m0, s34
	s_nop 0
	global_load_lds_dwordx4 v[166:167], off
	s_waitcnt vmcnt(8)
	s_waitcnt lgkmcnt(0)
	s_barrier
	s_waitcnt lgkmcnt(0)
	v_mfma_f32_16x16x32_bf16 v[60:63], v[128:131], v[192:195], v[60:63]
	v_mfma_f32_16x16x32_bf16 v[56:59], v[136:139], v[192:195], v[56:59]
	v_mfma_f32_16x16x32_bf16 v[48:51], v[128:131], v[200:203], v[48:51]
	v_mfma_f32_16x16x32_bf16 v[40:43], v[136:139], v[200:203], v[40:43]
	v_mfma_f32_16x16x32_bf16 v[36:39], v[128:131], v[208:211], v[36:39]
	v_mfma_f32_16x16x32_bf16 v[28:31], v[136:139], v[208:211], v[28:31]
	v_mfma_f32_16x16x32_bf16 v[20:23], v[128:131], v[216:219], v[20:23]
	v_mfma_f32_16x16x32_bf16 v[12:15], v[136:139], v[216:219], v[12:15]
	v_mfma_f32_16x16x32_bf16 v[60:63], v[132:135], v[196:199], v[60:63]
	v_mfma_f32_16x16x32_bf16 v[56:59], v[156:159], v[196:199], v[56:59]
	v_mfma_f32_16x16x32_bf16 v[48:51], v[132:135], v[204:207], v[48:51]
	v_mfma_f32_16x16x32_bf16 v[40:43], v[156:159], v[204:207], v[40:43]
	v_mfma_f32_16x16x32_bf16 v[36:39], v[132:135], v[212:215], v[36:39]
	v_mfma_f32_16x16x32_bf16 v[28:31], v[156:159], v[212:215], v[28:31]
	v_mfma_f32_16x16x32_bf16 v[20:23], v[132:135], v[220:223], v[20:23]
	v_mfma_f32_16x16x32_bf16 v[12:15], v[156:159], v[220:223], v[12:15]
	v_mfma_f32_16x16x32_bf16 v[52:55], v[176:179], v[192:195], v[52:55]
	v_mfma_f32_16x16x32_bf16 v[44:47], v[184:187], v[192:195], v[44:47]
	v_mfma_f32_16x16x32_bf16 v[32:35], v[176:179], v[200:203], v[32:35]
	v_mfma_f32_16x16x32_bf16 v[24:27], v[184:187], v[200:203], v[24:27]
	v_mfma_f32_16x16x32_bf16 v[16:19], v[176:179], v[208:211], v[16:19]
	v_mfma_f32_16x16x32_bf16 v[8:11], v[184:187], v[208:211], v[8:11]
	v_mfma_f32_16x16x32_bf16 v[4:7], v[176:179], v[216:219], v[4:7]
	v_mfma_f32_16x16x32_bf16 v[0:3], v[184:187], v[216:219], v[0:3]
	v_mfma_f32_16x16x32_bf16 v[52:55], v[180:183], v[196:199], v[52:55]
	v_mfma_f32_16x16x32_bf16 v[44:47], v[188:191], v[196:199], v[44:47]
	v_mfma_f32_16x16x32_bf16 v[32:35], v[180:183], v[204:207], v[32:35]
	v_mfma_f32_16x16x32_bf16 v[24:27], v[188:191], v[204:207], v[24:27]
	v_mfma_f32_16x16x32_bf16 v[16:19], v[180:183], v[212:215], v[16:19]
	v_mfma_f32_16x16x32_bf16 v[8:11], v[188:191], v[212:215], v[8:11]
	v_mfma_f32_16x16x32_bf16 v[4:7], v[180:183], v[220:223], v[4:7]
	v_mfma_f32_16x16x32_bf16 v[0:3], v[188:191], v[220:223], v[0:3]
	s_barrier
	s_add_i32 s63, s63, 2
	s_add_u32 s64, s64, 0x100
	s_addc_u32 s65, s65, 0
	s_add_u32 s55, s55, 0x100
	s_addc_u32 s57, s57, 0
	s_cmp_gt_u32 s63, 13
	s_cbranch_scc0 .LBB0_1012
	s_and_b64 vcc, exec, s[12:13]
	s_cbranch_vccz .LBB0_1015
	s_barrier

; #define PG8_STAGE(bufoff, gbase, voff) do { _Pragma("unroll") for (int _i = 0; _i < 2; ++_i) \
;         __builtin_amdgcn_global_load_lds((const unsigned*)((const char*)(gbase) + (voff)[_i]), (LAS unsigned*)(lds + (bufoff) + ldsw + _i * 8192), 16, 0, 0); } while (0)
; #define PG8_LDA(dst, b, h) do { _Pragma("unroll") for (int m = 0; m < 4; ++m) _Pragma("unroll") for (int k = 0; k < 2; ++k) dst[m][k] = *(const LAS bf16x8*)(lds + PG8_SA(b, h) + aoff + m * 2048 + k * 1024); } while (0)
; #define PG8_LDB(dst, b, h) do { _Pragma("unroll") for (int n = 0; n < 2; ++n) _Pragma("unroll") for (int k = 0; k < 2; ++k) dst[n][k] = *(const LAS bf16x8*)(lds + PG8_SB(b, h) + boff + n * 2048 + k * 1024); } while (0)
; #define PG8_MMA(ai, bj, At, Bt) do { __builtin_amdgcn_s_setprio(1); _Pragma("unroll") for (int m = 0; m < 4; ++m) _Pragma("unroll") for (int n = 0; n < 2; ++n) _Pragma("unroll") for (int k = 0; k < 2; ++k) \
;         acc[ai][bj][m][n] = __builtin_amdgcn_mfma_f32_16x16x32_bf16(Bt[n][k], At[m][k], acc[ai][bj][m][n], 0, 0, 0); __builtin_amdgcn_s_setprio(0); } while (0)
; #define PG8_WAIT_V(n) asm volatile("s_waitcnt vmcnt(" #n ")" ::: "memory")
; #define PG8_WAIT_L(n) asm volatile("s_waitcnt lgkmcnt(" #n ")" ::: "memory")
; #define PG8_BAR __builtin_amdgcn_s_barrier()
; #define PG8_SCHED __builtin_amdgcn_sched_barrier(0)
; template <class Epi, class Sched, bool ALIGN_EPI = true, bool SP2 = true>
; __device__ __forceinline__ void gemm_phase(LAS unsigned char* lds, const Gemm g, const Sched& S, const Epi& E) {
;     ...
;             const bool last = (t == nt - 2);
;             const char* a1 = cA + (size_t)(t + 1) * kstep;
;             const char* a2 = last ? nA : cA + (size_t)(t + 2) * kstep; const char* b2 = last ? nB : cB + (size_t)(t + 2) * kstep;
;             const char* a3 = a2 + kstep; const char* b3 = b2 + kstep;
;             if constexpr (SP2) {
;             PG8_LDB(B0, 0, 0); PG8_LDB(B1, 0, 1); PG8_SCHED; PG8_LDA(At, 0, 0); PG8_STAGE(PG8_SA(1, 1), a1 + hstep, voffA);
;             PG8_WAIT_V(8); PG8_WAIT_L(0); PG8_BAR; PG8_MMA(0, 0, At, B0); PG8_MMA(0, 1, At, B1); PG8_BAR; PG8_SCHED;
;             PG8_LDA(At, 0, 1); PG8_STAGE(PG8_SB(0, 0), b2, voffB); PG8_STAGE(PG8_SB(0, 1), b2 + hstep, voffB); PG8_STAGE(PG8_SA(0, 0), a2, voffA);
;             PG8_WAIT_V(8); PG8_WAIT_L(0); PG8_BAR; PG8_MMA(1, 0, At, B0); PG8_MMA(1, 1, At, B1); PG8_BAR; PG8_SCHED;
.LBB0_1037:
	ds_read_b128 v[144:147], v153
	ds_read_b128 v[156:159], v153 offset:1024
	ds_read_b128 v[166:169], v153 offset:2048
	ds_read_b128 v[170:173], v153 offset:3072
	ds_read_b128 v[176:179], v154
	ds_read_b128 v[180:183], v154 offset:1024
	ds_read_b128 v[184:187], v154 offset:2048
	ds_read_b128 v[188:191], v154 offset:3072
	s_add_u32 s59, s70, 0xfffc0080
	s_addc_u32 s61, s71, -1
	s_cmp_eq_u32 s49, 12
	s_cselect_b32 s75, s43, s61
	s_cselect_b32 s74, s44, s59
	s_cselect_b32 s73, s45, s48
	s_cselect_b32 s72, s46, s47
	v_lshl_add_u64 v[148:149], s[70:71], 0, v[136:137]
	s_add_i32 m0, s17, 0xc000
	ds_read_b128 v[192:195], v155
	ds_read_b128 v[196:199], v155 offset:1024
	ds_read_b128 v[200:203], v155 offset:2048
	ds_read_b128 v[204:207], v155 offset:3072
	ds_read_b128 v[208:211], v155 offset:4096
	ds_read_b128 v[212:215], v155 offset:5120
	ds_read_b128 v[216:219], v155 offset:6144
	ds_read_b128 v[220:223], v155 offset:7168
	global_load_lds_dwordx4 v[148:149], off
	v_lshl_add_u64 v[148:149], s[70:71], 0, v[138:139]
	s_add_i32 m0, s17, 0xe000
	s_nop 0
	global_load_lds_dwordx4 v[148:149], off
	s_waitcnt vmcnt(8)
	s_waitcnt lgkmcnt(0)
	s_barrier
	s_waitcnt lgkmcnt(0)
	v_mfma_f32_16x16x32_bf16 v[124:127], v[144:147], v[192:195], v[124:127]
	v_mfma_f32_16x16x32_bf16 v[120:123], v[166:169], v[192:195], v[120:123]
	v_mfma_f32_16x16x32_bf16 v[108:111], v[144:147], v[200:203], v[108:111]
	v_mfma_f32_16x16x32_bf16 v[104:107], v[166:169], v[200:203], v[104:107]
	v_mfma_f32_16x16x32_bf16 v[92:95], v[144:147], v[208:211], v[92:95]
	v_mfma_f32_16x16x32_bf16 v[88:91], v[166:169], v[208:211], v[88:91]
	v_mfma_f32_16x16x32_bf16 v[76:79], v[144:147], v[216:219], v[76:79]
	v_mfma_f32_16x16x32_bf16 v[72:75], v[166:169], v[216:219], v[72:75]
	v_mfma_f32_16x16x32_bf16 v[124:127], v[156:159], v[196:199], v[124:127]
	v_mfma_f32_16x16x32_bf16 v[120:123], v[170:173], v[196:199], v[120:123]
	v_mfma_f32_16x16x32_bf16 v[108:111], v[156:159], v[204:207], v[108:111]
	v_mfma_f32_16x16x32_bf16 v[104:107], v[170:173], v[204:207], v[104:107]
	v_mfma_f32_16x16x32_bf16 v[92:95], v[156:159], v[212:215], v[92:95]
	v_mfma_f32_16x16x32_bf16 v[88:91], v[170:173], v[212:215], v[88:91]
	v_mfma_f32_16x16x32_bf16 v[76:79], v[156:159], v[220:223], v[76:79]
	v_mfma_f32_16x16x32_bf16 v[72:75], v[170:173], v[220:223], v[72:75]
	v_mfma_f32_16x16x32_bf16 v[116:119], v[176:179], v[192:195], v[116:119]
	v_mfma_f32_16x16x32_bf16 v[112:115], v[184:187], v[192:195], v[112:115]
	v_mfma_f32_16x16x32_bf16 v[100:103], v[176:179], v[200:203], v[100:103]
	v_mfma_f32_16x16x32_bf16 v[96:99], v[184:187], v[200:203], v[96:99]
	v_mfma_f32_16x16x32_bf16 v[84:87], v[176:179], v[208:211], v[84:87]
	v_mfma_f32_16x16x32_bf16 v[80:83], v[184:187], v[208:211], v[80:83]
	v_mfma_f32_16x16x32_bf16 v[68:71], v[176:179], v[216:219], v[68:71]
	v_mfma_f32_16x16x32_bf16 v[64:67], v[184:187], v[216:219], v[64:67]
	v_mfma_f32_16x16x32_bf16 v[116:119], v[180:183], v[196:199], v[116:119]
	v_mfma_f32_16x16x32_bf16 v[112:115], v[188:191], v[196:199], v[112:115]
	v_mfma_f32_16x16x32_bf16 v[100:103], v[180:183], v[204:207], v[100:103]
	v_mfma_f32_16x16x32_bf16 v[96:99], v[188:191], v[204:207], v[96:99]
	v_mfma_f32_16x16x32_bf16 v[84:87], v[180:183], v[212:215], v[84:87]
	v_mfma_f32_16x16x32_bf16 v[80:83], v[188:191], v[212:215], v[80:83]
	v_mfma_f32_16x16x32_bf16 v[68:71], v[180:183], v[220:223], v[68:71]
	v_mfma_f32_16x16x32_bf16 v[64:67], v[188:191], v[220:223], v[64:67]
	s_barrier
	s_add_i32 s59, s38, s16
	v_lshl_add_u64 v[148:149], s[72:73], 0, v[130:131]
	s_mov_b32 m0, s59
	ds_read_b128 v[192:195], v155 offset:16384
	ds_read_b128 v[196:199], v155 offset:17408
	ds_read_b128 v[200:203], v155 offset:18432
	ds_read_b128 v[204:207], v155 offset:19456
	ds_read_b128 v[208:211], v155 offset:20480
	ds_read_b128 v[212:215], v155 offset:21504
	ds_read_b128 v[216:219], v155 offset:22528
	ds_read_b128 v[220:223], v155 offset:23552
	global_load_lds_dwordx4 v[148:149], off
	s_add_i32 m0, s59, 0x2000
	s_add_u32 s78, s72, 0x40000
	v_lshl_add_u64 v[224:225], s[72:73], 0, v[134:135]
	s_addc_u32 s79, s73, 0
	s_add_i32 s59, s39, s16
	global_load_lds_dwordx4 v[224:225], off
	v_lshl_add_u64 v[226:227], s[78:79], 0, v[130:131]
	s_mov_b32 m0, s59
	v_lshl_add_u64 v[228:229], s[74:75], 0, v[132:133]
	global_load_lds_dwordx4 v[226:227], off
	v_lshl_add_u64 v[226:227], s[78:79], 0, v[134:135]
	s_add_i32 m0, s59, 0x2000
	s_nop 0
	global_load_lds_dwordx4 v[226:227], off
	v_lshl_add_u64 v[226:227], s[74:75], 0, v[128:129]
	s_mov_b32 m0, s17
	s_nop 0
	global_load_lds_dwordx4 v[226:227], off
	s_mov_b32 m0, s18
	s_nop 0
	global_load_lds_dwordx4 v[228:229], off
	s_waitcnt vmcnt(8)
	s_waitcnt lgkmcnt(0)
	s_barrier
; #define PG8_STAGE(bufoff, gbase, voff) do { _Pragma("unroll") for (int _i = 0; _i < 2; ++_i) \
;         __builtin_amdgcn_global_load_lds((const unsigned*)((const char*)(gbase) + (voff)[_i]), (LAS unsigned*)(lds + (bufoff) + ldsw + _i * 8192), 16, 0, 0); } while (0)
; #define PG8_LDA(dst, b, h) do { _Pragma("unroll") for (int m = 0; m < 4; ++m) _Pragma("unroll") for (int k = 0; k < 2; ++k) dst[m][k] = *(const LAS bf16x8*)(lds + PG8_SA(b, h) + aoff + m * 2048 + k * 1024); } while (0)
; #define PG8_LDB(dst, b, h) do { _Pragma("unroll") for (int n = 0; n < 2; ++n) _Pragma("unroll") for (int k = 0; k < 2; ++k) dst[n][k] = *(const LAS bf16x8*)(lds + PG8_SB(b, h) + boff + n * 2048 + k * 1024); } while (0)
; #define PG8_MMA(ai, bj, At, Bt) do { __builtin_amdgcn_s_setprio(1); _Pragma("unroll") for (int m = 0; m < 4; ++m) _Pragma("unroll") for (int n = 0; n < 2; ++n) _Pragma("unroll") for (int k = 0; k < 2; ++k) \
;         acc[ai][bj][m][n] = __builtin_amdgcn_mfma_f32_16x16x32_bf16(Bt[n][k], At[m][k], acc[ai][bj][m][n], 0, 0, 0); __builtin_amdgcn_s_setprio(0); } while (0)
; #define PG8_WAIT_V(n) asm volatile("s_waitcnt vmcnt(" #n ")" ::: "memory")
; #define PG8_WAIT_L(n) asm volatile("s_waitcnt lgkmcnt(" #n ")" ::: "memory")
; #define PG8_BAR __builtin_amdgcn_s_barrier()
; #define PG8_SCHED __builtin_amdgcn_sched_barrier(0)
; template <class Epi, class Sched, bool ALIGN_EPI = true, bool SP2 = true>
; __device__ __forceinline__ void gemm_phase(LAS unsigned char* lds, const Gemm g, const Sched& S, const Epi& E) {
;     ...
;             PG8_WAIT_V(8); PG8_WAIT_L(0); PG8_BAR; PG8_MMA(1, 0, At, B0); PG8_MMA(1, 1, At, B1); PG8_BAR; PG8_SCHED;
;             PG8_LDB(B0, 1, 0); PG8_LDB(B1, 1, 1); PG8_SCHED; PG8_LDA(At, 1, 0); PG8_STAGE(PG8_SA(0, 1), a2 + hstep, voffA);
;             PG8_WAIT_V(8); PG8_WAIT_L(0); PG8_BAR; PG8_MMA(0, 0, At, B0); PG8_MMA(0, 1, At, B1); PG8_BAR; PG8_SCHED;
	s_waitcnt lgkmcnt(0)
	v_mfma_f32_16x16x32_bf16 v[60:63], v[144:147], v[192:195], v[60:63]
	v_mfma_f32_16x16x32_bf16 v[56:59], v[166:169], v[192:195], v[56:59]
	v_mfma_f32_16x16x32_bf16 v[44:47], v[144:147], v[200:203], v[44:47]
	v_mfma_f32_16x16x32_bf16 v[40:43], v[166:169], v[200:203], v[40:43]
	v_mfma_f32_16x16x32_bf16 v[28:31], v[144:147], v[208:211], v[28:31]
	v_mfma_f32_16x16x32_bf16 v[24:27], v[166:169], v[208:211], v[24:27]
	v_mfma_f32_16x16x32_bf16 v[12:15], v[144:147], v[216:219], v[12:15]
	v_mfma_f32_16x16x32_bf16 v[8:11], v[166:169], v[216:219], v[8:11]
	v_mfma_f32_16x16x32_bf16 v[60:63], v[156:159], v[196:199], v[60:63]
	v_mfma_f32_16x16x32_bf16 v[56:59], v[170:173], v[196:199], v[56:59]
	v_mfma_f32_16x16x32_bf16 v[44:47], v[156:159], v[204:207], v[44:47]
	v_mfma_f32_16x16x32_bf16 v[40:43], v[170:173], v[204:207], v[40:43]
	v_mfma_f32_16x16x32_bf16 v[28:31], v[156:159], v[212:215], v[28:31]
	v_mfma_f32_16x16x32_bf16 v[24:27], v[170:173], v[212:215], v[24:27]
	v_mfma_f32_16x16x32_bf16 v[12:15], v[156:159], v[220:223], v[12:15]
	v_mfma_f32_16x16x32_bf16 v[8:11], v[170:173], v[220:223], v[8:11]
	v_mfma_f32_16x16x32_bf16 v[52:55], v[176:179], v[192:195], v[52:55]
	v_mfma_f32_16x16x32_bf16 v[48:51], v[184:187], v[192:195], v[48:51]
	v_mfma_f32_16x16x32_bf16 v[36:39], v[176:179], v[200:203], v[36:39]
	v_mfma_f32_16x16x32_bf16 v[32:35], v[184:187], v[200:203], v[32:35]
	v_mfma_f32_16x16x32_bf16 v[20:23], v[176:179], v[208:211], v[20:23]
	v_mfma_f32_16x16x32_bf16 v[16:19], v[184:187], v[208:211], v[16:19]
	v_mfma_f32_16x16x32_bf16 v[4:7], v[176:179], v[216:219], v[4:7]
	v_mfma_f32_16x16x32_bf16 v[0:3], v[184:187], v[216:219], v[0:3]
	v_mfma_f32_16x16x32_bf16 v[52:55], v[180:183], v[196:199], v[52:55]
	v_mfma_f32_16x16x32_bf16 v[48:51], v[188:191], v[196:199], v[48:51]
	v_mfma_f32_16x16x32_bf16 v[36:39], v[180:183], v[204:207], v[36:39]
	v_mfma_f32_16x16x32_bf16 v[32:35], v[188:191], v[204:207], v[32:35]
	v_mfma_f32_16x16x32_bf16 v[20:23], v[180:183], v[212:215], v[20:23]
	v_mfma_f32_16x16x32_bf16 v[16:19], v[188:191], v[212:215], v[16:19]
	v_mfma_f32_16x16x32_bf16 v[4:7], v[180:183], v[220:223], v[4:7]
	v_mfma_f32_16x16x32_bf16 v[0:3], v[188:191], v[220:223], v[0:3]
	s_barrier
	s_add_i32 s59, 0, 0x18000
	v_add_u32_e32 v163, s59, v151
	s_add_i32 s61, 0, 0x1c000
	ds_read_b128 v[144:147], v163
	ds_read_b128 v[156:159], v163 offset:1024
	ds_read_b128 v[166:169], v163 offset:2048
	ds_read_b128 v[170:173], v163 offset:3072
	v_add_u32_e32 v163, s61, v151
	ds_read_b128 v[176:179], v163
	ds_read_b128 v[180:183], v163 offset:1024
	ds_read_b128 v[184:187], v163 offset:2048
	ds_read_b128 v[188:191], v163 offset:3072
	s_add_u32 s74, s74, 0x40000
	s_addc_u32 s75, s75, 0
	s_mov_b32 m0, s19
	v_lshl_add_u64 v[230:231], s[74:75], 0, v[128:129]
	ds_read_b128 v[192:195], v155 offset:32768
	ds_read_b128 v[196:199], v155 offset:33792
	ds_read_b128 v[200:203], v155 offset:34816
	ds_read_b128 v[204:207], v155 offset:35840
	ds_read_b128 v[208:211], v155 offset:36864
	ds_read_b128 v[212:215], v155 offset:37888
	ds_read_b128 v[216:219], v155 offset:38912
	ds_read_b128 v[220:223], v155 offset:39936
	global_load_lds_dwordx4 v[230:231], off
	v_lshl_add_u64 v[230:231], s[74:75], 0, v[132:133]
	s_mov_b32 m0, s21
	s_nop 0
	global_load_lds_dwordx4 v[230:231], off
	s_waitcnt vmcnt(8)
	s_waitcnt lgkmcnt(0)
	s_barrier
	s_waitcnt lgkmcnt(0)
	v_mfma_f32_16x16x32_bf16 v[124:127], v[144:147], v[192:195], v[124:127]
	v_mfma_f32_16x16x32_bf16 v[120:123], v[166:169], v[192:195], v[120:123]
	v_mfma_f32_16x16x32_bf16 v[108:111], v[144:147], v[200:203], v[108:111]
	v_mfma_f32_16x16x32_bf16 v[104:107], v[166:169], v[200:203], v[104:107]
	v_mfma_f32_16x16x32_bf16 v[92:95], v[144:147], v[208:211], v[92:95]
	v_mfma_f32_16x16x32_bf16 v[88:91], v[166:169], v[208:211], v[88:91]
	v_mfma_f32_16x16x32_bf16 v[76:79], v[144:147], v[216:219], v[76:79]
	v_mfma_f32_16x16x32_bf16 v[72:75], v[166:169], v[216:219], v[72:75]
	v_mfma_f32_16x16x32_bf16 v[124:127], v[156:159], v[196:199], v[124:127]
	v_mfma_f32_16x16x32_bf16 v[120:123], v[170:173], v[196:199], v[120:123]
	v_mfma_f32_16x16x32_bf16 v[108:111], v[156:159], v[204:207], v[108:111]
	v_mfma_f32_16x16x32_bf16 v[104:107], v[170:173], v[204:207], v[104:107]
	v_mfma_f32_16x16x32_bf16 v[92:95], v[156:159], v[212:215], v[92:95]
	v_mfma_f32_16x16x32_bf16 v[88:91], v[170:173], v[212:215], v[88:91]
	v_mfma_f32_16x16x32_bf16 v[76:79], v[156:159], v[220:223], v[76:79]
	v_mfma_f32_16x16x32_bf16 v[72:75], v[170:173], v[220:223], v[72:75]
	v_mfma_f32_16x16x32_bf16 v[116:119], v[176:179], v[192:195], v[116:119]
	v_mfma_f32_16x16x32_bf16 v[112:115], v[184:187], v[192:195], v[112:115]
	v_mfma_f32_16x16x32_bf16 v[100:103], v[176:179], v[200:203], v[100:103]
	v_mfma_f32_16x16x32_bf16 v[96:99], v[184:187], v[200:203], v[96:99]
	v_mfma_f32_16x16x32_bf16 v[84:87], v[176:179], v[208:211], v[84:87]
	v_mfma_f32_16x16x32_bf16 v[80:83], v[184:187], v[208:211], v[80:83]
	v_mfma_f32_16x16x32_bf16 v[68:71], v[176:179], v[216:219], v[68:71]
	v_mfma_f32_16x16x32_bf16 v[64:67], v[184:187], v[216:219], v[64:67]
	v_mfma_f32_16x16x32_bf16 v[116:119], v[180:183], v[196:199], v[116:119]
	v_mfma_f32_16x16x32_bf16 v[112:115], v[188:191], v[196:199], v[112:115]
	v_mfma_f32_16x16x32_bf16 v[100:103], v[180:183], v[204:207], v[100:103]
	v_mfma_f32_16x16x32_bf16 v[96:99], v[188:191], v[204:207], v[96:99]
	v_mfma_f32_16x16x32_bf16 v[84:87], v[180:183], v[212:215], v[84:87]
	v_mfma_f32_16x16x32_bf16 v[80:83], v[188:191], v[212:215], v[80:83]
	v_mfma_f32_16x16x32_bf16 v[68:71], v[180:183], v[220:223], v[68:71]
	v_mfma_f32_16x16x32_bf16 v[64:67], v[188:191], v[220:223], v[64:67]
	s_barrier
; #define PG8_STAGE(bufoff, gbase, voff) do { _Pragma("unroll") for (int _i = 0; _i < 2; ++_i) \
;         __builtin_amdgcn_global_load_lds((const unsigned*)((const char*)(gbase) + (voff)[_i]), (LAS unsigned*)(lds + (bufoff) + ldsw + _i * 8192), 16, 0, 0); } while (0)
; #define PG8_LDA(dst, b, h) do { _Pragma("unroll") for (int m = 0; m < 4; ++m) _Pragma("unroll") for (int k = 0; k < 2; ++k) dst[m][k] = *(const LAS bf16x8*)(lds + PG8_SA(b, h) + aoff + m * 2048 + k * 1024); } while (0)
; #define PG8_MMA(ai, bj, At, Bt) do { __builtin_amdgcn_s_setprio(1); _Pragma("unroll") for (int m = 0; m < 4; ++m) _Pragma("unroll") for (int n = 0; n < 2; ++n) _Pragma("unroll") for (int k = 0; k < 2; ++k) \
;         acc[ai][bj][m][n] = __builtin_amdgcn_mfma_f32_16x16x32_bf16(Bt[n][k], At[m][k], acc[ai][bj][m][n], 0, 0, 0); __builtin_amdgcn_s_setprio(0); } while (0)
; #define PG8_WAIT_V(n) asm volatile("s_waitcnt vmcnt(" #n ")" ::: "memory")
; #define PG8_WAIT_L(n) asm volatile("s_waitcnt lgkmcnt(" #n ")" ::: "memory")
; #define PG8_BAR __builtin_amdgcn_s_barrier()
; #define PG8_SCHED __builtin_amdgcn_sched_barrier(0)
; template <class Epi, class Sched, bool ALIGN_EPI = true, bool SP2 = true>
; __device__ __forceinline__ void gemm_phase(LAS unsigned char* lds, const Gemm g, const Sched& S, const Epi& E) {
;     ...
;             PG8_LDA(At, 1, 1); PG8_STAGE(PG8_SB(1, 0), b3, voffB); PG8_STAGE(PG8_SB(1, 1), b3 + hstep, voffB); PG8_STAGE(PG8_SA(1, 0), a3, voffA);
;             PG8_WAIT_V(8); PG8_WAIT_L(0); PG8_BAR; PG8_MMA(1, 0, At, B0); PG8_MMA(1, 1, At, B1); PG8_BAR; PG8_SCHED;
;     ...
;         if constexpr (ALIGN_EPI) { if (wr == 0) PG8_BAR; }
	s_add_i32 s59, s59, s16
	v_lshl_add_u64 v[148:149], v[148:149], 0, s[12:13]
	s_mov_b32 m0, s59
	ds_read_b128 v[192:195], v155 offset:49152
	ds_read_b128 v[196:199], v155 offset:50176
	ds_read_b128 v[200:203], v155 offset:51200
	ds_read_b128 v[204:207], v155 offset:52224
	ds_read_b128 v[208:211], v155 offset:53248
	ds_read_b128 v[212:215], v155 offset:54272
	ds_read_b128 v[216:219], v155 offset:55296
	ds_read_b128 v[220:223], v155 offset:56320
	global_load_lds_dwordx4 v[148:149], off
	s_add_i32 m0, s59, 0x2000
	s_add_u32 s72, s72, 0x40080
	v_lshl_add_u64 v[148:149], v[224:225], 0, s[12:13]
	s_addc_u32 s73, s73, 0
	s_add_i32 s59, s61, s16
	global_load_lds_dwordx4 v[148:149], off
	v_lshl_add_u64 v[148:149], s[72:73], 0, v[130:131]
	s_mov_b32 m0, s59
	s_nop 0
	global_load_lds_dwordx4 v[148:149], off
	v_lshl_add_u64 v[148:149], s[72:73], 0, v[134:135]
	s_add_i32 m0, s59, 0x2000
	s_nop 0
	global_load_lds_dwordx4 v[148:149], off
	v_lshl_add_u64 v[148:149], v[226:227], 0, s[12:13]
	s_mov_b32 m0, s24
	s_nop 0
	global_load_lds_dwordx4 v[148:149], off
	v_lshl_add_u64 v[148:149], v[228:229], 0, s[12:13]
	s_mov_b32 m0, s25
	s_nop 0
	global_load_lds_dwordx4 v[148:149], off
	s_waitcnt vmcnt(8)
	s_waitcnt lgkmcnt(0)
	s_barrier
	s_waitcnt lgkmcnt(0)
	v_mfma_f32_16x16x32_bf16 v[60:63], v[144:147], v[192:195], v[60:63]
	v_mfma_f32_16x16x32_bf16 v[56:59], v[166:169], v[192:195], v[56:59]
	v_mfma_f32_16x16x32_bf16 v[44:47], v[144:147], v[200:203], v[44:47]
	v_mfma_f32_16x16x32_bf16 v[40:43], v[166:169], v[200:203], v[40:43]
	v_mfma_f32_16x16x32_bf16 v[28:31], v[144:147], v[208:211], v[28:31]
	v_mfma_f32_16x16x32_bf16 v[24:27], v[166:169], v[208:211], v[24:27]
	v_mfma_f32_16x16x32_bf16 v[12:15], v[144:147], v[216:219], v[12:15]
	v_mfma_f32_16x16x32_bf16 v[8:11], v[166:169], v[216:219], v[8:11]
	v_mfma_f32_16x16x32_bf16 v[60:63], v[156:159], v[196:199], v[60:63]
	v_mfma_f32_16x16x32_bf16 v[56:59], v[170:173], v[196:199], v[56:59]
	v_mfma_f32_16x16x32_bf16 v[44:47], v[156:159], v[204:207], v[44:47]
	v_mfma_f32_16x16x32_bf16 v[40:43], v[170:173], v[204:207], v[40:43]
	v_mfma_f32_16x16x32_bf16 v[28:31], v[156:159], v[212:215], v[28:31]
	v_mfma_f32_16x16x32_bf16 v[24:27], v[170:173], v[212:215], v[24:27]
	v_mfma_f32_16x16x32_bf16 v[12:15], v[156:159], v[220:223], v[12:15]
	v_mfma_f32_16x16x32_bf16 v[8:11], v[170:173], v[220:223], v[8:11]
	v_mfma_f32_16x16x32_bf16 v[52:55], v[176:179], v[192:195], v[52:55]
	v_mfma_f32_16x16x32_bf16 v[48:51], v[184:187], v[192:195], v[48:51]
	v_mfma_f32_16x16x32_bf16 v[36:39], v[176:179], v[200:203], v[36:39]
	v_mfma_f32_16x16x32_bf16 v[32:35], v[184:187], v[200:203], v[32:35]
	v_mfma_f32_16x16x32_bf16 v[20:23], v[176:179], v[208:211], v[20:23]
	v_mfma_f32_16x16x32_bf16 v[16:19], v[184:187], v[208:211], v[16:19]
	v_mfma_f32_16x16x32_bf16 v[4:7], v[176:179], v[216:219], v[4:7]
	v_mfma_f32_16x16x32_bf16 v[0:3], v[184:187], v[216:219], v[0:3]
	v_mfma_f32_16x16x32_bf16 v[52:55], v[180:183], v[196:199], v[52:55]
	v_mfma_f32_16x16x32_bf16 v[48:51], v[188:191], v[196:199], v[48:51]
	v_mfma_f32_16x16x32_bf16 v[36:39], v[180:183], v[204:207], v[36:39]
	v_mfma_f32_16x16x32_bf16 v[32:35], v[188:191], v[204:207], v[32:35]
	v_mfma_f32_16x16x32_bf16 v[20:23], v[180:183], v[212:215], v[20:23]
	v_mfma_f32_16x16x32_bf16 v[16:19], v[188:191], v[212:215], v[16:19]
	v_mfma_f32_16x16x32_bf16 v[4:7], v[180:183], v[220:223], v[4:7]
	v_mfma_f32_16x16x32_bf16 v[0:3], v[188:191], v[220:223], v[0:3]
	s_barrier
	s_add_i32 s49, s49, 2
	s_add_u32 s70, s70, 0x100
	s_addc_u32 s71, s71, 0
	s_add_u32 s47, s47, 0x100
	s_addc_u32 s48, s48, 0
	s_cmp_gt_u32 s49, 13
	s_cbranch_scc0 .LBB0_1037
	s_and_b64 vcc, exec, s[14:15]
	s_cbranch_vccz .LBB0_1040
	s_barrier

; #define PG8_STAGE(bufoff, gbase, voff) do { _Pragma("unroll") for (int _i = 0; _i < 2; ++_i) \
;         __builtin_amdgcn_global_load_lds((const unsigned*)((const char*)(gbase) + (voff)[_i]), (LAS unsigned*)(lds + (bufoff) + ldsw + _i * 8192), 16, 0, 0); } while (0)
; #define PG8_LDA(dst, b, h) do { _Pragma("unroll") for (int m = 0; m < 4; ++m) _Pragma("unroll") for (int k = 0; k < 2; ++k) dst[m][k] = *(const LAS bf16x8*)(lds + PG8_SA(b, h) + aoff + m * 2048 + k * 1024); } while (0)
; #define PG8_LDB(dst, b, h) do { _Pragma("unroll") for (int n = 0; n < 2; ++n) _Pragma("unroll") for (int k = 0; k < 2; ++k) dst[n][k] = *(const LAS bf16x8*)(lds + PG8_SB(b, h) + boff + n * 2048 + k * 1024); } while (0)
; #define PG8_MMA(ai, bj, At, Bt) do { __builtin_amdgcn_s_setprio(1); _Pragma("unroll") for (int m = 0; m < 4; ++m) _Pragma("unroll") for (int n = 0; n < 2; ++n) _Pragma("unroll") for (int k = 0; k < 2; ++k) \
;         acc[ai][bj][m][n] = __builtin_amdgcn_mfma_f32_16x16x32_bf16(Bt[n][k], At[m][k], acc[ai][bj][m][n], 0, 0, 0); __builtin_amdgcn_s_setprio(0); } while (0)
; #define PG8_WAIT_V(n) asm volatile("s_waitcnt vmcnt(" #n ")" ::: "memory")
; #define PG8_WAIT_L(n) asm volatile("s_waitcnt lgkmcnt(" #n ")" ::: "memory")
; #define PG8_BAR __builtin_amdgcn_s_barrier()
; #define PG8_SCHED __builtin_amdgcn_sched_barrier(0)
; template <class Epi, class Sched, bool ALIGN_EPI = true, bool SP2 = true>
; __device__ __forceinline__ void gemm_phase(LAS unsigned char* lds, const Gemm g, const Sched& S, const Epi& E) {
;     ...
;             const bool last = (t == nt - 2);
;             const char* a1 = cA + (size_t)(t + 1) * kstep;
;             const char* a2 = last ? nA : cA + (size_t)(t + 2) * kstep; const char* b2 = last ? nB : cB + (size_t)(t + 2) * kstep;
;             const char* a3 = a2 + kstep; const char* b3 = b2 + kstep;
;             if constexpr (SP2) {
;             PG8_LDB(B0, 0, 0); PG8_LDB(B1, 0, 1); PG8_SCHED; PG8_LDA(At, 0, 0); PG8_STAGE(PG8_SA(1, 1), a1 + hstep, voffA);
;             PG8_WAIT_V(8); PG8_WAIT_L(0); PG8_BAR; PG8_MMA(0, 0, At, B0); PG8_MMA(0, 1, At, B1); PG8_BAR; PG8_SCHED;
;             PG8_LDA(At, 0, 1); PG8_STAGE(PG8_SB(0, 0), b2, voffB); PG8_STAGE(PG8_SB(0, 1), b2 + hstep, voffB); PG8_STAGE(PG8_SA(0, 0), a2, voffA);
;             PG8_WAIT_V(8); PG8_WAIT_L(0); PG8_BAR; PG8_MMA(1, 0, At, B0); PG8_MMA(1, 1, At, B1); PG8_BAR; PG8_SCHED;
.LBB0_1113:
	ds_read_b128 v[150:153], v147
	ds_read_b128 v[154:157], v147 offset:1024
	ds_read_b128 v[166:169], v147 offset:2048
	ds_read_b128 v[170:173], v147 offset:3072
	ds_read_b128 v[176:179], v148
	ds_read_b128 v[180:183], v148 offset:1024
	ds_read_b128 v[184:187], v148 offset:2048
	ds_read_b128 v[188:191], v148 offset:3072
	s_add_u32 s68, s64, 0xfffc0080
	s_addc_u32 s69, s65, -1
	s_cmp_eq_u32 s74, 12
	s_cselect_b32 s71, s49, s69
	s_cselect_b32 s70, s55, s68
	s_cselect_b32 s69, s57, s73
	s_cselect_b32 s68, s59, s72
	v_lshl_add_u64 v[158:159], s[64:65], 0, v[136:137]
	s_add_i32 m0, s17, 0xc000
	ds_read_b128 v[192:195], v149
	ds_read_b128 v[196:199], v149 offset:1024
	ds_read_b128 v[200:203], v149 offset:2048
	ds_read_b128 v[204:207], v149 offset:3072
	ds_read_b128 v[208:211], v149 offset:4096
	ds_read_b128 v[212:215], v149 offset:5120
	ds_read_b128 v[216:219], v149 offset:6144
	ds_read_b128 v[220:223], v149 offset:7168
	global_load_lds_dwordx4 v[158:159], off
	v_lshl_add_u64 v[158:159], s[64:65], 0, v[138:139]
	s_add_i32 m0, s17, 0xe000
	s_nop 0
	global_load_lds_dwordx4 v[158:159], off
	s_waitcnt vmcnt(8)
	s_waitcnt lgkmcnt(0)
	s_barrier
	s_waitcnt lgkmcnt(0)
	v_mfma_f32_16x16x32_bf16 v[124:127], v[150:153], v[192:195], v[124:127]
	v_mfma_f32_16x16x32_bf16 v[120:123], v[166:169], v[192:195], v[120:123]
	v_mfma_f32_16x16x32_bf16 v[116:119], v[150:153], v[200:203], v[116:119]
	v_mfma_f32_16x16x32_bf16 v[112:115], v[166:169], v[200:203], v[112:115]
	v_mfma_f32_16x16x32_bf16 v[100:103], v[150:153], v[208:211], v[100:103]
	v_mfma_f32_16x16x32_bf16 v[96:99], v[166:169], v[208:211], v[96:99]
	v_mfma_f32_16x16x32_bf16 v[84:87], v[150:153], v[216:219], v[84:87]
	v_mfma_f32_16x16x32_bf16 v[80:83], v[166:169], v[216:219], v[80:83]
	v_mfma_f32_16x16x32_bf16 v[124:127], v[154:157], v[196:199], v[124:127]
	v_mfma_f32_16x16x32_bf16 v[120:123], v[170:173], v[196:199], v[120:123]
	v_mfma_f32_16x16x32_bf16 v[116:119], v[154:157], v[204:207], v[116:119]
	v_mfma_f32_16x16x32_bf16 v[112:115], v[170:173], v[204:207], v[112:115]
	v_mfma_f32_16x16x32_bf16 v[100:103], v[154:157], v[212:215], v[100:103]
	v_mfma_f32_16x16x32_bf16 v[96:99], v[170:173], v[212:215], v[96:99]
	v_mfma_f32_16x16x32_bf16 v[84:87], v[154:157], v[220:223], v[84:87]
	v_mfma_f32_16x16x32_bf16 v[80:83], v[170:173], v[220:223], v[80:83]
	v_mfma_f32_16x16x32_bf16 v[108:111], v[176:179], v[192:195], v[108:111]
	v_mfma_f32_16x16x32_bf16 v[104:107], v[184:187], v[192:195], v[104:107]
	v_mfma_f32_16x16x32_bf16 v[92:95], v[176:179], v[200:203], v[92:95]
	v_mfma_f32_16x16x32_bf16 v[88:91], v[184:187], v[200:203], v[88:91]
	v_mfma_f32_16x16x32_bf16 v[76:79], v[176:179], v[208:211], v[76:79]
	v_mfma_f32_16x16x32_bf16 v[72:75], v[184:187], v[208:211], v[72:75]
	v_mfma_f32_16x16x32_bf16 v[68:71], v[176:179], v[216:219], v[68:71]
	v_mfma_f32_16x16x32_bf16 v[64:67], v[184:187], v[216:219], v[64:67]
	v_mfma_f32_16x16x32_bf16 v[108:111], v[180:183], v[196:199], v[108:111]
	v_mfma_f32_16x16x32_bf16 v[104:107], v[188:191], v[196:199], v[104:107]
	v_mfma_f32_16x16x32_bf16 v[92:95], v[180:183], v[204:207], v[92:95]
	v_mfma_f32_16x16x32_bf16 v[88:91], v[188:191], v[204:207], v[88:91]
	v_mfma_f32_16x16x32_bf16 v[76:79], v[180:183], v[212:215], v[76:79]
	v_mfma_f32_16x16x32_bf16 v[72:75], v[188:191], v[212:215], v[72:75]
	v_mfma_f32_16x16x32_bf16 v[68:71], v[180:183], v[220:223], v[68:71]
	v_mfma_f32_16x16x32_bf16 v[64:67], v[188:191], v[220:223], v[64:67]
	s_barrier
	s_add_i32 s75, s38, s16
	v_lshl_add_u64 v[158:159], s[68:69], 0, v[130:131]
	s_mov_b32 m0, s75
	ds_read_b128 v[192:195], v149 offset:16384
	ds_read_b128 v[196:199], v149 offset:17408
	ds_read_b128 v[200:203], v149 offset:18432
	ds_read_b128 v[204:207], v149 offset:19456
	ds_read_b128 v[208:211], v149 offset:20480
	ds_read_b128 v[212:215], v149 offset:21504
	ds_read_b128 v[216:219], v149 offset:22528
	ds_read_b128 v[220:223], v149 offset:23552
	global_load_lds_dwordx4 v[158:159], off
	s_add_i32 m0, s75, 0x2000
	s_add_u32 s78, s68, 0x40000
	v_lshl_add_u64 v[224:225], s[68:69], 0, v[134:135]
	s_addc_u32 s79, s69, 0
	s_add_i32 s75, s39, s16
	global_load_lds_dwordx4 v[224:225], off
	v_lshl_add_u64 v[226:227], s[78:79], 0, v[130:131]
	s_mov_b32 m0, s75
	v_lshl_add_u64 v[228:229], s[70:71], 0, v[132:133]
	global_load_lds_dwordx4 v[226:227], off
	v_lshl_add_u64 v[226:227], s[78:79], 0, v[134:135]
	s_add_i32 m0, s75, 0x2000
	s_nop 0
	global_load_lds_dwordx4 v[226:227], off
	v_lshl_add_u64 v[226:227], s[70:71], 0, v[128:129]
	s_mov_b32 m0, s17
	s_nop 0
	global_load_lds_dwordx4 v[226:227], off
	s_mov_b32 m0, s18
	s_nop 0
	global_load_lds_dwordx4 v[228:229], off
	s_waitcnt vmcnt(8)
	s_waitcnt lgkmcnt(0)
	s_barrier
; #define PG8_STAGE(bufoff, gbase, voff) do { _Pragma("unroll") for (int _i = 0; _i < 2; ++_i) \
;         __builtin_amdgcn_global_load_lds((const unsigned*)((const char*)(gbase) + (voff)[_i]), (LAS unsigned*)(lds + (bufoff) + ldsw + _i * 8192), 16, 0, 0); } while (0)
; #define PG8_LDA(dst, b, h) do { _Pragma("unroll") for (int m = 0; m < 4; ++m) _Pragma("unroll") for (int k = 0; k < 2; ++k) dst[m][k] = *(const LAS bf16x8*)(lds + PG8_SA(b, h) + aoff + m * 2048 + k * 1024); } while (0)
; #define PG8_LDB(dst, b, h) do { _Pragma("unroll") for (int n = 0; n < 2; ++n) _Pragma("unroll") for (int k = 0; k < 2; ++k) dst[n][k] = *(const LAS bf16x8*)(lds + PG8_SB(b, h) + boff + n * 2048 + k * 1024); } while (0)
; #define PG8_MMA(ai, bj, At, Bt) do { __builtin_amdgcn_s_setprio(1); _Pragma("unroll") for (int m = 0; m < 4; ++m) _Pragma("unroll") for (int n = 0; n < 2; ++n) _Pragma("unroll") for (int k = 0; k < 2; ++k) \
;         acc[ai][bj][m][n] = __builtin_amdgcn_mfma_f32_16x16x32_bf16(Bt[n][k], At[m][k], acc[ai][bj][m][n], 0, 0, 0); __builtin_amdgcn_s_setprio(0); } while (0)
; #define PG8_WAIT_V(n) asm volatile("s_waitcnt vmcnt(" #n ")" ::: "memory")
; #define PG8_WAIT_L(n) asm volatile("s_waitcnt lgkmcnt(" #n ")" ::: "memory")
; #define PG8_BAR __builtin_amdgcn_s_barrier()
; #define PG8_SCHED __builtin_amdgcn_sched_barrier(0)
; template <class Epi, class Sched, bool ALIGN_EPI = true, bool SP2 = true>
; __device__ __forceinline__ void gemm_phase(LAS unsigned char* lds, const Gemm g, const Sched& S, const Epi& E) {
;     ...
;             PG8_WAIT_V(8); PG8_WAIT_L(0); PG8_BAR; PG8_MMA(1, 0, At, B0); PG8_MMA(1, 1, At, B1); PG8_BAR; PG8_SCHED;
;             PG8_LDB(B0, 1, 0); PG8_LDB(B1, 1, 1); PG8_SCHED; PG8_LDA(At, 1, 0); PG8_STAGE(PG8_SA(0, 1), a2 + hstep, voffA);
;             PG8_WAIT_V(8); PG8_WAIT_L(0); PG8_BAR; PG8_MMA(0, 0, At, B0); PG8_MMA(0, 1, At, B1); PG8_BAR; PG8_SCHED;
	s_waitcnt lgkmcnt(0)
	v_mfma_f32_16x16x32_bf16 v[60:63], v[150:153], v[192:195], v[60:63]
	v_mfma_f32_16x16x32_bf16 v[56:59], v[166:169], v[192:195], v[56:59]
	v_mfma_f32_16x16x32_bf16 v[52:55], v[150:153], v[200:203], v[52:55]
	v_mfma_f32_16x16x32_bf16 v[48:51], v[166:169], v[200:203], v[48:51]
	v_mfma_f32_16x16x32_bf16 v[36:39], v[150:153], v[208:211], v[36:39]
	v_mfma_f32_16x16x32_bf16 v[32:35], v[166:169], v[208:211], v[32:35]
	v_mfma_f32_16x16x32_bf16 v[20:23], v[150:153], v[216:219], v[20:23]
	v_mfma_f32_16x16x32_bf16 v[16:19], v[166:169], v[216:219], v[16:19]
	v_mfma_f32_16x16x32_bf16 v[60:63], v[154:157], v[196:199], v[60:63]
	v_mfma_f32_16x16x32_bf16 v[56:59], v[170:173], v[196:199], v[56:59]
	v_mfma_f32_16x16x32_bf16 v[52:55], v[154:157], v[204:207], v[52:55]
	v_mfma_f32_16x16x32_bf16 v[48:51], v[170:173], v[204:207], v[48:51]
	v_mfma_f32_16x16x32_bf16 v[36:39], v[154:157], v[212:215], v[36:39]
	v_mfma_f32_16x16x32_bf16 v[32:35], v[170:173], v[212:215], v[32:35]
	v_mfma_f32_16x16x32_bf16 v[20:23], v[154:157], v[220:223], v[20:23]
	v_mfma_f32_16x16x32_bf16 v[16:19], v[170:173], v[220:223], v[16:19]
	v_mfma_f32_16x16x32_bf16 v[44:47], v[176:179], v[192:195], v[44:47]
	v_mfma_f32_16x16x32_bf16 v[40:43], v[184:187], v[192:195], v[40:43]
	v_mfma_f32_16x16x32_bf16 v[28:31], v[176:179], v[200:203], v[28:31]
	v_mfma_f32_16x16x32_bf16 v[24:27], v[184:187], v[200:203], v[24:27]
	v_mfma_f32_16x16x32_bf16 v[12:15], v[176:179], v[208:211], v[12:15]
	v_mfma_f32_16x16x32_bf16 v[8:11], v[184:187], v[208:211], v[8:11]
	v_mfma_f32_16x16x32_bf16 v[4:7], v[176:179], v[216:219], v[4:7]
	v_mfma_f32_16x16x32_bf16 v[0:3], v[184:187], v[216:219], v[0:3]
	v_mfma_f32_16x16x32_bf16 v[44:47], v[180:183], v[196:199], v[44:47]
	v_mfma_f32_16x16x32_bf16 v[40:43], v[188:191], v[196:199], v[40:43]
	v_mfma_f32_16x16x32_bf16 v[28:31], v[180:183], v[204:207], v[28:31]
	v_mfma_f32_16x16x32_bf16 v[24:27], v[188:191], v[204:207], v[24:27]
	v_mfma_f32_16x16x32_bf16 v[12:15], v[180:183], v[212:215], v[12:15]
	v_mfma_f32_16x16x32_bf16 v[8:11], v[188:191], v[212:215], v[8:11]
	v_mfma_f32_16x16x32_bf16 v[4:7], v[180:183], v[220:223], v[4:7]
	v_mfma_f32_16x16x32_bf16 v[0:3], v[188:191], v[220:223], v[0:3]
	s_barrier
	s_add_i32 s75, 0, 0x18000
	v_add_u32_e32 v163, s75, v145
	s_add_i32 s78, 0, 0x1c000
	ds_read_b128 v[150:153], v163
	ds_read_b128 v[154:157], v163 offset:1024
	ds_read_b128 v[166:169], v163 offset:2048
	ds_read_b128 v[170:173], v163 offset:3072
	v_add_u32_e32 v163, s78, v145
	ds_read_b128 v[176:179], v163
	ds_read_b128 v[180:183], v163 offset:1024
	ds_read_b128 v[184:187], v163 offset:2048
	ds_read_b128 v[188:191], v163 offset:3072
	s_add_u32 s70, s70, 0x40000
	s_addc_u32 s71, s71, 0
	s_mov_b32 m0, s19
	v_lshl_add_u64 v[230:231], s[70:71], 0, v[128:129]
	ds_read_b128 v[192:195], v149 offset:32768
	ds_read_b128 v[196:199], v149 offset:33792
	ds_read_b128 v[200:203], v149 offset:34816
	ds_read_b128 v[204:207], v149 offset:35840
	ds_read_b128 v[208:211], v149 offset:36864
	ds_read_b128 v[212:215], v149 offset:37888
	ds_read_b128 v[216:219], v149 offset:38912
	ds_read_b128 v[220:223], v149 offset:39936
	global_load_lds_dwordx4 v[230:231], off
	v_lshl_add_u64 v[230:231], s[70:71], 0, v[132:133]
	s_mov_b32 m0, s21
	s_nop 0
	global_load_lds_dwordx4 v[230:231], off
	s_waitcnt vmcnt(8)
	s_waitcnt lgkmcnt(0)
	s_barrier
	s_waitcnt lgkmcnt(0)
	v_mfma_f32_16x16x32_bf16 v[124:127], v[150:153], v[192:195], v[124:127]
	v_mfma_f32_16x16x32_bf16 v[120:123], v[166:169], v[192:195], v[120:123]
	v_mfma_f32_16x16x32_bf16 v[116:119], v[150:153], v[200:203], v[116:119]
	v_mfma_f32_16x16x32_bf16 v[112:115], v[166:169], v[200:203], v[112:115]
	v_mfma_f32_16x16x32_bf16 v[100:103], v[150:153], v[208:211], v[100:103]
	v_mfma_f32_16x16x32_bf16 v[96:99], v[166:169], v[208:211], v[96:99]
	v_mfma_f32_16x16x32_bf16 v[84:87], v[150:153], v[216:219], v[84:87]
	v_mfma_f32_16x16x32_bf16 v[80:83], v[166:169], v[216:219], v[80:83]
	v_mfma_f32_16x16x32_bf16 v[124:127], v[154:157], v[196:199], v[124:127]
	v_mfma_f32_16x16x32_bf16 v[120:123], v[170:173], v[196:199], v[120:123]
	v_mfma_f32_16x16x32_bf16 v[116:119], v[154:157], v[204:207], v[116:119]
	v_mfma_f32_16x16x32_bf16 v[112:115], v[170:173], v[204:207], v[112:115]
	v_mfma_f32_16x16x32_bf16 v[100:103], v[154:157], v[212:215], v[100:103]
	v_mfma_f32_16x16x32_bf16 v[96:99], v[170:173], v[212:215], v[96:99]
	v_mfma_f32_16x16x32_bf16 v[84:87], v[154:157], v[220:223], v[84:87]
	v_mfma_f32_16x16x32_bf16 v[80:83], v[170:173], v[220:223], v[80:83]
	v_mfma_f32_16x16x32_bf16 v[108:111], v[176:179], v[192:195], v[108:111]
	v_mfma_f32_16x16x32_bf16 v[104:107], v[184:187], v[192:195], v[104:107]
	v_mfma_f32_16x16x32_bf16 v[92:95], v[176:179], v[200:203], v[92:95]
	v_mfma_f32_16x16x32_bf16 v[88:91], v[184:187], v[200:203], v[88:91]
	v_mfma_f32_16x16x32_bf16 v[76:79], v[176:179], v[208:211], v[76:79]
	v_mfma_f32_16x16x32_bf16 v[72:75], v[184:187], v[208:211], v[72:75]
	v_mfma_f32_16x16x32_bf16 v[68:71], v[176:179], v[216:219], v[68:71]
	v_mfma_f32_16x16x32_bf16 v[64:67], v[184:187], v[216:219], v[64:67]
	v_mfma_f32_16x16x32_bf16 v[108:111], v[180:183], v[196:199], v[108:111]
	v_mfma_f32_16x16x32_bf16 v[104:107], v[188:191], v[196:199], v[104:107]
	v_mfma_f32_16x16x32_bf16 v[92:95], v[180:183], v[204:207], v[92:95]
	v_mfma_f32_16x16x32_bf16 v[88:91], v[188:191], v[204:207], v[88:91]
	v_mfma_f32_16x16x32_bf16 v[76:79], v[180:183], v[212:215], v[76:79]
	v_mfma_f32_16x16x32_bf16 v[72:75], v[188:191], v[212:215], v[72:75]
	v_mfma_f32_16x16x32_bf16 v[68:71], v[180:183], v[220:223], v[68:71]
	v_mfma_f32_16x16x32_bf16 v[64:67], v[188:191], v[220:223], v[64:67]
	s_barrier
; #define PG8_STAGE(bufoff, gbase, voff) do { _Pragma("unroll") for (int _i = 0; _i < 2; ++_i) \
;         __builtin_amdgcn_global_load_lds((const unsigned*)((const char*)(gbase) + (voff)[_i]), (LAS unsigned*)(lds + (bufoff) + ldsw + _i * 8192), 16, 0, 0); } while (0)
; #define PG8_LDA(dst, b, h) do { _Pragma("unroll") for (int m = 0; m < 4; ++m) _Pragma("unroll") for (int k = 0; k < 2; ++k) dst[m][k] = *(const LAS bf16x8*)(lds + PG8_SA(b, h) + aoff + m * 2048 + k * 1024); } while (0)
; #define PG8_MMA(ai, bj, At, Bt) do { __builtin_amdgcn_s_setprio(1); _Pragma("unroll") for (int m = 0; m < 4; ++m) _Pragma("unroll") for (int n = 0; n < 2; ++n) _Pragma("unroll") for (int k = 0; k < 2; ++k) \
;         acc[ai][bj][m][n] = __builtin_amdgcn_mfma_f32_16x16x32_bf16(Bt[n][k], At[m][k], acc[ai][bj][m][n], 0, 0, 0); __builtin_amdgcn_s_setprio(0); } while (0)
; #define PG8_WAIT_V(n) asm volatile("s_waitcnt vmcnt(" #n ")" ::: "memory")
; #define PG8_WAIT_L(n) asm volatile("s_waitcnt lgkmcnt(" #n ")" ::: "memory")
; #define PG8_BAR __builtin_amdgcn_s_barrier()
; #define PG8_SCHED __builtin_amdgcn_sched_barrier(0)
; template <class Epi, class Sched, bool ALIGN_EPI = true, bool SP2 = true>
; __device__ __forceinline__ void gemm_phase(LAS unsigned char* lds, const Gemm g, const Sched& S, const Epi& E) {
;     ...
;             PG8_LDA(At, 1, 1); PG8_STAGE(PG8_SB(1, 0), b3, voffB); PG8_STAGE(PG8_SB(1, 1), b3 + hstep, voffB); PG8_STAGE(PG8_SA(1, 0), a3, voffA);
;             PG8_WAIT_V(8); PG8_WAIT_L(0); PG8_BAR; PG8_MMA(1, 0, At, B0); PG8_MMA(1, 1, At, B1); PG8_BAR; PG8_SCHED;
;     ...
;         if constexpr (ALIGN_EPI) { if (wr == 0) PG8_BAR; }
	s_add_i32 s70, s75, s16
	v_lshl_add_u64 v[158:159], v[158:159], 0, s[10:11]
	s_mov_b32 m0, s70
	ds_read_b128 v[192:195], v149 offset:49152
	ds_read_b128 v[196:199], v149 offset:50176
	ds_read_b128 v[200:203], v149 offset:51200
	ds_read_b128 v[204:207], v149 offset:52224
	ds_read_b128 v[208:211], v149 offset:53248
	ds_read_b128 v[212:215], v149 offset:54272
	ds_read_b128 v[216:219], v149 offset:55296
	ds_read_b128 v[220:223], v149 offset:56320
	global_load_lds_dwordx4 v[158:159], off
	s_add_i32 m0, s70, 0x2000
	s_add_u32 s68, s68, 0x40080
	v_lshl_add_u64 v[158:159], v[224:225], 0, s[10:11]
	s_addc_u32 s69, s69, 0
	s_add_i32 s70, s78, s16
	global_load_lds_dwordx4 v[158:159], off
	v_lshl_add_u64 v[158:159], s[68:69], 0, v[130:131]
	s_mov_b32 m0, s70
	s_nop 0
	global_load_lds_dwordx4 v[158:159], off
	v_lshl_add_u64 v[158:159], s[68:69], 0, v[134:135]
	s_add_i32 m0, s70, 0x2000
	s_nop 0
	global_load_lds_dwordx4 v[158:159], off
	v_lshl_add_u64 v[158:159], v[226:227], 0, s[10:11]
	s_mov_b32 m0, s24
	s_nop 0
	global_load_lds_dwordx4 v[158:159], off
	v_lshl_add_u64 v[158:159], v[228:229], 0, s[10:11]
	s_mov_b32 m0, s25
	s_nop 0
	global_load_lds_dwordx4 v[158:159], off
	s_waitcnt vmcnt(8)
	s_waitcnt lgkmcnt(0)
	s_barrier
	s_waitcnt lgkmcnt(0)
	v_mfma_f32_16x16x32_bf16 v[60:63], v[150:153], v[192:195], v[60:63]
	v_mfma_f32_16x16x32_bf16 v[56:59], v[166:169], v[192:195], v[56:59]
	v_mfma_f32_16x16x32_bf16 v[52:55], v[150:153], v[200:203], v[52:55]
	v_mfma_f32_16x16x32_bf16 v[48:51], v[166:169], v[200:203], v[48:51]
	v_mfma_f32_16x16x32_bf16 v[36:39], v[150:153], v[208:211], v[36:39]
	v_mfma_f32_16x16x32_bf16 v[32:35], v[166:169], v[208:211], v[32:35]
	v_mfma_f32_16x16x32_bf16 v[20:23], v[150:153], v[216:219], v[20:23]
	v_mfma_f32_16x16x32_bf16 v[16:19], v[166:169], v[216:219], v[16:19]
	v_mfma_f32_16x16x32_bf16 v[60:63], v[154:157], v[196:199], v[60:63]
	v_mfma_f32_16x16x32_bf16 v[56:59], v[170:173], v[196:199], v[56:59]
	v_mfma_f32_16x16x32_bf16 v[52:55], v[154:157], v[204:207], v[52:55]
	v_mfma_f32_16x16x32_bf16 v[48:51], v[170:173], v[204:207], v[48:51]
	v_mfma_f32_16x16x32_bf16 v[36:39], v[154:157], v[212:215], v[36:39]
	v_mfma_f32_16x16x32_bf16 v[32:35], v[170:173], v[212:215], v[32:35]
	v_mfma_f32_16x16x32_bf16 v[20:23], v[154:157], v[220:223], v[20:23]
	v_mfma_f32_16x16x32_bf16 v[16:19], v[170:173], v[220:223], v[16:19]
	v_mfma_f32_16x16x32_bf16 v[44:47], v[176:179], v[192:195], v[44:47]
	v_mfma_f32_16x16x32_bf16 v[40:43], v[184:187], v[192:195], v[40:43]
	v_mfma_f32_16x16x32_bf16 v[28:31], v[176:179], v[200:203], v[28:31]
	v_mfma_f32_16x16x32_bf16 v[24:27], v[184:187], v[200:203], v[24:27]
	v_mfma_f32_16x16x32_bf16 v[12:15], v[176:179], v[208:211], v[12:15]
	v_mfma_f32_16x16x32_bf16 v[8:11], v[184:187], v[208:211], v[8:11]
	v_mfma_f32_16x16x32_bf16 v[4:7], v[176:179], v[216:219], v[4:7]
	v_mfma_f32_16x16x32_bf16 v[0:3], v[184:187], v[216:219], v[0:3]
	v_mfma_f32_16x16x32_bf16 v[44:47], v[180:183], v[196:199], v[44:47]
	v_mfma_f32_16x16x32_bf16 v[40:43], v[188:191], v[196:199], v[40:43]
	v_mfma_f32_16x16x32_bf16 v[28:31], v[180:183], v[204:207], v[28:31]
	v_mfma_f32_16x16x32_bf16 v[24:27], v[188:191], v[204:207], v[24:27]
	v_mfma_f32_16x16x32_bf16 v[12:15], v[180:183], v[212:215], v[12:15]
	v_mfma_f32_16x16x32_bf16 v[8:11], v[188:191], v[212:215], v[8:11]
	v_mfma_f32_16x16x32_bf16 v[4:7], v[180:183], v[220:223], v[4:7]
	v_mfma_f32_16x16x32_bf16 v[0:3], v[188:191], v[220:223], v[0:3]
	s_barrier
	s_add_i32 s74, s74, 2
	s_add_u32 s64, s64, 0x100
	s_addc_u32 s65, s65, 0
	s_add_u32 s72, s72, 0x100
	s_addc_u32 s73, s73, 0
	s_cmp_gt_u32 s74, 13
	s_cbranch_scc0 .LBB0_1113
	s_and_b64 vcc, exec, s[12:13]
	s_cbranch_vccz .LBB0_1116
	s_barrier

; #define PG8_STAGE(bufoff, gbase, voff) do { _Pragma("unroll") for (int _i = 0; _i < 2; ++_i) \
;         __builtin_amdgcn_global_load_lds((const unsigned*)((const char*)(gbase) + (voff)[_i]), (LAS unsigned*)(lds + (bufoff) + ldsw + _i * 8192), 16, 0, 0); } while (0)
; #define PG8_LDA(dst, b, h) do { _Pragma("unroll") for (int m = 0; m < 4; ++m) _Pragma("unroll") for (int k = 0; k < 2; ++k) dst[m][k] = *(const LAS bf16x8*)(lds + PG8_SA(b, h) + aoff + m * 2048 + k * 1024); } while (0)
; #define PG8_LDB(dst, b, h) do { _Pragma("unroll") for (int n = 0; n < 2; ++n) _Pragma("unroll") for (int k = 0; k < 2; ++k) dst[n][k] = *(const LAS bf16x8*)(lds + PG8_SB(b, h) + boff + n * 2048 + k * 1024); } while (0)
; #define PG8_MMA(ai, bj, At, Bt) do { __builtin_amdgcn_s_setprio(1); _Pragma("unroll") for (int m = 0; m < 4; ++m) _Pragma("unroll") for (int n = 0; n < 2; ++n) _Pragma("unroll") for (int k = 0; k < 2; ++k) \
;         acc[ai][bj][m][n] = __builtin_amdgcn_mfma_f32_16x16x32_bf16(Bt[n][k], At[m][k], acc[ai][bj][m][n], 0, 0, 0); __builtin_amdgcn_s_setprio(0); } while (0)
; #define PG8_WAIT_V(n) asm volatile("s_waitcnt vmcnt(" #n ")" ::: "memory")
; #define PG8_WAIT_L(n) asm volatile("s_waitcnt lgkmcnt(" #n ")" ::: "memory")
; #define PG8_BAR __builtin_amdgcn_s_barrier()
; #define PG8_SCHED __builtin_amdgcn_sched_barrier(0)
; template <class Epi, class Sched, bool ALIGN_EPI = true, bool SP2 = true>
; __device__ __forceinline__ void gemm_phase(LAS unsigned char* lds, const Gemm g, const Sched& S, const Epi& E) {
;     ...
;             const bool last = (t == nt - 2);
;             const char* a1 = cA + (size_t)(t + 1) * kstep;
;             const char* a2 = last ? nA : cA + (size_t)(t + 2) * kstep; const char* b2 = last ? nB : cB + (size_t)(t + 2) * kstep;
;             const char* a3 = a2 + kstep; const char* b3 = b2 + kstep;
;             if constexpr (SP2) {
;             PG8_LDB(B0, 0, 0); PG8_LDB(B1, 0, 1); PG8_SCHED; PG8_LDA(At, 0, 0); PG8_STAGE(PG8_SA(1, 1), a1 + hstep, voffA);
;             PG8_WAIT_V(8); PG8_WAIT_L(0); PG8_BAR; PG8_MMA(0, 0, At, B0); PG8_MMA(0, 1, At, B1); PG8_BAR; PG8_SCHED;
;             PG8_LDA(At, 0, 1); PG8_STAGE(PG8_SB(0, 0), b2, voffB); PG8_STAGE(PG8_SB(0, 1), b2 + hstep, voffB); PG8_STAGE(PG8_SA(0, 0), a2, voffA);
;             PG8_WAIT_V(8); PG8_WAIT_L(0); PG8_BAR; PG8_MMA(1, 0, At, B0); PG8_MMA(1, 1, At, B1); PG8_BAR; PG8_SCHED;
.LBB0_1236:
	ds_read_b128 v[152:155], v149
	ds_read_b128 v[156:159], v149 offset:1024
	ds_read_b128 v[166:169], v149 offset:2048
	ds_read_b128 v[170:173], v149 offset:3072
	ds_read_b128 v[176:179], v150
	ds_read_b128 v[180:183], v150 offset:1024
	ds_read_b128 v[184:187], v150 offset:2048
	ds_read_b128 v[188:191], v150 offset:3072
	s_add_u32 s48, s46, 0xfffc0080
	s_addc_u32 s49, s47, -1
	s_cmp_eq_u32 s58, 12
	s_cselect_b32 s51, s37, s49
	s_cselect_b32 s50, s54, s48
	s_cselect_b32 s49, s15, s57
	s_cselect_b32 s48, s55, s56
	v_lshl_add_u64 v[144:145], s[46:47], 0, v[136:137]
	s_add_i32 m0, s18, 0xc000
	ds_read_b128 v[192:195], v151
	ds_read_b128 v[196:199], v151 offset:1024
	ds_read_b128 v[200:203], v151 offset:2048
	ds_read_b128 v[204:207], v151 offset:3072
	ds_read_b128 v[208:211], v151 offset:4096
	ds_read_b128 v[212:215], v151 offset:5120
	ds_read_b128 v[216:219], v151 offset:6144
	ds_read_b128 v[220:223], v151 offset:7168
	global_load_lds_dwordx4 v[144:145], off
	v_lshl_add_u64 v[144:145], s[46:47], 0, v[138:139]
	s_add_i32 m0, s18, 0xe000
	s_nop 0
	global_load_lds_dwordx4 v[144:145], off
	s_waitcnt vmcnt(8)
	s_waitcnt lgkmcnt(0)
	s_barrier
	s_waitcnt lgkmcnt(0)
	v_mfma_f32_16x16x32_bf16 v[124:127], v[152:155], v[192:195], v[124:127]
	v_mfma_f32_16x16x32_bf16 v[120:123], v[166:169], v[192:195], v[120:123]
	v_mfma_f32_16x16x32_bf16 v[108:111], v[152:155], v[200:203], v[108:111]
	v_mfma_f32_16x16x32_bf16 v[104:107], v[166:169], v[200:203], v[104:107]
	v_mfma_f32_16x16x32_bf16 v[92:95], v[152:155], v[208:211], v[92:95]
	v_mfma_f32_16x16x32_bf16 v[88:91], v[166:169], v[208:211], v[88:91]
	v_mfma_f32_16x16x32_bf16 v[76:79], v[152:155], v[216:219], v[76:79]
	v_mfma_f32_16x16x32_bf16 v[72:75], v[166:169], v[216:219], v[72:75]
	v_mfma_f32_16x16x32_bf16 v[124:127], v[156:159], v[196:199], v[124:127]
	v_mfma_f32_16x16x32_bf16 v[120:123], v[170:173], v[196:199], v[120:123]
	v_mfma_f32_16x16x32_bf16 v[108:111], v[156:159], v[204:207], v[108:111]
	v_mfma_f32_16x16x32_bf16 v[104:107], v[170:173], v[204:207], v[104:107]
	v_mfma_f32_16x16x32_bf16 v[92:95], v[156:159], v[212:215], v[92:95]
	v_mfma_f32_16x16x32_bf16 v[88:91], v[170:173], v[212:215], v[88:91]
	v_mfma_f32_16x16x32_bf16 v[76:79], v[156:159], v[220:223], v[76:79]
	v_mfma_f32_16x16x32_bf16 v[72:75], v[170:173], v[220:223], v[72:75]
	v_mfma_f32_16x16x32_bf16 v[116:119], v[176:179], v[192:195], v[116:119]
	v_mfma_f32_16x16x32_bf16 v[112:115], v[184:187], v[192:195], v[112:115]
	v_mfma_f32_16x16x32_bf16 v[100:103], v[176:179], v[200:203], v[100:103]
	v_mfma_f32_16x16x32_bf16 v[96:99], v[184:187], v[200:203], v[96:99]
	v_mfma_f32_16x16x32_bf16 v[84:87], v[176:179], v[208:211], v[84:87]
	v_mfma_f32_16x16x32_bf16 v[80:83], v[184:187], v[208:211], v[80:83]
	v_mfma_f32_16x16x32_bf16 v[68:71], v[176:179], v[216:219], v[68:71]
	v_mfma_f32_16x16x32_bf16 v[64:67], v[184:187], v[216:219], v[64:67]
	v_mfma_f32_16x16x32_bf16 v[116:119], v[180:183], v[196:199], v[116:119]
	v_mfma_f32_16x16x32_bf16 v[112:115], v[188:191], v[196:199], v[112:115]
	v_mfma_f32_16x16x32_bf16 v[100:103], v[180:183], v[204:207], v[100:103]
	v_mfma_f32_16x16x32_bf16 v[96:99], v[188:191], v[204:207], v[96:99]
	v_mfma_f32_16x16x32_bf16 v[84:87], v[180:183], v[212:215], v[84:87]
	v_mfma_f32_16x16x32_bf16 v[80:83], v[188:191], v[212:215], v[80:83]
	v_mfma_f32_16x16x32_bf16 v[68:71], v[180:183], v[220:223], v[68:71]
	v_mfma_f32_16x16x32_bf16 v[64:67], v[188:191], v[220:223], v[64:67]
	s_barrier
	s_add_i32 s59, s39, s2
	v_lshl_add_u64 v[144:145], s[48:49], 0, v[132:133]
	s_mov_b32 m0, s59
	ds_read_b128 v[192:195], v151 offset:16384
	ds_read_b128 v[196:199], v151 offset:17408
	ds_read_b128 v[200:203], v151 offset:18432
	ds_read_b128 v[204:207], v151 offset:19456
	ds_read_b128 v[208:211], v151 offset:20480
	ds_read_b128 v[212:215], v151 offset:21504
	ds_read_b128 v[216:219], v151 offset:22528
	ds_read_b128 v[220:223], v151 offset:23552
	global_load_lds_dwordx4 v[144:145], off
	s_add_i32 m0, s59, 0x2000
	s_add_u32 s60, s48, 0x40000
	v_lshl_add_u64 v[224:225], s[48:49], 0, v[128:129]
	s_addc_u32 s61, s49, 0
	s_add_i32 s59, s45, s2
	global_load_lds_dwordx4 v[224:225], off
	v_lshl_add_u64 v[226:227], s[60:61], 0, v[132:133]
	s_mov_b32 m0, s59
	v_lshl_add_u64 v[228:229], s[50:51], 0, v[130:131]
	global_load_lds_dwordx4 v[226:227], off
	v_lshl_add_u64 v[226:227], s[60:61], 0, v[128:129]
	s_add_i32 m0, s59, 0x2000
	s_nop 0
	global_load_lds_dwordx4 v[226:227], off
	v_lshl_add_u64 v[226:227], s[50:51], 0, v[134:135]
	s_mov_b32 m0, s18
	s_nop 0
	global_load_lds_dwordx4 v[226:227], off
	s_mov_b32 m0, s19
	s_nop 0
	global_load_lds_dwordx4 v[228:229], off
	s_waitcnt vmcnt(8)
	s_waitcnt lgkmcnt(0)
	s_barrier
; #define PG8_STAGE(bufoff, gbase, voff) do { _Pragma("unroll") for (int _i = 0; _i < 2; ++_i) \
;         __builtin_amdgcn_global_load_lds((const unsigned*)((const char*)(gbase) + (voff)[_i]), (LAS unsigned*)(lds + (bufoff) + ldsw + _i * 8192), 16, 0, 0); } while (0)
; #define PG8_LDA(dst, b, h) do { _Pragma("unroll") for (int m = 0; m < 4; ++m) _Pragma("unroll") for (int k = 0; k < 2; ++k) dst[m][k] = *(const LAS bf16x8*)(lds + PG8_SA(b, h) + aoff + m * 2048 + k * 1024); } while (0)
; #define PG8_LDB(dst, b, h) do { _Pragma("unroll") for (int n = 0; n < 2; ++n) _Pragma("unroll") for (int k = 0; k < 2; ++k) dst[n][k] = *(const LAS bf16x8*)(lds + PG8_SB(b, h) + boff + n * 2048 + k * 1024); } while (0)
; #define PG8_MMA(ai, bj, At, Bt) do { __builtin_amdgcn_s_setprio(1); _Pragma("unroll") for (int m = 0; m < 4; ++m) _Pragma("unroll") for (int n = 0; n < 2; ++n) _Pragma("unroll") for (int k = 0; k < 2; ++k) \
;         acc[ai][bj][m][n] = __builtin_amdgcn_mfma_f32_16x16x32_bf16(Bt[n][k], At[m][k], acc[ai][bj][m][n], 0, 0, 0); __builtin_amdgcn_s_setprio(0); } while (0)
; #define PG8_WAIT_V(n) asm volatile("s_waitcnt vmcnt(" #n ")" ::: "memory")
; #define PG8_WAIT_L(n) asm volatile("s_waitcnt lgkmcnt(" #n ")" ::: "memory")
; #define PG8_BAR __builtin_amdgcn_s_barrier()
; #define PG8_SCHED __builtin_amdgcn_sched_barrier(0)
; template <class Epi, class Sched, bool ALIGN_EPI = true, bool SP2 = true>
; __device__ __forceinline__ void gemm_phase(LAS unsigned char* lds, const Gemm g, const Sched& S, const Epi& E) {
;     ...
;             PG8_WAIT_V(8); PG8_WAIT_L(0); PG8_BAR; PG8_MMA(1, 0, At, B0); PG8_MMA(1, 1, At, B1); PG8_BAR; PG8_SCHED;
;             PG8_LDB(B0, 1, 0); PG8_LDB(B1, 1, 1); PG8_SCHED; PG8_LDA(At, 1, 0); PG8_STAGE(PG8_SA(0, 1), a2 + hstep, voffA);
;             PG8_WAIT_V(8); PG8_WAIT_L(0); PG8_BAR; PG8_MMA(0, 0, At, B0); PG8_MMA(0, 1, At, B1); PG8_BAR; PG8_SCHED;
	s_waitcnt lgkmcnt(0)
	v_mfma_f32_16x16x32_bf16 v[60:63], v[152:155], v[192:195], v[60:63]
	v_mfma_f32_16x16x32_bf16 v[56:59], v[166:169], v[192:195], v[56:59]
	v_mfma_f32_16x16x32_bf16 v[44:47], v[152:155], v[200:203], v[44:47]
	v_mfma_f32_16x16x32_bf16 v[40:43], v[166:169], v[200:203], v[40:43]
	v_mfma_f32_16x16x32_bf16 v[28:31], v[152:155], v[208:211], v[28:31]
	v_mfma_f32_16x16x32_bf16 v[24:27], v[166:169], v[208:211], v[24:27]
	v_mfma_f32_16x16x32_bf16 v[12:15], v[152:155], v[216:219], v[12:15]
	v_mfma_f32_16x16x32_bf16 v[8:11], v[166:169], v[216:219], v[8:11]
	v_mfma_f32_16x16x32_bf16 v[60:63], v[156:159], v[196:199], v[60:63]
	v_mfma_f32_16x16x32_bf16 v[56:59], v[170:173], v[196:199], v[56:59]
	v_mfma_f32_16x16x32_bf16 v[44:47], v[156:159], v[204:207], v[44:47]
	v_mfma_f32_16x16x32_bf16 v[40:43], v[170:173], v[204:207], v[40:43]
	v_mfma_f32_16x16x32_bf16 v[28:31], v[156:159], v[212:215], v[28:31]
	v_mfma_f32_16x16x32_bf16 v[24:27], v[170:173], v[212:215], v[24:27]
	v_mfma_f32_16x16x32_bf16 v[12:15], v[156:159], v[220:223], v[12:15]
	v_mfma_f32_16x16x32_bf16 v[8:11], v[170:173], v[220:223], v[8:11]
	v_mfma_f32_16x16x32_bf16 v[52:55], v[176:179], v[192:195], v[52:55]
	v_mfma_f32_16x16x32_bf16 v[48:51], v[184:187], v[192:195], v[48:51]
	v_mfma_f32_16x16x32_bf16 v[36:39], v[176:179], v[200:203], v[36:39]
	v_mfma_f32_16x16x32_bf16 v[32:35], v[184:187], v[200:203], v[32:35]
	v_mfma_f32_16x16x32_bf16 v[20:23], v[176:179], v[208:211], v[20:23]
	v_mfma_f32_16x16x32_bf16 v[16:19], v[184:187], v[208:211], v[16:19]
	v_mfma_f32_16x16x32_bf16 v[4:7], v[176:179], v[216:219], v[4:7]
	v_mfma_f32_16x16x32_bf16 v[0:3], v[184:187], v[216:219], v[0:3]
	v_mfma_f32_16x16x32_bf16 v[52:55], v[180:183], v[196:199], v[52:55]
	v_mfma_f32_16x16x32_bf16 v[48:51], v[188:191], v[196:199], v[48:51]
	v_mfma_f32_16x16x32_bf16 v[36:39], v[180:183], v[204:207], v[36:39]
	v_mfma_f32_16x16x32_bf16 v[32:35], v[188:191], v[204:207], v[32:35]
	v_mfma_f32_16x16x32_bf16 v[20:23], v[180:183], v[212:215], v[20:23]
	v_mfma_f32_16x16x32_bf16 v[16:19], v[188:191], v[212:215], v[16:19]
	v_mfma_f32_16x16x32_bf16 v[4:7], v[180:183], v[220:223], v[4:7]
	v_mfma_f32_16x16x32_bf16 v[0:3], v[188:191], v[220:223], v[0:3]
	s_barrier
	s_add_i32 s59, 0, 0x18000
	v_add_u32_e32 v163, s59, v147
	s_add_i32 s60, 0, 0x1c000
	ds_read_b128 v[152:155], v163
	ds_read_b128 v[156:159], v163 offset:1024
	ds_read_b128 v[166:169], v163 offset:2048
	ds_read_b128 v[170:173], v163 offset:3072
	v_add_u32_e32 v163, s60, v147
	ds_read_b128 v[176:179], v163
	ds_read_b128 v[180:183], v163 offset:1024
	ds_read_b128 v[184:187], v163 offset:2048
	ds_read_b128 v[188:191], v163 offset:3072
	s_add_u32 s50, s50, 0x40000
	s_addc_u32 s51, s51, 0
	s_mov_b32 m0, s21
	v_lshl_add_u64 v[230:231], s[50:51], 0, v[134:135]
	ds_read_b128 v[192:195], v151 offset:32768
	ds_read_b128 v[196:199], v151 offset:33792
	ds_read_b128 v[200:203], v151 offset:34816
	ds_read_b128 v[204:207], v151 offset:35840
	ds_read_b128 v[208:211], v151 offset:36864
	ds_read_b128 v[212:215], v151 offset:37888
	ds_read_b128 v[216:219], v151 offset:38912
	ds_read_b128 v[220:223], v151 offset:39936
	global_load_lds_dwordx4 v[230:231], off
	v_lshl_add_u64 v[230:231], s[50:51], 0, v[130:131]
	s_mov_b32 m0, s23
	s_nop 0
	global_load_lds_dwordx4 v[230:231], off
	s_waitcnt vmcnt(8)
	s_waitcnt lgkmcnt(0)
	s_barrier
	s_waitcnt lgkmcnt(0)
	v_mfma_f32_16x16x32_bf16 v[124:127], v[152:155], v[192:195], v[124:127]
	v_mfma_f32_16x16x32_bf16 v[120:123], v[166:169], v[192:195], v[120:123]
	v_mfma_f32_16x16x32_bf16 v[108:111], v[152:155], v[200:203], v[108:111]
	v_mfma_f32_16x16x32_bf16 v[104:107], v[166:169], v[200:203], v[104:107]
	v_mfma_f32_16x16x32_bf16 v[92:95], v[152:155], v[208:211], v[92:95]
	v_mfma_f32_16x16x32_bf16 v[88:91], v[166:169], v[208:211], v[88:91]
	v_mfma_f32_16x16x32_bf16 v[76:79], v[152:155], v[216:219], v[76:79]
	v_mfma_f32_16x16x32_bf16 v[72:75], v[166:169], v[216:219], v[72:75]
	v_mfma_f32_16x16x32_bf16 v[124:127], v[156:159], v[196:199], v[124:127]
	v_mfma_f32_16x16x32_bf16 v[120:123], v[170:173], v[196:199], v[120:123]
	v_mfma_f32_16x16x32_bf16 v[108:111], v[156:159], v[204:207], v[108:111]
	v_mfma_f32_16x16x32_bf16 v[104:107], v[170:173], v[204:207], v[104:107]
	v_mfma_f32_16x16x32_bf16 v[92:95], v[156:159], v[212:215], v[92:95]
	v_mfma_f32_16x16x32_bf16 v[88:91], v[170:173], v[212:215], v[88:91]
	v_mfma_f32_16x16x32_bf16 v[76:79], v[156:159], v[220:223], v[76:79]
	v_mfma_f32_16x16x32_bf16 v[72:75], v[170:173], v[220:223], v[72:75]
	v_mfma_f32_16x16x32_bf16 v[116:119], v[176:179], v[192:195], v[116:119]
	v_mfma_f32_16x16x32_bf16 v[112:115], v[184:187], v[192:195], v[112:115]
	v_mfma_f32_16x16x32_bf16 v[100:103], v[176:179], v[200:203], v[100:103]
	v_mfma_f32_16x16x32_bf16 v[96:99], v[184:187], v[200:203], v[96:99]
	v_mfma_f32_16x16x32_bf16 v[84:87], v[176:179], v[208:211], v[84:87]
	v_mfma_f32_16x16x32_bf16 v[80:83], v[184:187], v[208:211], v[80:83]
	v_mfma_f32_16x16x32_bf16 v[68:71], v[176:179], v[216:219], v[68:71]
	v_mfma_f32_16x16x32_bf16 v[64:67], v[184:187], v[216:219], v[64:67]
	v_mfma_f32_16x16x32_bf16 v[116:119], v[180:183], v[196:199], v[116:119]
	v_mfma_f32_16x16x32_bf16 v[112:115], v[188:191], v[196:199], v[112:115]
	v_mfma_f32_16x16x32_bf16 v[100:103], v[180:183], v[204:207], v[100:103]
	v_mfma_f32_16x16x32_bf16 v[96:99], v[188:191], v[204:207], v[96:99]
	v_mfma_f32_16x16x32_bf16 v[84:87], v[180:183], v[212:215], v[84:87]
	v_mfma_f32_16x16x32_bf16 v[80:83], v[188:191], v[212:215], v[80:83]
	v_mfma_f32_16x16x32_bf16 v[68:71], v[180:183], v[220:223], v[68:71]
	v_mfma_f32_16x16x32_bf16 v[64:67], v[188:191], v[220:223], v[64:67]
	s_barrier
; #define PG8_STAGE(bufoff, gbase, voff) do { _Pragma("unroll") for (int _i = 0; _i < 2; ++_i) \
;         __builtin_amdgcn_global_load_lds((const unsigned*)((const char*)(gbase) + (voff)[_i]), (LAS unsigned*)(lds + (bufoff) + ldsw + _i * 8192), 16, 0, 0); } while (0)
; #define PG8_LDA(dst, b, h) do { _Pragma("unroll") for (int m = 0; m < 4; ++m) _Pragma("unroll") for (int k = 0; k < 2; ++k) dst[m][k] = *(const LAS bf16x8*)(lds + PG8_SA(b, h) + aoff + m * 2048 + k * 1024); } while (0)
; #define PG8_MMA(ai, bj, At, Bt) do { __builtin_amdgcn_s_setprio(1); _Pragma("unroll") for (int m = 0; m < 4; ++m) _Pragma("unroll") for (int n = 0; n < 2; ++n) _Pragma("unroll") for (int k = 0; k < 2; ++k) \
;         acc[ai][bj][m][n] = __builtin_amdgcn_mfma_f32_16x16x32_bf16(Bt[n][k], At[m][k], acc[ai][bj][m][n], 0, 0, 0); __builtin_amdgcn_s_setprio(0); } while (0)
; #define PG8_WAIT_V(n) asm volatile("s_waitcnt vmcnt(" #n ")" ::: "memory")
; #define PG8_WAIT_L(n) asm volatile("s_waitcnt lgkmcnt(" #n ")" ::: "memory")
; #define PG8_BAR __builtin_amdgcn_s_barrier()
; #define PG8_SCHED __builtin_amdgcn_sched_barrier(0)
; template <class Epi, class Sched, bool ALIGN_EPI = true, bool SP2 = true>
; __device__ __forceinline__ void gemm_phase(LAS unsigned char* lds, const Gemm g, const Sched& S, const Epi& E) {
;     ...
;             PG8_LDA(At, 1, 1); PG8_STAGE(PG8_SB(1, 0), b3, voffB); PG8_STAGE(PG8_SB(1, 1), b3 + hstep, voffB); PG8_STAGE(PG8_SA(1, 0), a3, voffA);
;             PG8_WAIT_V(8); PG8_WAIT_L(0); PG8_BAR; PG8_MMA(1, 0, At, B0); PG8_MMA(1, 1, At, B1); PG8_BAR; PG8_SCHED;
;     ...
;         if constexpr (ALIGN_EPI) { if (wr == 0) PG8_BAR; }
	s_add_i32 s50, s59, s2
	v_lshl_add_u64 v[144:145], v[144:145], 0, s[10:11]
	s_mov_b32 m0, s50
	ds_read_b128 v[192:195], v151 offset:49152
	ds_read_b128 v[196:199], v151 offset:50176
	ds_read_b128 v[200:203], v151 offset:51200
	ds_read_b128 v[204:207], v151 offset:52224
	ds_read_b128 v[208:211], v151 offset:53248
	ds_read_b128 v[212:215], v151 offset:54272
	ds_read_b128 v[216:219], v151 offset:55296
	ds_read_b128 v[220:223], v151 offset:56320
	global_load_lds_dwordx4 v[144:145], off
	s_add_i32 m0, s50, 0x2000
	s_add_u32 s48, s48, 0x40080
	v_lshl_add_u64 v[144:145], v[224:225], 0, s[10:11]
	s_addc_u32 s49, s49, 0
	s_add_i32 s50, s60, s2
	global_load_lds_dwordx4 v[144:145], off
	v_lshl_add_u64 v[144:145], s[48:49], 0, v[132:133]
	s_mov_b32 m0, s50
	s_nop 0
	global_load_lds_dwordx4 v[144:145], off
	v_lshl_add_u64 v[144:145], s[48:49], 0, v[128:129]
	s_add_i32 m0, s50, 0x2000
	s_nop 0
	global_load_lds_dwordx4 v[144:145], off
	v_lshl_add_u64 v[144:145], v[226:227], 0, s[10:11]
	s_mov_b32 m0, s25
	s_nop 0
	global_load_lds_dwordx4 v[144:145], off
	v_lshl_add_u64 v[144:145], v[228:229], 0, s[10:11]
	s_mov_b32 m0, s34
	s_nop 0
	global_load_lds_dwordx4 v[144:145], off
	s_waitcnt vmcnt(8)
	s_waitcnt lgkmcnt(0)
	s_barrier
	s_waitcnt lgkmcnt(0)
	v_mfma_f32_16x16x32_bf16 v[60:63], v[152:155], v[192:195], v[60:63]
	v_mfma_f32_16x16x32_bf16 v[56:59], v[166:169], v[192:195], v[56:59]
	v_mfma_f32_16x16x32_bf16 v[44:47], v[152:155], v[200:203], v[44:47]
	v_mfma_f32_16x16x32_bf16 v[40:43], v[166:169], v[200:203], v[40:43]
	v_mfma_f32_16x16x32_bf16 v[28:31], v[152:155], v[208:211], v[28:31]
	v_mfma_f32_16x16x32_bf16 v[24:27], v[166:169], v[208:211], v[24:27]
	v_mfma_f32_16x16x32_bf16 v[12:15], v[152:155], v[216:219], v[12:15]
	v_mfma_f32_16x16x32_bf16 v[8:11], v[166:169], v[216:219], v[8:11]
	v_mfma_f32_16x16x32_bf16 v[60:63], v[156:159], v[196:199], v[60:63]
	v_mfma_f32_16x16x32_bf16 v[56:59], v[170:173], v[196:199], v[56:59]
	v_mfma_f32_16x16x32_bf16 v[44:47], v[156:159], v[204:207], v[44:47]
	v_mfma_f32_16x16x32_bf16 v[40:43], v[170:173], v[204:207], v[40:43]
	v_mfma_f32_16x16x32_bf16 v[28:31], v[156:159], v[212:215], v[28:31]
	v_mfma_f32_16x16x32_bf16 v[24:27], v[170:173], v[212:215], v[24:27]
	v_mfma_f32_16x16x32_bf16 v[12:15], v[156:159], v[220:223], v[12:15]
	v_mfma_f32_16x16x32_bf16 v[8:11], v[170:173], v[220:223], v[8:11]
	v_mfma_f32_16x16x32_bf16 v[52:55], v[176:179], v[192:195], v[52:55]
	v_mfma_f32_16x16x32_bf16 v[48:51], v[184:187], v[192:195], v[48:51]
	v_mfma_f32_16x16x32_bf16 v[36:39], v[176:179], v[200:203], v[36:39]
	v_mfma_f32_16x16x32_bf16 v[32:35], v[184:187], v[200:203], v[32:35]
	v_mfma_f32_16x16x32_bf16 v[20:23], v[176:179], v[208:211], v[20:23]
	v_mfma_f32_16x16x32_bf16 v[16:19], v[184:187], v[208:211], v[16:19]
	v_mfma_f32_16x16x32_bf16 v[4:7], v[176:179], v[216:219], v[4:7]
	v_mfma_f32_16x16x32_bf16 v[0:3], v[184:187], v[216:219], v[0:3]
	v_mfma_f32_16x16x32_bf16 v[52:55], v[180:183], v[196:199], v[52:55]
	v_mfma_f32_16x16x32_bf16 v[48:51], v[188:191], v[196:199], v[48:51]
	v_mfma_f32_16x16x32_bf16 v[36:39], v[180:183], v[204:207], v[36:39]
	v_mfma_f32_16x16x32_bf16 v[32:35], v[188:191], v[204:207], v[32:35]
	v_mfma_f32_16x16x32_bf16 v[20:23], v[180:183], v[212:215], v[20:23]
	v_mfma_f32_16x16x32_bf16 v[16:19], v[188:191], v[212:215], v[16:19]
	v_mfma_f32_16x16x32_bf16 v[4:7], v[180:183], v[220:223], v[4:7]
	v_mfma_f32_16x16x32_bf16 v[0:3], v[188:191], v[220:223], v[0:3]
	s_barrier
	s_add_i32 s58, s58, 2
	s_add_u32 s46, s46, 0x100
	s_addc_u32 s47, s47, 0
	s_add_u32 s56, s56, 0x100
	s_addc_u32 s57, s57, 0
	s_cmp_gt_u32 s58, 13
	s_cbranch_scc0 .LBB0_1236
	s_and_b64 vcc, exec, s[12:13]
	s_cbranch_vccz .LBB0_1239
	s_barrier

; #define PG8_STAGE(bufoff, gbase, voff) do { _Pragma("unroll") for (int _i = 0; _i < 2; ++_i) \
;         __builtin_amdgcn_global_load_lds((const unsigned*)((const char*)(gbase) + (voff)[_i]), (LAS unsigned*)(lds + (bufoff) + ldsw + _i * 8192), 16, 0, 0); } while (0)
; #define PG8_LDA(dst, b, h) do { _Pragma("unroll") for (int m = 0; m < 4; ++m) _Pragma("unroll") for (int k = 0; k < 2; ++k) dst[m][k] = *(const LAS bf16x8*)(lds + PG8_SA(b, h) + aoff + m * 2048 + k * 1024); } while (0)
; #define PG8_LDB(dst, b, h) do { _Pragma("unroll") for (int n = 0; n < 2; ++n) _Pragma("unroll") for (int k = 0; k < 2; ++k) dst[n][k] = *(const LAS bf16x8*)(lds + PG8_SB(b, h) + boff + n * 2048 + k * 1024); } while (0)
; #define PG8_MMA(ai, bj, At, Bt) do { __builtin_amdgcn_s_setprio(1); _Pragma("unroll") for (int m = 0; m < 4; ++m) _Pragma("unroll") for (int n = 0; n < 2; ++n) _Pragma("unroll") for (int k = 0; k < 2; ++k) \
;         acc[ai][bj][m][n] = __builtin_amdgcn_mfma_f32_16x16x32_bf16(Bt[n][k], At[m][k], acc[ai][bj][m][n], 0, 0, 0); __builtin_amdgcn_s_setprio(0); } while (0)
; #define PG8_WAIT_V(n) asm volatile("s_waitcnt vmcnt(" #n ")" ::: "memory")
; #define PG8_WAIT_L(n) asm volatile("s_waitcnt lgkmcnt(" #n ")" ::: "memory")
; #define PG8_BAR __builtin_amdgcn_s_barrier()
; #define PG8_SCHED __builtin_amdgcn_sched_barrier(0)
; template <class Epi, class Sched, bool ALIGN_EPI = true, bool SP2 = true>
; __device__ __forceinline__ void gemm_phase(LAS unsigned char* lds, const Gemm g, const Sched& S, const Epi& E) {
;     ...
;             const bool last = (t == nt - 2);
;             const char* a1 = cA + (size_t)(t + 1) * kstep;
;             const char* a2 = last ? nA : cA + (size_t)(t + 2) * kstep; const char* b2 = last ? nB : cB + (size_t)(t + 2) * kstep;
;             const char* a3 = a2 + kstep; const char* b3 = b2 + kstep;
;             if constexpr (SP2) {
;             PG8_LDB(B0, 0, 0); PG8_LDB(B1, 0, 1); PG8_SCHED; PG8_LDA(At, 0, 0); PG8_STAGE(PG8_SA(1, 1), a1 + hstep, voffA);
;             PG8_WAIT_V(8); PG8_WAIT_L(0); PG8_BAR; PG8_MMA(0, 0, At, B0); PG8_MMA(0, 1, At, B1); PG8_BAR; PG8_SCHED;
;             PG8_LDA(At, 0, 1); PG8_STAGE(PG8_SB(0, 0), b2, voffB); PG8_STAGE(PG8_SB(0, 1), b2 + hstep, voffB); PG8_STAGE(PG8_SA(0, 0), a2, voffA);
;             PG8_WAIT_V(8); PG8_WAIT_L(0); PG8_BAR; PG8_MMA(1, 0, At, B0); PG8_MMA(1, 1, At, B1); PG8_BAR; PG8_SCHED;
.LBB0_1316:
	ds_read_b128 v[150:153], v147
	ds_read_b128 v[154:157], v147 offset:1024
	ds_read_b128 v[166:169], v147 offset:2048
	ds_read_b128 v[170:173], v147 offset:3072
	ds_read_b128 v[176:179], v148
	ds_read_b128 v[180:183], v148 offset:1024
	ds_read_b128 v[184:187], v148 offset:2048
	ds_read_b128 v[188:191], v148 offset:3072
	s_add_u32 s48, s46, 0x100
	s_addc_u32 s49, s47, 0
	s_cmp_eq_u32 s65, 40
	s_cselect_b32 s53, s7, s49
	s_cselect_b32 s52, s6, s48
	s_cselect_b32 s51, s45, s64
	s_cselect_b32 s50, s44, s63
	v_lshl_add_u64 v[158:159], s[46:47], 0, v[136:137]
	s_add_i32 m0, s16, 0xc000
	ds_read_b128 v[192:195], v149
	ds_read_b128 v[196:199], v149 offset:1024
	ds_read_b128 v[200:203], v149 offset:2048
	ds_read_b128 v[204:207], v149 offset:3072
	ds_read_b128 v[208:211], v149 offset:4096
	ds_read_b128 v[212:215], v149 offset:5120
	ds_read_b128 v[216:219], v149 offset:6144
	ds_read_b128 v[220:223], v149 offset:7168
	global_load_lds_dwordx4 v[158:159], off
	v_lshl_add_u64 v[158:159], s[46:47], 0, v[138:139]
	s_add_i32 m0, s16, 0xe000
	s_nop 0
	global_load_lds_dwordx4 v[158:159], off
	s_waitcnt vmcnt(8)
	s_waitcnt lgkmcnt(0)
	s_barrier
	s_waitcnt lgkmcnt(0)
	v_mfma_f32_16x16x32_bf16 v[124:127], v[150:153], v[192:195], v[124:127]
	v_mfma_f32_16x16x32_bf16 v[120:123], v[166:169], v[192:195], v[120:123]
	v_mfma_f32_16x16x32_bf16 v[116:119], v[150:153], v[200:203], v[116:119]
	v_mfma_f32_16x16x32_bf16 v[112:115], v[166:169], v[200:203], v[112:115]
	v_mfma_f32_16x16x32_bf16 v[100:103], v[150:153], v[208:211], v[100:103]
	v_mfma_f32_16x16x32_bf16 v[96:99], v[166:169], v[208:211], v[96:99]
	v_mfma_f32_16x16x32_bf16 v[84:87], v[150:153], v[216:219], v[84:87]
	v_mfma_f32_16x16x32_bf16 v[80:83], v[166:169], v[216:219], v[80:83]
	v_mfma_f32_16x16x32_bf16 v[124:127], v[154:157], v[196:199], v[124:127]
	v_mfma_f32_16x16x32_bf16 v[120:123], v[170:173], v[196:199], v[120:123]
	v_mfma_f32_16x16x32_bf16 v[116:119], v[154:157], v[204:207], v[116:119]
	v_mfma_f32_16x16x32_bf16 v[112:115], v[170:173], v[204:207], v[112:115]
	v_mfma_f32_16x16x32_bf16 v[100:103], v[154:157], v[212:215], v[100:103]
	v_mfma_f32_16x16x32_bf16 v[96:99], v[170:173], v[212:215], v[96:99]
	v_mfma_f32_16x16x32_bf16 v[84:87], v[154:157], v[220:223], v[84:87]
	v_mfma_f32_16x16x32_bf16 v[80:83], v[170:173], v[220:223], v[80:83]
	v_mfma_f32_16x16x32_bf16 v[108:111], v[176:179], v[192:195], v[108:111]
	v_mfma_f32_16x16x32_bf16 v[104:107], v[184:187], v[192:195], v[104:107]
	v_mfma_f32_16x16x32_bf16 v[92:95], v[176:179], v[200:203], v[92:95]
	v_mfma_f32_16x16x32_bf16 v[88:91], v[184:187], v[200:203], v[88:91]
	v_mfma_f32_16x16x32_bf16 v[76:79], v[176:179], v[208:211], v[76:79]
	v_mfma_f32_16x16x32_bf16 v[72:75], v[184:187], v[208:211], v[72:75]
	v_mfma_f32_16x16x32_bf16 v[68:71], v[176:179], v[216:219], v[68:71]
	v_mfma_f32_16x16x32_bf16 v[64:67], v[184:187], v[216:219], v[64:67]
	v_mfma_f32_16x16x32_bf16 v[108:111], v[180:183], v[196:199], v[108:111]
	v_mfma_f32_16x16x32_bf16 v[104:107], v[188:191], v[196:199], v[104:107]
	v_mfma_f32_16x16x32_bf16 v[92:95], v[180:183], v[204:207], v[92:95]
	v_mfma_f32_16x16x32_bf16 v[88:91], v[188:191], v[204:207], v[88:91]
	v_mfma_f32_16x16x32_bf16 v[76:79], v[180:183], v[212:215], v[76:79]
	v_mfma_f32_16x16x32_bf16 v[72:75], v[188:191], v[212:215], v[72:75]
	v_mfma_f32_16x16x32_bf16 v[68:71], v[180:183], v[220:223], v[68:71]
	v_mfma_f32_16x16x32_bf16 v[64:67], v[188:191], v[220:223], v[64:67]
	s_barrier
	s_add_i32 s46, s35, s3
	v_lshl_add_u64 v[158:159], s[50:51], 0, v[130:131]
	s_mov_b32 m0, s46
	ds_read_b128 v[192:195], v149 offset:16384
	ds_read_b128 v[196:199], v149 offset:17408
	ds_read_b128 v[200:203], v149 offset:18432
	ds_read_b128 v[204:207], v149 offset:19456
	ds_read_b128 v[208:211], v149 offset:20480
	ds_read_b128 v[212:215], v149 offset:21504
	ds_read_b128 v[216:219], v149 offset:22528
	ds_read_b128 v[220:223], v149 offset:23552
	global_load_lds_dwordx4 v[158:159], off
	s_add_i32 m0, s46, 0x2000
	s_add_u32 s46, s50, 0xb0000
	v_lshl_add_u64 v[224:225], s[50:51], 0, v[134:135]
	s_addc_u32 s47, s51, 0
	s_add_i32 s66, s54, s3
	global_load_lds_dwordx4 v[224:225], off
	v_lshl_add_u64 v[226:227], s[46:47], 0, v[130:131]
	s_mov_b32 m0, s66
	v_lshl_add_u64 v[228:229], s[52:53], 0, v[132:133]
	global_load_lds_dwordx4 v[226:227], off
	v_lshl_add_u64 v[226:227], s[46:47], 0, v[134:135]
	s_add_i32 m0, s66, 0x2000
	s_nop 0
	global_load_lds_dwordx4 v[226:227], off
	v_lshl_add_u64 v[226:227], s[52:53], 0, v[128:129]
	s_mov_b32 m0, s16
	s_nop 0
	global_load_lds_dwordx4 v[226:227], off
	s_mov_b32 m0, s17
	s_nop 0
	global_load_lds_dwordx4 v[228:229], off
	s_waitcnt vmcnt(8)
	s_waitcnt lgkmcnt(0)
	s_barrier
; #define PG8_STAGE(bufoff, gbase, voff) do { _Pragma("unroll") for (int _i = 0; _i < 2; ++_i) \
;         __builtin_amdgcn_global_load_lds((const unsigned*)((const char*)(gbase) + (voff)[_i]), (LAS unsigned*)(lds + (bufoff) + ldsw + _i * 8192), 16, 0, 0); } while (0)
; #define PG8_LDA(dst, b, h) do { _Pragma("unroll") for (int m = 0; m < 4; ++m) _Pragma("unroll") for (int k = 0; k < 2; ++k) dst[m][k] = *(const LAS bf16x8*)(lds + PG8_SA(b, h) + aoff + m * 2048 + k * 1024); } while (0)
; #define PG8_LDB(dst, b, h) do { _Pragma("unroll") for (int n = 0; n < 2; ++n) _Pragma("unroll") for (int k = 0; k < 2; ++k) dst[n][k] = *(const LAS bf16x8*)(lds + PG8_SB(b, h) + boff + n * 2048 + k * 1024); } while (0)
; #define PG8_MMA(ai, bj, At, Bt) do { __builtin_amdgcn_s_setprio(1); _Pragma("unroll") for (int m = 0; m < 4; ++m) _Pragma("unroll") for (int n = 0; n < 2; ++n) _Pragma("unroll") for (int k = 0; k < 2; ++k) \
;         acc[ai][bj][m][n] = __builtin_amdgcn_mfma_f32_16x16x32_bf16(Bt[n][k], At[m][k], acc[ai][bj][m][n], 0, 0, 0); __builtin_amdgcn_s_setprio(0); } while (0)
; #define PG8_WAIT_V(n) asm volatile("s_waitcnt vmcnt(" #n ")" ::: "memory")
; #define PG8_WAIT_L(n) asm volatile("s_waitcnt lgkmcnt(" #n ")" ::: "memory")
; #define PG8_BAR __builtin_amdgcn_s_barrier()
; #define PG8_SCHED __builtin_amdgcn_sched_barrier(0)
; template <class Epi, class Sched, bool ALIGN_EPI = true, bool SP2 = true>
; __device__ __forceinline__ void gemm_phase(LAS unsigned char* lds, const Gemm g, const Sched& S, const Epi& E) {
;     ...
;             PG8_WAIT_V(8); PG8_WAIT_L(0); PG8_BAR; PG8_MMA(1, 0, At, B0); PG8_MMA(1, 1, At, B1); PG8_BAR; PG8_SCHED;
;             PG8_LDB(B0, 1, 0); PG8_LDB(B1, 1, 1); PG8_SCHED; PG8_LDA(At, 1, 0); PG8_STAGE(PG8_SA(0, 1), a2 + hstep, voffA);
;             PG8_WAIT_V(8); PG8_WAIT_L(0); PG8_BAR; PG8_MMA(0, 0, At, B0); PG8_MMA(0, 1, At, B1); PG8_BAR; PG8_SCHED;
	s_waitcnt lgkmcnt(0)
	v_mfma_f32_16x16x32_bf16 v[60:63], v[150:153], v[192:195], v[60:63]
	v_mfma_f32_16x16x32_bf16 v[56:59], v[166:169], v[192:195], v[56:59]
	v_mfma_f32_16x16x32_bf16 v[52:55], v[150:153], v[200:203], v[52:55]
	v_mfma_f32_16x16x32_bf16 v[48:51], v[166:169], v[200:203], v[48:51]
	v_mfma_f32_16x16x32_bf16 v[36:39], v[150:153], v[208:211], v[36:39]
	v_mfma_f32_16x16x32_bf16 v[32:35], v[166:169], v[208:211], v[32:35]
	v_mfma_f32_16x16x32_bf16 v[20:23], v[150:153], v[216:219], v[20:23]
	v_mfma_f32_16x16x32_bf16 v[16:19], v[166:169], v[216:219], v[16:19]
	v_mfma_f32_16x16x32_bf16 v[60:63], v[154:157], v[196:199], v[60:63]
	v_mfma_f32_16x16x32_bf16 v[56:59], v[170:173], v[196:199], v[56:59]
	v_mfma_f32_16x16x32_bf16 v[52:55], v[154:157], v[204:207], v[52:55]
	v_mfma_f32_16x16x32_bf16 v[48:51], v[170:173], v[204:207], v[48:51]
	v_mfma_f32_16x16x32_bf16 v[36:39], v[154:157], v[212:215], v[36:39]
	v_mfma_f32_16x16x32_bf16 v[32:35], v[170:173], v[212:215], v[32:35]
	v_mfma_f32_16x16x32_bf16 v[20:23], v[154:157], v[220:223], v[20:23]
	v_mfma_f32_16x16x32_bf16 v[16:19], v[170:173], v[220:223], v[16:19]
	v_mfma_f32_16x16x32_bf16 v[44:47], v[176:179], v[192:195], v[44:47]
	v_mfma_f32_16x16x32_bf16 v[40:43], v[184:187], v[192:195], v[40:43]
	v_mfma_f32_16x16x32_bf16 v[28:31], v[176:179], v[200:203], v[28:31]
	v_mfma_f32_16x16x32_bf16 v[24:27], v[184:187], v[200:203], v[24:27]
	v_mfma_f32_16x16x32_bf16 v[12:15], v[176:179], v[208:211], v[12:15]
	v_mfma_f32_16x16x32_bf16 v[8:11], v[184:187], v[208:211], v[8:11]
	v_mfma_f32_16x16x32_bf16 v[4:7], v[176:179], v[216:219], v[4:7]
	v_mfma_f32_16x16x32_bf16 v[0:3], v[184:187], v[216:219], v[0:3]
	v_mfma_f32_16x16x32_bf16 v[44:47], v[180:183], v[196:199], v[44:47]
	v_mfma_f32_16x16x32_bf16 v[40:43], v[188:191], v[196:199], v[40:43]
	v_mfma_f32_16x16x32_bf16 v[28:31], v[180:183], v[204:207], v[28:31]
	v_mfma_f32_16x16x32_bf16 v[24:27], v[188:191], v[204:207], v[24:27]
	v_mfma_f32_16x16x32_bf16 v[12:15], v[180:183], v[212:215], v[12:15]
	v_mfma_f32_16x16x32_bf16 v[8:11], v[188:191], v[212:215], v[8:11]
	v_mfma_f32_16x16x32_bf16 v[4:7], v[180:183], v[220:223], v[4:7]
	v_mfma_f32_16x16x32_bf16 v[0:3], v[188:191], v[220:223], v[0:3]
	s_barrier
	s_add_i32 s66, 0, 0x18000
	v_add_u32_e32 v160, s66, v145
	s_add_i32 s67, 0, 0x1c000
	ds_read_b128 v[150:153], v160
	ds_read_b128 v[154:157], v160 offset:1024
	ds_read_b128 v[166:169], v160 offset:2048
	ds_read_b128 v[170:173], v160 offset:3072
	v_add_u32_e32 v160, s67, v145
	ds_read_b128 v[176:179], v160
	ds_read_b128 v[180:183], v160 offset:1024
	ds_read_b128 v[184:187], v160 offset:2048
	ds_read_b128 v[188:191], v160 offset:3072
	s_add_u32 s46, s52, 0xb0000
	s_addc_u32 s47, s53, 0
	s_mov_b32 m0, s18
	v_lshl_add_u64 v[230:231], s[46:47], 0, v[128:129]
	ds_read_b128 v[192:195], v149 offset:32768
	ds_read_b128 v[196:199], v149 offset:33792
	ds_read_b128 v[200:203], v149 offset:34816
	ds_read_b128 v[204:207], v149 offset:35840
	ds_read_b128 v[208:211], v149 offset:36864
	ds_read_b128 v[212:215], v149 offset:37888
	ds_read_b128 v[216:219], v149 offset:38912
	ds_read_b128 v[220:223], v149 offset:39936
	global_load_lds_dwordx4 v[230:231], off
	v_lshl_add_u64 v[230:231], s[46:47], 0, v[132:133]
	s_mov_b32 m0, s19
	s_nop 0
	global_load_lds_dwordx4 v[230:231], off
	s_waitcnt vmcnt(8)
	s_waitcnt lgkmcnt(0)
	s_barrier
	s_waitcnt lgkmcnt(0)
	v_mfma_f32_16x16x32_bf16 v[124:127], v[150:153], v[192:195], v[124:127]
	v_mfma_f32_16x16x32_bf16 v[120:123], v[166:169], v[192:195], v[120:123]
	v_mfma_f32_16x16x32_bf16 v[116:119], v[150:153], v[200:203], v[116:119]
	v_mfma_f32_16x16x32_bf16 v[112:115], v[166:169], v[200:203], v[112:115]
	v_mfma_f32_16x16x32_bf16 v[100:103], v[150:153], v[208:211], v[100:103]
	v_mfma_f32_16x16x32_bf16 v[96:99], v[166:169], v[208:211], v[96:99]
	v_mfma_f32_16x16x32_bf16 v[84:87], v[150:153], v[216:219], v[84:87]
	v_mfma_f32_16x16x32_bf16 v[80:83], v[166:169], v[216:219], v[80:83]
	v_mfma_f32_16x16x32_bf16 v[124:127], v[154:157], v[196:199], v[124:127]
	v_mfma_f32_16x16x32_bf16 v[120:123], v[170:173], v[196:199], v[120:123]
	v_mfma_f32_16x16x32_bf16 v[116:119], v[154:157], v[204:207], v[116:119]
	v_mfma_f32_16x16x32_bf16 v[112:115], v[170:173], v[204:207], v[112:115]
	v_mfma_f32_16x16x32_bf16 v[100:103], v[154:157], v[212:215], v[100:103]
	v_mfma_f32_16x16x32_bf16 v[96:99], v[170:173], v[212:215], v[96:99]
	v_mfma_f32_16x16x32_bf16 v[84:87], v[154:157], v[220:223], v[84:87]
	v_mfma_f32_16x16x32_bf16 v[80:83], v[170:173], v[220:223], v[80:83]
	v_mfma_f32_16x16x32_bf16 v[108:111], v[176:179], v[192:195], v[108:111]
	v_mfma_f32_16x16x32_bf16 v[104:107], v[184:187], v[192:195], v[104:107]
	v_mfma_f32_16x16x32_bf16 v[92:95], v[176:179], v[200:203], v[92:95]
	v_mfma_f32_16x16x32_bf16 v[88:91], v[184:187], v[200:203], v[88:91]
	v_mfma_f32_16x16x32_bf16 v[76:79], v[176:179], v[208:211], v[76:79]
	v_mfma_f32_16x16x32_bf16 v[72:75], v[184:187], v[208:211], v[72:75]
	v_mfma_f32_16x16x32_bf16 v[68:71], v[176:179], v[216:219], v[68:71]
	v_mfma_f32_16x16x32_bf16 v[64:67], v[184:187], v[216:219], v[64:67]
	v_mfma_f32_16x16x32_bf16 v[108:111], v[180:183], v[196:199], v[108:111]
	v_mfma_f32_16x16x32_bf16 v[104:107], v[188:191], v[196:199], v[104:107]
	v_mfma_f32_16x16x32_bf16 v[92:95], v[180:183], v[204:207], v[92:95]
	v_mfma_f32_16x16x32_bf16 v[88:91], v[188:191], v[204:207], v[88:91]
	v_mfma_f32_16x16x32_bf16 v[76:79], v[180:183], v[212:215], v[76:79]
	v_mfma_f32_16x16x32_bf16 v[72:75], v[188:191], v[212:215], v[72:75]
	v_mfma_f32_16x16x32_bf16 v[68:71], v[180:183], v[220:223], v[68:71]
	v_mfma_f32_16x16x32_bf16 v[64:67], v[188:191], v[220:223], v[64:67]
	s_barrier
; #define PG8_STAGE(bufoff, gbase, voff) do { _Pragma("unroll") for (int _i = 0; _i < 2; ++_i) \
;         __builtin_amdgcn_global_load_lds((const unsigned*)((const char*)(gbase) + (voff)[_i]), (LAS unsigned*)(lds + (bufoff) + ldsw + _i * 8192), 16, 0, 0); } while (0)
; #define PG8_LDA(dst, b, h) do { _Pragma("unroll") for (int m = 0; m < 4; ++m) _Pragma("unroll") for (int k = 0; k < 2; ++k) dst[m][k] = *(const LAS bf16x8*)(lds + PG8_SA(b, h) + aoff + m * 2048 + k * 1024); } while (0)
; #define PG8_MMA(ai, bj, At, Bt) do { __builtin_amdgcn_s_setprio(1); _Pragma("unroll") for (int m = 0; m < 4; ++m) _Pragma("unroll") for (int n = 0; n < 2; ++n) _Pragma("unroll") for (int k = 0; k < 2; ++k) \
;         acc[ai][bj][m][n] = __builtin_amdgcn_mfma_f32_16x16x32_bf16(Bt[n][k], At[m][k], acc[ai][bj][m][n], 0, 0, 0); __builtin_amdgcn_s_setprio(0); } while (0)
; #define PG8_WAIT_V(n) asm volatile("s_waitcnt vmcnt(" #n ")" ::: "memory")
; #define PG8_WAIT_L(n) asm volatile("s_waitcnt lgkmcnt(" #n ")" ::: "memory")
; #define PG8_BAR __builtin_amdgcn_s_barrier()
; #define PG8_SCHED __builtin_amdgcn_sched_barrier(0)
; template <class Epi, class Sched, bool ALIGN_EPI = true, bool SP2 = true>
; __device__ __forceinline__ void gemm_phase(LAS unsigned char* lds, const Gemm g, const Sched& S, const Epi& E) {
;     ...
;             PG8_LDA(At, 1, 1); PG8_STAGE(PG8_SB(1, 0), b3, voffB); PG8_STAGE(PG8_SB(1, 1), b3 + hstep, voffB); PG8_STAGE(PG8_SA(1, 0), a3, voffA);
;             PG8_WAIT_V(8); PG8_WAIT_L(0); PG8_BAR; PG8_MMA(1, 0, At, B0); PG8_MMA(1, 1, At, B1); PG8_BAR; PG8_SCHED;
;     ...
;         if constexpr (ALIGN_EPI) { if (wr == 0) PG8_BAR; }
	s_add_i32 s46, s66, s3
	v_lshl_add_u64 v[158:159], v[158:159], 0, s[12:13]
	s_mov_b32 m0, s46
	ds_read_b128 v[192:195], v149 offset:49152
	ds_read_b128 v[196:199], v149 offset:50176
	ds_read_b128 v[200:203], v149 offset:51200
	ds_read_b128 v[204:207], v149 offset:52224
	ds_read_b128 v[208:211], v149 offset:53248
	ds_read_b128 v[212:215], v149 offset:54272
	ds_read_b128 v[216:219], v149 offset:55296
	ds_read_b128 v[220:223], v149 offset:56320
	global_load_lds_dwordx4 v[158:159], off
	s_add_i32 m0, s46, 0x2000
	s_add_u32 s46, s50, 0xb0080
	v_lshl_add_u64 v[158:159], v[224:225], 0, s[12:13]
	s_addc_u32 s47, s51, 0
	s_add_i32 s50, s67, s3
	global_load_lds_dwordx4 v[158:159], off
	v_lshl_add_u64 v[158:159], s[46:47], 0, v[130:131]
	s_mov_b32 m0, s50
	s_nop 0
	global_load_lds_dwordx4 v[158:159], off
	v_lshl_add_u64 v[158:159], s[46:47], 0, v[134:135]
	s_add_i32 m0, s50, 0x2000
	s_nop 0
	global_load_lds_dwordx4 v[158:159], off
	v_lshl_add_u64 v[158:159], v[226:227], 0, s[12:13]
	s_mov_b32 m0, s23
	s_nop 0
	global_load_lds_dwordx4 v[158:159], off
	v_lshl_add_u64 v[158:159], v[228:229], 0, s[12:13]
	s_mov_b32 m0, s24
	s_nop 0
	global_load_lds_dwordx4 v[158:159], off
	s_waitcnt vmcnt(8)
	s_waitcnt lgkmcnt(0)
	s_barrier
	s_waitcnt lgkmcnt(0)
	v_mfma_f32_16x16x32_bf16 v[60:63], v[150:153], v[192:195], v[60:63]
	v_mfma_f32_16x16x32_bf16 v[56:59], v[166:169], v[192:195], v[56:59]
	v_mfma_f32_16x16x32_bf16 v[52:55], v[150:153], v[200:203], v[52:55]
	v_mfma_f32_16x16x32_bf16 v[48:51], v[166:169], v[200:203], v[48:51]
	v_mfma_f32_16x16x32_bf16 v[36:39], v[150:153], v[208:211], v[36:39]
	v_mfma_f32_16x16x32_bf16 v[32:35], v[166:169], v[208:211], v[32:35]
	v_mfma_f32_16x16x32_bf16 v[20:23], v[150:153], v[216:219], v[20:23]
	v_mfma_f32_16x16x32_bf16 v[16:19], v[166:169], v[216:219], v[16:19]
	v_mfma_f32_16x16x32_bf16 v[60:63], v[154:157], v[196:199], v[60:63]
	v_mfma_f32_16x16x32_bf16 v[56:59], v[170:173], v[196:199], v[56:59]
	v_mfma_f32_16x16x32_bf16 v[52:55], v[154:157], v[204:207], v[52:55]
	v_mfma_f32_16x16x32_bf16 v[48:51], v[170:173], v[204:207], v[48:51]
	v_mfma_f32_16x16x32_bf16 v[36:39], v[154:157], v[212:215], v[36:39]
	v_mfma_f32_16x16x32_bf16 v[32:35], v[170:173], v[212:215], v[32:35]
	v_mfma_f32_16x16x32_bf16 v[20:23], v[154:157], v[220:223], v[20:23]
	v_mfma_f32_16x16x32_bf16 v[16:19], v[170:173], v[220:223], v[16:19]
	v_mfma_f32_16x16x32_bf16 v[44:47], v[176:179], v[192:195], v[44:47]
	v_mfma_f32_16x16x32_bf16 v[40:43], v[184:187], v[192:195], v[40:43]
	v_mfma_f32_16x16x32_bf16 v[28:31], v[176:179], v[200:203], v[28:31]
	v_mfma_f32_16x16x32_bf16 v[24:27], v[184:187], v[200:203], v[24:27]
	v_mfma_f32_16x16x32_bf16 v[12:15], v[176:179], v[208:211], v[12:15]
	v_mfma_f32_16x16x32_bf16 v[8:11], v[184:187], v[208:211], v[8:11]
	v_mfma_f32_16x16x32_bf16 v[4:7], v[176:179], v[216:219], v[4:7]
	v_mfma_f32_16x16x32_bf16 v[0:3], v[184:187], v[216:219], v[0:3]
	v_mfma_f32_16x16x32_bf16 v[44:47], v[180:183], v[196:199], v[44:47]
	v_mfma_f32_16x16x32_bf16 v[40:43], v[188:191], v[196:199], v[40:43]
	v_mfma_f32_16x16x32_bf16 v[28:31], v[180:183], v[204:207], v[28:31]
	v_mfma_f32_16x16x32_bf16 v[24:27], v[188:191], v[204:207], v[24:27]
	v_mfma_f32_16x16x32_bf16 v[12:15], v[180:183], v[212:215], v[12:15]
	v_mfma_f32_16x16x32_bf16 v[8:11], v[188:191], v[212:215], v[8:11]
	v_mfma_f32_16x16x32_bf16 v[4:7], v[180:183], v[220:223], v[4:7]
	v_mfma_f32_16x16x32_bf16 v[0:3], v[188:191], v[220:223], v[0:3]
	s_barrier
	s_add_i32 s65, s65, 2
	s_add_u32 s63, s63, 0x100
	s_addc_u32 s64, s64, 0
	s_cmp_gt_u32 s65, 41
	s_mov_b64 s[46:47], s[48:49]
	s_cbranch_scc0 .LBB0_1316
	s_and_b64 vcc, exec, s[14:15]
	s_cbranch_vccz .LBB0_1319
	s_barrier
